# P1 q/k epilogue: rope cos/sin table staged in LDS after the k-loop; per-row fetches are ds_read (lgkmcnt) instead of global loads that queued behind the previous rows' stores
# speedup vs baseline: 1.0540x; 1.0035x over previous
; __device__ __forceinline__ void inproj_tile(const Params& p, char* smem, int l, int mt, int nt) {
;     ...
;     if (nt < 8) {
;       const bool isq = nt < 4;
;       const float* nw = (isq ? p.q_norm_w : p.k_norm_w) + l * 64;
;       float w4[4];
; #pragma unroll
;       for (int n = 0; n < 4; ++n) w4[n] = nw[n * 16 + fr] * (isq ? 0.125f : 1.f);
; #pragma unroll
;       for (int m = 0; m < 8; ++m)
; #pragma unroll
;         for (int j = 0; j < 4; ++j) {
;           float ss = 0.f;
; #pragma unroll
;           for (int n = 0; n < 4; ++n) ss += acc[m][n][j] * acc[m][n][j];
;           ss += __shfl_xor(ss, 1); ss += __shfl_xor(ss, 2); ss += __shfl_xor(ss, 4); ss += __shfl_xor(ss, 8);
;           float rstd = rsqrtf(ss * (1.f / 64.f) + EPSF);
;           int row = rowbase + m * 16 + fq * 4 + j;
;           float v[4];
; #pragma unroll
;           for (int n = 0; n < 4; ++n) v[n] = acc[m][n][j] * rstd * w4[n];
;           bool lat = row < MLAT;
;           float rv[4] = {v[0], v[1], v[2], v[3]};
;           if (lat) {
;             int t = row & 8191, pr = t >> 6, pc = t & 63;
;             float c0 = rope[pr * 16 + fr], s0 = rope[2048 + pr * 16 + fr];
;             float c1 = rope[pc * 16 + fr], s1 = rope[2048 + pc * 16 + fr];
;             rv[0] = v[0] * c0 - v[1] * s0; rv[1] = v[1] * c0 + v[0] * s0;
;             rv[2] = v[2] * c1 - v[3] * s1; rv[3] = v[3] * c1 + v[2] * s1;
.LBB0_309:
	s_andn2_b64 vcc, exec, s[0:1]
	s_cbranch_vccnz .LBB0_294
	s_add_u32 s6, s8, 0x18e24000
	s_addc_u32 s7, s9, 0
	v_lshlrev_b32_e32 v211, 4, v172
	global_load_dwordx4 v[240:243], v211, s[6:7]
	s_add_u32 s100, s6, 0x1000
	s_addc_u32 s101, s7, 0
	global_load_dwordx4 v[244:247], v211, s[100:101]
	s_add_u32 s100, s6, 0x2000
	s_addc_u32 s101, s7, 0
	global_load_dwordx4 v[248:251], v211, s[100:101]
	s_add_u32 s100, s6, 0x3000
	s_addc_u32 s101, s7, 0
	global_load_dwordx4 v[252:255], v211, s[100:101]
	s_mov_b32 s100, s6
	s_waitcnt vmcnt(0)
	ds_write_b128 v211, v[240:243]
	ds_write_b128 v211, v[244:247] offset:4096
	ds_write_b128 v211, v[248:251] offset:8192
	ds_write_b128 v211, v[252:255] offset:12288
	s_waitcnt lgkmcnt(0)
	s_barrier
	s_cmp_gt_i32 s13, 3
	s_cselect_b64 s[10:11], -1, 0
	s_cmp_lt_i32 s13, 4
	s_cselect_b64 vcc, -1, 0
	s_and_b64 s[0:1], vcc, exec
	s_cselect_b32 s13, s81, s83
	s_cselect_b32 s14, s80, s82
	s_lshl_b32 s0, s12, 6
	s_ashr_i32 s1, s0, 31
	s_lshl_b64 s[0:1], s[0:1], 2
	s_add_u32 s0, s14, s0
	s_addc_u32 s1, s13, s1
	v_lshlrev_b32_e32 v135, 2, v168
	global_load_dword v136, v135, s[0:1]
	global_load_dword v137, v135, s[0:1] offset:64
	global_load_dword v145, v135, s[0:1] offset:128
	global_load_dword v144, v135, s[0:1] offset:192
	v_and_b32_e32 v141, 64, v173
	v_mov_b32_e32 v2, v120
	v_mov_b32_e32 v3, v124
	v_xor_b32_e32 v133, 1, v173
	v_mov_b32_e32 v138, v128
	v_mov_b32_e32 v139, v116
	v_add_u32_e32 v116, 64, v141
	v_pk_mul_f32 v[2:3], v[2:3], v[2:3]
	v_cndmask_b32_e32 v134, 1.0, v202, vcc
	v_pk_mul_f32 v[142:143], v[138:139], v[138:139]
	v_cmp_lt_i32_e32 vcc, v133, v116
	v_add_f32_e32 v2, v2, v3
	v_add_f32_e32 v2, v143, v2
	v_cndmask_b32_e32 v128, v173, v133, vcc
	v_lshlrev_b32_e32 v158, 2, v128
	v_add_f32_e32 v2, v142, v2
	s_nop 1
	v_mov_b32_dpp v3, v2 quad_perm:[1,0,3,2] row_mask:0xf bank_mask:0xf
	v_xor_b32_e32 v146, 2, v173
	v_cmp_lt_i32_e32 vcc, v146, v116
	v_xor_b32_e32 v128, 4, v173
	s_movk_i32 s0, 0x7e0
	v_cndmask_b32_e32 v133, v173, v146, vcc
	v_lshlrev_b32_e32 v159, 2, v133
	s_waitcnt lgkmcnt(0)
	v_add_f32_e32 v2, v2, v3
	s_nop 1
	v_mov_b32_dpp v3, v2 quad_perm:[2,3,0,1] row_mask:0xf bank_mask:0xf
	v_cmp_lt_i32_e32 vcc, v128, v116
	v_xor_b32_e32 v133, 8, v173
	s_waitcnt lgkmcnt(0)
	v_add_f32_e32 v3, v2, v3
	v_cndmask_b32_e32 v128, v173, v128, vcc
	v_lshlrev_b32_e32 v160, 2, v128
	s_nop 1
	v_mov_b32_dpp v128, v3 row_half_mirror row_mask:0xf bank_mask:0xf
	v_cmp_lt_i32_e32 vcc, v133, v116
	v_lshl_or_b32 v2, v140, 2, v132
	v_lshl_or_b32 v140, v140, 8, v135
	v_cndmask_b32_e32 v116, v173, v133, vcc
	v_lshlrev_b32_e32 v161, 2, v116
	s_waitcnt lgkmcnt(0)
	v_add_f32_e32 v3, v3, v128
	s_nop 1
	v_mov_b32_dpp v116, v3 row_mirror row_mask:0xf bank_mask:0xf
	v_lshrrev_b32_e32 v128, 2, v132
	v_mov_b32_e32 v132, v124
	v_mov_b32_e32 v133, v120
	v_and_or_b32 v120, v128, s0, v168
	s_waitcnt lgkmcnt(0)
	v_add_f32_e32 v3, v3, v116
	v_fmamk_f32 v3, v3, 0x3c800000, v197
	v_mul_f32_e32 v116, 0x4b800000, v3
	v_cmp_gt_f32_e32 vcc, s92, v3
	v_cmp_gt_i32_e64 s[0:1], s91, v2
	v_lshlrev_b32_e32 v142, 2, v120
	v_cndmask_b32_e32 v3, v3, v116, vcc
	v_rsq_f32_e32 v3, v3
	s_nop 0
	v_mul_f32_e32 v116, 0x45800000, v3
	v_cndmask_b32_e32 v116, v3, v116, vcc
	v_pk_mul_f32 v[132:133], v[116:117], v[132:133] op_sel_hi:[0,1]
	v_pk_mul_f32 v[146:147], v[116:117], v[138:139] op_sel_hi:[0,1]
	s_waitcnt vmcnt(0)
	v_pk_mul_f32 v[138:139], v[134:135], v[136:137] op_sel_hi:[0,1]
	v_pk_mul_f32 v[150:151], v[138:139], v[132:133]
	v_pk_mul_f32 v[136:137], v[134:135], v[144:145] op_sel_hi:[0,1]
	v_pk_mul_f32 v[148:149], v[136:137], v[146:147]
	v_mov_b32_e32 v116, v150
	v_mov_b32_e32 v145, v151
	v_mov_b32_e32 v146, v149
	v_mov_b32_e32 v152, v148
	s_and_saveexec_b64 s[12:13], s[0:1]
	s_cbranch_execz .LBB0_312
	v_mov_b32_e32 v143, v1
	v_lshl_add_u64 v[132:133], s[6:7], 0, v[142:143]
	v_subrev_u32_e32 v211, s100, v132
	ds_read_b32 v116, v211
	v_add_co_u32_e32 v132, vcc, 0x2000, v132
	v_mov_b32_e32 v141, v1
	s_nop 0
	v_addc_co_u32_e32 v133, vcc, 0, v133, vcc
	v_subrev_u32_e32 v211, s100, v132
	ds_read_b32 v120, v211
	v_lshl_add_u64 v[132:133], s[6:7], 0, v[140:141]
	v_subrev_u32_e32 v211, s100, v132
	ds_read_b32 v135, v211
	v_add_co_u32_e32 v132, vcc, 0x2000, v132
	s_waitcnt lgkmcnt(0)
	v_pk_mul_f32 v[154:155], v[150:151], v[120:121] op_sel:[1,0] op_sel_hi:[0,0]
	v_addc_co_u32_e32 v133, vcc, 0, v133, vcc
	v_subrev_u32_e32 v211, s100, v132
	ds_read_b32 v134, v211
	v_pk_mul_f32 v[132:133], v[150:151], v[116:117] op_sel_hi:[1,0]
	v_pk_fma_f32 v[144:145], v[150:151], v[116:117], v[154:155] op_sel_hi:[1,0,1]
	v_mul_f32_e32 v116, v149, v135
	v_mov_b32_e32 v152, v135
	s_waitcnt lgkmcnt(0)
	v_pk_fma_f32 v[146:147], v[148:149], v[134:135], v[116:117] op_sel_hi:[1,1,0] neg_lo:[1,0,0] neg_hi:[1,0,0]
	v_mov_b32_e32 v153, v134
	v_mul_f32_e32 v116, v149, v134
	v_pk_fma_f32 v[152:153], v[148:149], v[152:153], v[116:117] op_sel_hi:[1,1,0]
	v_sub_f32_e32 v116, v132, v154

; __device__ __forceinline__ void inproj_tile(const Params& p, char* smem, int l, int mt, int nt) {
;     ...
;           float ss = 0.f;
; #pragma unroll
;           for (int n = 0; n < 4; ++n) ss += acc[m][n][j] * acc[m][n][j];
;           ss += __shfl_xor(ss, 1); ss += __shfl_xor(ss, 2); ss += __shfl_xor(ss, 4); ss += __shfl_xor(ss, 8);
;           float rstd = rsqrtf(ss * (1.f / 64.f) + EPSF);
;           int row = rowbase + m * 16 + fq * 4 + j;
;           float v[4];
; #pragma unroll
;           for (int n = 0; n < 4; ++n) v[n] = acc[m][n][j] * rstd * w4[n];
;           bool lat = row < MLAT;
;           float rv[4] = {v[0], v[1], v[2], v[3]};
;           if (lat) {
;             int t = row & 8191, pr = t >> 6, pc = t & 63;
;             float c0 = rope[pr * 16 + fr], s0 = rope[2048 + pr * 16 + fr];
;             float c1 = rope[pc * 16 + fr], s1 = rope[2048 + pc * 16 + fr];
;             rv[0] = v[0] * c0 - v[1] * s0; rv[1] = v[1] * c0 + v[0] * s0;
;             rv[2] = v[2] * c1 - v[3] * s1; rv[3] = v[3] * c1 + v[2] * s1;
.LBB0_321:
	s_or_b64 exec, exec, s[0:1]
	v_mov_b32_e32 v124, v121
	v_pk_mul_f32 v[144:145], v[124:125], v[124:125]
	v_mov_b32_e32 v116, v129
	v_pk_mul_f32 v[128:129], v[116:117], v[116:117]
	v_add_f32_e32 v3, v144, v145
	v_add_f32_e32 v3, v129, v3
	v_add_f32_e32 v3, v128, v3
	s_nop 1
	v_mov_b32_dpp v120, v3 quad_perm:[1,0,3,2] row_mask:0xf bank_mask:0xf
	s_waitcnt lgkmcnt(0)
	v_add_f32_e32 v3, v3, v120
	s_nop 1
	v_mov_b32_dpp v120, v3 quad_perm:[2,3,0,1] row_mask:0xf bank_mask:0xf
	s_waitcnt lgkmcnt(0)
	v_add_f32_e32 v3, v3, v120
	s_nop 1
	v_mov_b32_dpp v120, v3 row_half_mirror row_mask:0xf bank_mask:0xf
	s_waitcnt lgkmcnt(0)
	v_add_f32_e32 v3, v3, v120
	s_nop 1
	v_mov_b32_dpp v120, v3 row_mirror row_mask:0xf bank_mask:0xf
	s_waitcnt lgkmcnt(0)
	v_add_f32_e32 v3, v3, v120
	v_fmamk_f32 v3, v3, 0x3c800000, v197
	v_cmp_gt_f32_e32 vcc, s92, v3
	v_mul_f32_e32 v120, 0x4b800000, v3
	s_nop 0
	v_cndmask_b32_e32 v3, v3, v120, vcc
	v_rsq_f32_e32 v3, v3
	s_nop 0
	v_mul_f32_e32 v120, 0x45800000, v3
	v_cndmask_b32_e32 v128, v3, v120, vcc
	v_mov_b32_e32 v120, v125
	v_pk_mul_f32 v[120:121], v[128:129], v[120:121] op_sel_hi:[0,1]
	v_pk_mul_f32 v[116:117], v[128:129], v[116:117] op_sel_hi:[0,1]
	v_pk_mul_f32 v[124:125], v[138:139], v[120:121]
	v_pk_mul_f32 v[116:117], v[136:137], v[116:117]
	v_or_b32_e32 v120, 1, v2
	v_cmp_gt_i32_e64 s[0:1], s91, v120
	v_mov_b32_e32 v3, v124
	v_mov_b32_e32 v129, v125
	v_mov_b32_e32 v144, v117
	v_mov_b32_e32 v146, v116
	s_and_saveexec_b64 s[10:11], s[0:1]
	s_cbranch_execz .LBB0_323
	v_lshlrev_b32_e32 v3, 4, v120
	s_movk_i32 s12, 0xd0
	v_and_or_b32 v3, v3, s12, v168
	v_mov_b32_e32 v143, v1
	v_lshlrev_b32_e32 v146, 2, v3
	v_mov_b32_e32 v147, v1
	v_lshl_add_u64 v[128:129], s[6:7], 0, v[142:143]
	v_lshl_add_u64 v[146:147], s[6:7], 0, v[146:147]
	v_subrev_u32_e32 v211, s100, v128
	ds_read_b32 v144, v211
	v_subrev_u32_e32 v211, s100, v146
	ds_read_b32 v149, v211
	v_add_co_u32_e32 v128, vcc, 0x2000, v128
	s_waitcnt lgkmcnt(0)
	v_pk_mul_f32 v[150:151], v[124:125], v[144:145] op_sel_hi:[1,0]
	v_addc_co_u32_e32 v129, vcc, 0, v129, vcc
	v_subrev_u32_e32 v211, s100, v128
	ds_read_b32 v128, v211
	v_add_co_u32_e32 v146, vcc, 0x2000, v146
	s_nop 1
	v_addc_co_u32_e32 v147, vcc, 0, v147, vcc
	v_subrev_u32_e32 v211, s100, v146
	ds_read_b32 v148, v211
	v_mov_b32_e32 v146, v149
	s_waitcnt lgkmcnt(0)
	v_pk_mul_f32 v[152:153], v[124:125], v[128:129] op_sel:[1,0] op_sel_hi:[0,0]
	v_pk_fma_f32 v[128:129], v[124:125], v[144:145], v[152:153] op_sel_hi:[1,0,1]
	v_sub_f32_e32 v3, v150, v152
	v_mul_f32_e32 v128, v117, v149
	v_pk_fma_f32 v[144:145], v[116:117], v[148:149], v[128:129] op_sel_hi:[1,1,0] neg_lo:[1,0,0] neg_hi:[1,0,0]
	v_mov_b32_e32 v147, v148
	v_mul_f32_e32 v128, v117, v148
	v_pk_fma_f32 v[146:147], v[116:117], v[146:147], v[128:129] op_sel_hi:[1,1,0]

; __device__ __forceinline__ void inproj_tile(const Params& p, char* smem, int l, int mt, int nt) {
;     ...
;           float ss = 0.f;
; #pragma unroll
;           for (int n = 0; n < 4; ++n) ss += acc[m][n][j] * acc[m][n][j];
;           ss += __shfl_xor(ss, 1); ss += __shfl_xor(ss, 2); ss += __shfl_xor(ss, 4); ss += __shfl_xor(ss, 8);
;           float rstd = rsqrtf(ss * (1.f / 64.f) + EPSF);
;           int row = rowbase + m * 16 + fq * 4 + j;
;           float v[4];
; #pragma unroll
;           for (int n = 0; n < 4; ++n) v[n] = acc[m][n][j] * rstd * w4[n];
;           bool lat = row < MLAT;
;           float rv[4] = {v[0], v[1], v[2], v[3]};
;           if (lat) {
;             int t = row & 8191, pr = t >> 6, pc = t & 63;
;             float c0 = rope[pr * 16 + fr], s0 = rope[2048 + pr * 16 + fr];
;             float c1 = rope[pc * 16 + fr], s1 = rope[2048 + pc * 16 + fr];
;             rv[0] = v[0] * c0 - v[1] * s0; rv[1] = v[1] * c0 + v[0] * s0;
;             rv[2] = v[2] * c1 - v[3] * s1; rv[3] = v[3] * c1 + v[2] * s1;
.LBB0_331:
	s_or_b64 exec, exec, s[0:1]
	v_mov_b32_e32 v116, v122
	v_mov_b32_e32 v117, v126
	v_pk_mul_f32 v[116:117], v[116:117], v[116:117]
	v_mov_b32_e32 v120, v130
	v_mov_b32_e32 v121, v118
	v_pk_mul_f32 v[124:125], v[120:121], v[120:121]
	v_add_f32_e32 v3, v116, v117
	v_add_f32_e32 v3, v125, v3
	v_add_f32_e32 v3, v124, v3
	s_nop 1
	v_mov_b32_dpp v116, v3 quad_perm:[1,0,3,2] row_mask:0xf bank_mask:0xf
	v_mov_b32_e32 v124, v126
	v_mov_b32_e32 v125, v122
	s_waitcnt lgkmcnt(0)
	v_add_f32_e32 v3, v3, v116
	s_nop 1
	v_mov_b32_dpp v116, v3 quad_perm:[2,3,0,1] row_mask:0xf bank_mask:0xf
	s_waitcnt lgkmcnt(0)
	v_add_f32_e32 v3, v3, v116
	s_nop 1
	v_mov_b32_dpp v116, v3 row_half_mirror row_mask:0xf bank_mask:0xf
	s_waitcnt lgkmcnt(0)
	v_add_f32_e32 v3, v3, v116
	s_nop 1
	v_mov_b32_dpp v116, v3 row_mirror row_mask:0xf bank_mask:0xf
	s_waitcnt lgkmcnt(0)
	v_add_f32_e32 v3, v3, v116
	v_fmamk_f32 v3, v3, 0x3c800000, v197
	v_cmp_gt_f32_e32 vcc, s92, v3
	v_mul_f32_e32 v116, 0x4b800000, v3
	s_nop 0
	v_cndmask_b32_e32 v3, v3, v116, vcc
	v_rsq_f32_e32 v3, v3
	s_nop 0
	v_mul_f32_e32 v116, 0x45800000, v3
	v_cndmask_b32_e32 v116, v3, v116, vcc
	v_pk_mul_f32 v[124:125], v[116:117], v[124:125] op_sel_hi:[0,1]
	v_pk_mul_f32 v[116:117], v[116:117], v[120:121] op_sel_hi:[0,1]
	v_pk_mul_f32 v[124:125], v[138:139], v[124:125]
	v_pk_mul_f32 v[116:117], v[136:137], v[116:117]
	v_or_b32_e32 v120, 2, v2
	v_cmp_gt_i32_e64 s[0:1], s91, v120
	v_mov_b32_e32 v3, v124
	v_mov_b32_e32 v129, v125
	v_mov_b32_e32 v144, v117
	v_mov_b32_e32 v146, v116
	s_and_saveexec_b64 s[10:11], s[0:1]
	s_cbranch_execz .LBB0_333
	v_mov_b32_e32 v143, v1
	v_lshl_add_u64 v[128:129], s[6:7], 0, v[142:143]
	v_subrev_u32_e32 v211, s100, v128
	ds_read_b32 v118, v211
	v_add_co_u32_e32 v128, vcc, 0x2000, v128
	v_lshlrev_b32_e32 v3, 4, v120
	s_movk_i32 s12, 0xe0
	v_addc_co_u32_e32 v129, vcc, 0, v129, vcc
	v_and_or_b32 v3, v3, s12, v168
	v_subrev_u32_e32 v211, s100, v128
	ds_read_b32 v122, v211
	v_lshlrev_b32_e32 v128, 2, v3
	v_mov_b32_e32 v129, v1
	v_lshl_add_u64 v[128:129], s[6:7], 0, v[128:129]
	v_subrev_u32_e32 v211, s100, v128
	ds_read_b32 v147, v211
	v_add_co_u32_e32 v128, vcc, 0x2000, v128
	s_waitcnt lgkmcnt(0)
	v_pk_mul_f32 v[148:149], v[124:125], v[118:119] op_sel_hi:[1,0]
	v_addc_co_u32_e32 v129, vcc, 0, v129, vcc
	v_subrev_u32_e32 v211, s100, v128
	ds_read_b32 v146, v211
	v_pk_mul_f32 v[150:151], v[124:125], v[122:123] op_sel:[1,0] op_sel_hi:[0,0]
	v_pk_fma_f32 v[128:129], v[124:125], v[118:119], v[150:151] op_sel_hi:[1,0,1]
	v_sub_f32_e32 v3, v148, v150
	v_mul_f32_e32 v118, v117, v147
	v_mov_b32_e32 v152, v147
	s_waitcnt lgkmcnt(0)
	v_pk_fma_f32 v[144:145], v[116:117], v[146:147], v[118:119] op_sel_hi:[1,1,0] neg_lo:[1,0,0] neg_hi:[1,0,0]
	v_mov_b32_e32 v153, v146
	v_mul_f32_e32 v118, v117, v146
	v_pk_fma_f32 v[146:147], v[116:117], v[152:153], v[118:119] op_sel_hi:[1,1,0]

; __device__ __forceinline__ void inproj_tile(const Params& p, char* smem, int l, int mt, int nt) {
;     ...
;           float ss = 0.f;
; #pragma unroll
;           for (int n = 0; n < 4; ++n) ss += acc[m][n][j] * acc[m][n][j];
;           ss += __shfl_xor(ss, 1); ss += __shfl_xor(ss, 2); ss += __shfl_xor(ss, 4); ss += __shfl_xor(ss, 8);
;           float rstd = rsqrtf(ss * (1.f / 64.f) + EPSF);
;           int row = rowbase + m * 16 + fq * 4 + j;
;           float v[4];
; #pragma unroll
;           for (int n = 0; n < 4; ++n) v[n] = acc[m][n][j] * rstd * w4[n];
;           bool lat = row < MLAT;
;           float rv[4] = {v[0], v[1], v[2], v[3]};
;           if (lat) {
;             int t = row & 8191, pr = t >> 6, pc = t & 63;
;             float c0 = rope[pr * 16 + fr], s0 = rope[2048 + pr * 16 + fr];
;             float c1 = rope[pc * 16 + fr], s1 = rope[2048 + pc * 16 + fr];
;             rv[0] = v[0] * c0 - v[1] * s0; rv[1] = v[1] * c0 + v[0] * s0;
;             rv[2] = v[2] * c1 - v[3] * s1; rv[3] = v[3] * c1 + v[2] * s1;
.LBB0_341:
	s_or_b64 exec, exec, s[0:1]
	v_mov_b32_e32 v126, v123
	v_pk_mul_f32 v[116:117], v[126:127], v[126:127]
	v_mov_b32_e32 v118, v131
	v_pk_mul_f32 v[120:121], v[118:119], v[118:119]
	v_add_f32_e32 v3, v116, v117
	v_add_f32_e32 v3, v121, v3
	v_add_f32_e32 v3, v120, v3
	s_nop 1
	v_mov_b32_dpp v116, v3 quad_perm:[1,0,3,2] row_mask:0xf bank_mask:0xf
	v_mov_b32_e32 v122, v127
	s_waitcnt lgkmcnt(0)
	v_add_f32_e32 v3, v3, v116
	s_nop 1
	v_mov_b32_dpp v116, v3 quad_perm:[2,3,0,1] row_mask:0xf bank_mask:0xf
	s_waitcnt lgkmcnt(0)
	v_add_f32_e32 v3, v3, v116
	s_nop 1
	v_mov_b32_dpp v116, v3 row_half_mirror row_mask:0xf bank_mask:0xf
	s_waitcnt lgkmcnt(0)
	v_add_f32_e32 v3, v3, v116
	s_nop 1
	v_mov_b32_dpp v116, v3 row_mirror row_mask:0xf bank_mask:0xf
	s_waitcnt lgkmcnt(0)
	v_add_f32_e32 v3, v3, v116
	v_fmamk_f32 v3, v3, 0x3c800000, v197
	v_cmp_gt_f32_e32 vcc, s92, v3
	v_mul_f32_e32 v116, 0x4b800000, v3
	s_nop 0
	v_cndmask_b32_e32 v3, v3, v116, vcc
	v_rsq_f32_e32 v3, v3
	s_nop 0
	v_mul_f32_e32 v116, 0x45800000, v3
	v_cndmask_b32_e32 v116, v3, v116, vcc
	v_pk_mul_f32 v[120:121], v[116:117], v[122:123] op_sel_hi:[0,1]
	v_pk_mul_f32 v[116:117], v[116:117], v[118:119] op_sel_hi:[0,1]
	v_pk_mul_f32 v[120:121], v[138:139], v[120:121]
	v_pk_mul_f32 v[116:117], v[136:137], v[116:117]
	v_or_b32_e32 v118, 3, v2
	v_cmp_gt_i32_e64 s[0:1], s91, v118
	v_mov_b32_e32 v3, v120
	v_mov_b32_e32 v123, v121
	v_mov_b32_e32 v124, v117
	v_mov_b32_e32 v126, v116
	s_and_saveexec_b64 s[10:11], s[0:1]
	s_cbranch_execz .LBB0_343
	v_lshlrev_b32_e32 v3, 4, v118
	s_movk_i32 s12, 0xf0
	v_and_or_b32 v3, v3, s12, v168
	v_mov_b32_e32 v143, v1
	v_lshlrev_b32_e32 v126, 2, v3
	v_mov_b32_e32 v127, v1
	v_lshl_add_u64 v[122:123], s[6:7], 0, v[142:143]
	v_lshl_add_u64 v[126:127], s[6:7], 0, v[126:127]
	v_subrev_u32_e32 v211, s100, v122
	ds_read_b32 v124, v211
	v_subrev_u32_e32 v211, s100, v126
	ds_read_b32 v129, v211
	v_add_co_u32_e32 v122, vcc, 0x2000, v122
	s_waitcnt lgkmcnt(0)
	v_pk_mul_f32 v[130:131], v[120:121], v[124:125] op_sel_hi:[1,0]
	v_addc_co_u32_e32 v123, vcc, 0, v123, vcc
	v_subrev_u32_e32 v211, s100, v122
	ds_read_b32 v122, v211
	v_add_co_u32_e32 v126, vcc, 0x2000, v126
	s_nop 1
	v_addc_co_u32_e32 v127, vcc, 0, v127, vcc
	v_subrev_u32_e32 v211, s100, v126
	ds_read_b32 v128, v211
	v_mov_b32_e32 v126, v129
	s_waitcnt lgkmcnt(0)
	v_pk_mul_f32 v[144:145], v[120:121], v[122:123] op_sel:[1,0] op_sel_hi:[0,0]
	v_pk_fma_f32 v[122:123], v[120:121], v[124:125], v[144:145] op_sel_hi:[1,0,1]
	v_sub_f32_e32 v3, v130, v144
	v_mul_f32_e32 v122, v117, v129
	v_pk_fma_f32 v[124:125], v[116:117], v[128:129], v[122:123] op_sel_hi:[1,1,0] neg_lo:[1,0,0] neg_hi:[1,0,0]
	v_mov_b32_e32 v127, v128
	v_mul_f32_e32 v122, v117, v128
	v_pk_fma_f32 v[126:127], v[116:117], v[126:127], v[122:123] op_sel_hi:[1,1,0]

; __device__ __forceinline__ void inproj_tile(const Params& p, char* smem, int l, int mt, int nt) {
;     ...
;           float ss = 0.f;
; #pragma unroll
;           for (int n = 0; n < 4; ++n) ss += acc[m][n][j] * acc[m][n][j];
;           ss += __shfl_xor(ss, 1); ss += __shfl_xor(ss, 2); ss += __shfl_xor(ss, 4); ss += __shfl_xor(ss, 8);
;           float rstd = rsqrtf(ss * (1.f / 64.f) + EPSF);
;           int row = rowbase + m * 16 + fq * 4 + j;
;           float v[4];
; #pragma unroll
;           for (int n = 0; n < 4; ++n) v[n] = acc[m][n][j] * rstd * w4[n];
;           bool lat = row < MLAT;
;           float rv[4] = {v[0], v[1], v[2], v[3]};
;           if (lat) {
;             int t = row & 8191, pr = t >> 6, pc = t & 63;
;             float c0 = rope[pr * 16 + fr], s0 = rope[2048 + pr * 16 + fr];
;             float c1 = rope[pc * 16 + fr], s1 = rope[2048 + pc * 16 + fr];
;             rv[0] = v[0] * c0 - v[1] * s0; rv[1] = v[1] * c0 + v[0] * s0;
;             rv[2] = v[2] * c1 - v[3] * s1; rv[3] = v[3] * c1 + v[2] * s1;
.LBB0_351:
	s_or_b64 exec, exec, s[0:1]
	v_mov_b32_e32 v118, v104
	v_mov_b32_e32 v119, v108
	v_pk_mul_f32 v[118:119], v[118:119], v[118:119]
	v_mov_b32_e32 v122, v112
	v_mov_b32_e32 v123, v100
	v_pk_mul_f32 v[120:121], v[122:123], v[122:123]
	v_add_f32_e32 v3, v118, v119
	v_add_f32_e32 v3, v121, v3
	v_add_f32_e32 v3, v120, v3
	s_nop 1
	v_mov_b32_dpp v100, v3 quad_perm:[1,0,3,2] row_mask:0xf bank_mask:0xf
	v_mov_b32_e32 v118, v108
	v_mov_b32_e32 v119, v104
	v_or_b32_e32 v116, 16, v2
	v_cmp_gt_i32_e64 s[0:1], s91, v116
	s_waitcnt lgkmcnt(0)
	v_add_f32_e32 v3, v3, v100
	s_nop 1
	v_mov_b32_dpp v100, v3 quad_perm:[2,3,0,1] row_mask:0xf bank_mask:0xf
	s_waitcnt lgkmcnt(0)
	v_add_f32_e32 v3, v3, v100
	s_nop 1
	v_mov_b32_dpp v100, v3 row_half_mirror row_mask:0xf bank_mask:0xf
	s_waitcnt lgkmcnt(0)
	v_add_f32_e32 v3, v3, v100
	s_nop 1
	v_mov_b32_dpp v100, v3 row_mirror row_mask:0xf bank_mask:0xf
	s_waitcnt lgkmcnt(0)
	v_add_f32_e32 v3, v3, v100
	v_fmamk_f32 v3, v3, 0x3c800000, v197
	v_cmp_gt_f32_e32 vcc, s92, v3
	v_mul_f32_e32 v100, 0x4b800000, v3
	s_nop 0
	v_cndmask_b32_e32 v3, v3, v100, vcc
	v_rsq_f32_e32 v3, v3
	s_nop 0
	v_mul_f32_e32 v100, 0x45800000, v3
	v_cndmask_b32_e32 v100, v3, v100, vcc
	v_pk_mul_f32 v[118:119], v[100:101], v[118:119] op_sel_hi:[0,1]
	v_pk_mul_f32 v[120:121], v[138:139], v[118:119]
	v_pk_mul_f32 v[118:119], v[100:101], v[122:123] op_sel_hi:[0,1]
	v_pk_mul_f32 v[118:119], v[136:137], v[118:119]
	v_mov_b32_e32 v3, v120
	v_mov_b32_e32 v123, v121
	v_mov_b32_e32 v124, v119
	v_mov_b32_e32 v126, v118
	s_and_saveexec_b64 s[10:11], s[0:1]
	s_cbranch_execz .LBB0_353
	v_mov_b32_e32 v143, v1
	v_lshl_add_u64 v[122:123], s[6:7], 0, v[142:143]
	v_subrev_u32_e32 v211, s100, v122
	ds_read_b32 v100, v211
	v_add_co_u32_e32 v122, vcc, 0x2000, v122
	v_lshlrev_b32_e32 v3, 4, v116
	s_movk_i32 s12, 0x1c0
	v_addc_co_u32_e32 v123, vcc, 0, v123, vcc
	v_and_or_b32 v3, v3, s12, v168
	v_subrev_u32_e32 v211, s100, v122
	ds_read_b32 v104, v211
	v_lshlrev_b32_e32 v122, 2, v3
	v_mov_b32_e32 v123, v1
	v_lshl_add_u64 v[122:123], s[6:7], 0, v[122:123]
	v_subrev_u32_e32 v211, s100, v122
	ds_read_b32 v127, v211
	v_add_co_u32_e32 v122, vcc, 0x2000, v122
	s_waitcnt lgkmcnt(0)
	v_pk_mul_f32 v[128:129], v[120:121], v[100:101] op_sel_hi:[1,0]
	v_addc_co_u32_e32 v123, vcc, 0, v123, vcc
	v_subrev_u32_e32 v211, s100, v122
	ds_read_b32 v126, v211
	v_pk_mul_f32 v[130:131], v[120:121], v[104:105] op_sel:[1,0] op_sel_hi:[0,0]
	v_pk_fma_f32 v[122:123], v[120:121], v[100:101], v[130:131] op_sel_hi:[1,0,1]
	v_sub_f32_e32 v3, v128, v130
	v_mul_f32_e32 v100, v119, v127
	v_mov_b32_e32 v144, v127
	s_waitcnt lgkmcnt(0)
	v_pk_fma_f32 v[124:125], v[118:119], v[126:127], v[100:101] op_sel_hi:[1,1,0] neg_lo:[1,0,0] neg_hi:[1,0,0]
	v_mov_b32_e32 v145, v126
	v_mul_f32_e32 v100, v119, v126
	v_pk_fma_f32 v[126:127], v[118:119], v[144:145], v[100:101] op_sel_hi:[1,1,0]

; __device__ __forceinline__ void inproj_tile(const Params& p, char* smem, int l, int mt, int nt) {
;     ...
;           float ss = 0.f;
; #pragma unroll
;           for (int n = 0; n < 4; ++n) ss += acc[m][n][j] * acc[m][n][j];
;           ss += __shfl_xor(ss, 1); ss += __shfl_xor(ss, 2); ss += __shfl_xor(ss, 4); ss += __shfl_xor(ss, 8);
;           float rstd = rsqrtf(ss * (1.f / 64.f) + EPSF);
;           int row = rowbase + m * 16 + fq * 4 + j;
;           float v[4];
; #pragma unroll
;           for (int n = 0; n < 4; ++n) v[n] = acc[m][n][j] * rstd * w4[n];
;           bool lat = row < MLAT;
;           float rv[4] = {v[0], v[1], v[2], v[3]};
;           if (lat) {
;             int t = row & 8191, pr = t >> 6, pc = t & 63;
;             float c0 = rope[pr * 16 + fr], s0 = rope[2048 + pr * 16 + fr];
;             float c1 = rope[pc * 16 + fr], s1 = rope[2048 + pc * 16 + fr];
;             rv[0] = v[0] * c0 - v[1] * s0; rv[1] = v[1] * c0 + v[0] * s0;
;             rv[2] = v[2] * c1 - v[3] * s1; rv[3] = v[3] * c1 + v[2] * s1;
.LBB0_361:
	s_or_b64 exec, exec, s[0:1]
	v_mov_b32_e32 v108, v105
	v_pk_mul_f32 v[116:117], v[108:109], v[108:109]
	v_mov_b32_e32 v100, v113
	v_pk_mul_f32 v[112:113], v[100:101], v[100:101]
	v_add_f32_e32 v3, v116, v117
	v_add_f32_e32 v3, v113, v3
	v_add_f32_e32 v3, v112, v3
	s_nop 1
	v_mov_b32_dpp v104, v3 quad_perm:[1,0,3,2] row_mask:0xf bank_mask:0xf
	s_waitcnt lgkmcnt(0)
	v_add_f32_e32 v3, v3, v104
	s_nop 1
	v_mov_b32_dpp v104, v3 quad_perm:[2,3,0,1] row_mask:0xf bank_mask:0xf
	s_waitcnt lgkmcnt(0)
	v_add_f32_e32 v3, v3, v104
	s_nop 1
	v_mov_b32_dpp v104, v3 row_half_mirror row_mask:0xf bank_mask:0xf
	s_waitcnt lgkmcnt(0)
	v_add_f32_e32 v3, v3, v104
	s_nop 1
	v_mov_b32_dpp v104, v3 row_mirror row_mask:0xf bank_mask:0xf
	s_waitcnt lgkmcnt(0)
	v_add_f32_e32 v3, v3, v104
	v_fmamk_f32 v3, v3, 0x3c800000, v197
	v_cmp_gt_f32_e32 vcc, s92, v3
	v_mul_f32_e32 v104, 0x4b800000, v3
	s_nop 0
	v_cndmask_b32_e32 v3, v3, v104, vcc
	v_rsq_f32_e32 v3, v3
	s_nop 0
	v_mul_f32_e32 v104, 0x45800000, v3
	v_cndmask_b32_e32 v112, v3, v104, vcc
	v_mov_b32_e32 v104, v109
	v_pk_mul_f32 v[104:105], v[112:113], v[104:105] op_sel_hi:[0,1]
	v_pk_mul_f32 v[100:101], v[112:113], v[100:101] op_sel_hi:[0,1]
	v_pk_mul_f32 v[108:109], v[138:139], v[104:105]
	v_pk_mul_f32 v[100:101], v[136:137], v[100:101]
	v_or_b32_e32 v104, 17, v2
	v_cmp_gt_i32_e64 s[0:1], s91, v104
	v_mov_b32_e32 v3, v108
	v_mov_b32_e32 v113, v109
	v_mov_b32_e32 v116, v101
	v_mov_b32_e32 v118, v100
	s_and_saveexec_b64 s[10:11], s[0:1]
	s_cbranch_execz .LBB0_363
	v_lshlrev_b32_e32 v3, 4, v104
	s_movk_i32 s12, 0x1d0
	v_and_or_b32 v3, v3, s12, v168
	v_mov_b32_e32 v143, v1
	v_lshlrev_b32_e32 v118, 2, v3
	v_mov_b32_e32 v119, v1
	v_lshl_add_u64 v[112:113], s[6:7], 0, v[142:143]
	v_lshl_add_u64 v[118:119], s[6:7], 0, v[118:119]
	v_subrev_u32_e32 v211, s100, v112
	ds_read_b32 v116, v211
	v_subrev_u32_e32 v211, s100, v118
	ds_read_b32 v121, v211
	v_add_co_u32_e32 v112, vcc, 0x2000, v112
	s_waitcnt lgkmcnt(0)
	v_pk_mul_f32 v[122:123], v[108:109], v[116:117] op_sel_hi:[1,0]
	v_addc_co_u32_e32 v113, vcc, 0, v113, vcc
	v_subrev_u32_e32 v211, s100, v112
	ds_read_b32 v112, v211
	v_add_co_u32_e32 v118, vcc, 0x2000, v118
	s_nop 1
	v_addc_co_u32_e32 v119, vcc, 0, v119, vcc
	v_subrev_u32_e32 v211, s100, v118
	ds_read_b32 v120, v211
	v_mov_b32_e32 v118, v121
	s_waitcnt lgkmcnt(0)
	v_pk_mul_f32 v[124:125], v[108:109], v[112:113] op_sel:[1,0] op_sel_hi:[0,0]
	v_pk_fma_f32 v[112:113], v[108:109], v[116:117], v[124:125] op_sel_hi:[1,0,1]
	v_sub_f32_e32 v3, v122, v124
	v_mul_f32_e32 v112, v101, v121
	v_pk_fma_f32 v[116:117], v[100:101], v[120:121], v[112:113] op_sel_hi:[1,1,0] neg_lo:[1,0,0] neg_hi:[1,0,0]
	v_mov_b32_e32 v119, v120
	v_mul_f32_e32 v112, v101, v120
	v_pk_fma_f32 v[118:119], v[100:101], v[118:119], v[112:113] op_sel_hi:[1,1,0]

; __device__ __forceinline__ void inproj_tile(const Params& p, char* smem, int l, int mt, int nt) {
;     ...
;           float ss = 0.f;
; #pragma unroll
;           for (int n = 0; n < 4; ++n) ss += acc[m][n][j] * acc[m][n][j];
;           ss += __shfl_xor(ss, 1); ss += __shfl_xor(ss, 2); ss += __shfl_xor(ss, 4); ss += __shfl_xor(ss, 8);
;           float rstd = rsqrtf(ss * (1.f / 64.f) + EPSF);
;           int row = rowbase + m * 16 + fq * 4 + j;
;           float v[4];
; #pragma unroll
;           for (int n = 0; n < 4; ++n) v[n] = acc[m][n][j] * rstd * w4[n];
;           bool lat = row < MLAT;
;           float rv[4] = {v[0], v[1], v[2], v[3]};
;           if (lat) {
;             int t = row & 8191, pr = t >> 6, pc = t & 63;
;             float c0 = rope[pr * 16 + fr], s0 = rope[2048 + pr * 16 + fr];
;             float c1 = rope[pc * 16 + fr], s1 = rope[2048 + pc * 16 + fr];
;             rv[0] = v[0] * c0 - v[1] * s0; rv[1] = v[1] * c0 + v[0] * s0;
;             rv[2] = v[2] * c1 - v[3] * s1; rv[3] = v[3] * c1 + v[2] * s1;
.LBB0_371:
	s_or_b64 exec, exec, s[0:1]
	v_mov_b32_e32 v100, v106
	v_mov_b32_e32 v101, v110
	v_pk_mul_f32 v[100:101], v[100:101], v[100:101]
	v_mov_b32_e32 v104, v114
	v_mov_b32_e32 v105, v102
	v_pk_mul_f32 v[108:109], v[104:105], v[104:105]
	v_add_f32_e32 v3, v100, v101
	v_add_f32_e32 v3, v109, v3
	v_add_f32_e32 v3, v108, v3
	s_nop 1
	v_mov_b32_dpp v100, v3 quad_perm:[1,0,3,2] row_mask:0xf bank_mask:0xf
	v_mov_b32_e32 v108, v110
	v_mov_b32_e32 v109, v106
	s_waitcnt lgkmcnt(0)
	v_add_f32_e32 v3, v3, v100
	s_nop 1
	v_mov_b32_dpp v100, v3 quad_perm:[2,3,0,1] row_mask:0xf bank_mask:0xf
	s_waitcnt lgkmcnt(0)
	v_add_f32_e32 v3, v3, v100
	s_nop 1
	v_mov_b32_dpp v100, v3 row_half_mirror row_mask:0xf bank_mask:0xf
	s_waitcnt lgkmcnt(0)
	v_add_f32_e32 v3, v3, v100
	s_nop 1
	v_mov_b32_dpp v100, v3 row_mirror row_mask:0xf bank_mask:0xf
	s_waitcnt lgkmcnt(0)
	v_add_f32_e32 v3, v3, v100
	v_fmamk_f32 v3, v3, 0x3c800000, v197
	v_cmp_gt_f32_e32 vcc, s92, v3
	v_mul_f32_e32 v100, 0x4b800000, v3
	s_nop 0
	v_cndmask_b32_e32 v3, v3, v100, vcc
	v_rsq_f32_e32 v3, v3
	s_nop 0
	v_mul_f32_e32 v100, 0x45800000, v3
	v_cndmask_b32_e32 v100, v3, v100, vcc
	v_pk_mul_f32 v[108:109], v[100:101], v[108:109] op_sel_hi:[0,1]
	v_pk_mul_f32 v[100:101], v[100:101], v[104:105] op_sel_hi:[0,1]
	v_pk_mul_f32 v[108:109], v[138:139], v[108:109]
	v_pk_mul_f32 v[100:101], v[136:137], v[100:101]
	v_or_b32_e32 v104, 18, v2
	v_cmp_gt_i32_e64 s[0:1], s91, v104
	v_mov_b32_e32 v3, v108
	v_mov_b32_e32 v113, v109
	v_mov_b32_e32 v116, v101
	v_mov_b32_e32 v118, v100
	s_and_saveexec_b64 s[10:11], s[0:1]
	s_cbranch_execz .LBB0_373
	v_mov_b32_e32 v143, v1
	v_lshl_add_u64 v[112:113], s[6:7], 0, v[142:143]
	v_subrev_u32_e32 v211, s100, v112
	ds_read_b32 v102, v211
	v_add_co_u32_e32 v112, vcc, 0x2000, v112
	v_lshlrev_b32_e32 v3, 4, v104
	s_nop 0
	v_addc_co_u32_e32 v113, vcc, 0, v113, vcc
	v_and_or_b32 v3, v3, s40, v168
	v_subrev_u32_e32 v211, s100, v112
	ds_read_b32 v106, v211
	v_lshlrev_b32_e32 v112, 2, v3
	v_mov_b32_e32 v113, v1
	v_lshl_add_u64 v[112:113], s[6:7], 0, v[112:113]
	v_subrev_u32_e32 v211, s100, v112
	ds_read_b32 v119, v211
	v_add_co_u32_e32 v112, vcc, 0x2000, v112
	s_waitcnt lgkmcnt(0)
	v_pk_mul_f32 v[120:121], v[108:109], v[102:103] op_sel_hi:[1,0]
	v_addc_co_u32_e32 v113, vcc, 0, v113, vcc
	v_subrev_u32_e32 v211, s100, v112
	ds_read_b32 v118, v211
	v_pk_mul_f32 v[122:123], v[108:109], v[106:107] op_sel:[1,0] op_sel_hi:[0,0]
	v_pk_fma_f32 v[112:113], v[108:109], v[102:103], v[122:123] op_sel_hi:[1,0,1]
	v_sub_f32_e32 v3, v120, v122
	v_mul_f32_e32 v102, v101, v119
	v_mov_b32_e32 v124, v119
	s_waitcnt lgkmcnt(0)
	v_pk_fma_f32 v[116:117], v[100:101], v[118:119], v[102:103] op_sel_hi:[1,1,0] neg_lo:[1,0,0] neg_hi:[1,0,0]
	v_mov_b32_e32 v125, v118
	v_mul_f32_e32 v102, v101, v118
	v_pk_fma_f32 v[118:119], v[100:101], v[124:125], v[102:103] op_sel_hi:[1,1,0]

; __device__ __forceinline__ void inproj_tile(const Params& p, char* smem, int l, int mt, int nt) {
;     ...
;           float ss = 0.f;
; #pragma unroll
;           for (int n = 0; n < 4; ++n) ss += acc[m][n][j] * acc[m][n][j];
;           ss += __shfl_xor(ss, 1); ss += __shfl_xor(ss, 2); ss += __shfl_xor(ss, 4); ss += __shfl_xor(ss, 8);
;           float rstd = rsqrtf(ss * (1.f / 64.f) + EPSF);
;           int row = rowbase + m * 16 + fq * 4 + j;
;           float v[4];
; #pragma unroll
;           for (int n = 0; n < 4; ++n) v[n] = acc[m][n][j] * rstd * w4[n];
;           bool lat = row < MLAT;
;           float rv[4] = {v[0], v[1], v[2], v[3]};
;           if (lat) {
;             int t = row & 8191, pr = t >> 6, pc = t & 63;
;             float c0 = rope[pr * 16 + fr], s0 = rope[2048 + pr * 16 + fr];
;             float c1 = rope[pc * 16 + fr], s1 = rope[2048 + pc * 16 + fr];
;             rv[0] = v[0] * c0 - v[1] * s0; rv[1] = v[1] * c0 + v[0] * s0;
;             rv[2] = v[2] * c1 - v[3] * s1; rv[3] = v[3] * c1 + v[2] * s1;
.LBB0_381:
	s_or_b64 exec, exec, s[0:1]
	v_mov_b32_e32 v110, v107
	v_pk_mul_f32 v[100:101], v[110:111], v[110:111]
	v_mov_b32_e32 v102, v115
	v_pk_mul_f32 v[104:105], v[102:103], v[102:103]
	v_add_f32_e32 v3, v100, v101
	v_add_f32_e32 v3, v105, v3
	v_add_f32_e32 v3, v104, v3
	s_nop 1
	v_mov_b32_dpp v100, v3 quad_perm:[1,0,3,2] row_mask:0xf bank_mask:0xf
	v_mov_b32_e32 v106, v111
	s_waitcnt lgkmcnt(0)
	v_add_f32_e32 v3, v3, v100
	s_nop 1
	v_mov_b32_dpp v100, v3 quad_perm:[2,3,0,1] row_mask:0xf bank_mask:0xf
	s_waitcnt lgkmcnt(0)
	v_add_f32_e32 v3, v3, v100
	s_nop 1
	v_mov_b32_dpp v100, v3 row_half_mirror row_mask:0xf bank_mask:0xf
	s_waitcnt lgkmcnt(0)
	v_add_f32_e32 v3, v3, v100
	s_nop 1
	v_mov_b32_dpp v100, v3 row_mirror row_mask:0xf bank_mask:0xf
	s_waitcnt lgkmcnt(0)
	v_add_f32_e32 v3, v3, v100
	v_fmamk_f32 v3, v3, 0x3c800000, v197
	v_cmp_gt_f32_e32 vcc, s92, v3
	v_mul_f32_e32 v100, 0x4b800000, v3
	s_nop 0
	v_cndmask_b32_e32 v3, v3, v100, vcc
	v_rsq_f32_e32 v3, v3
	s_nop 0
	v_mul_f32_e32 v100, 0x45800000, v3
	v_cndmask_b32_e32 v100, v3, v100, vcc
	v_pk_mul_f32 v[104:105], v[100:101], v[106:107] op_sel_hi:[0,1]
	v_pk_mul_f32 v[100:101], v[100:101], v[102:103] op_sel_hi:[0,1]
	v_pk_mul_f32 v[104:105], v[138:139], v[104:105]
	v_pk_mul_f32 v[100:101], v[136:137], v[100:101]
	v_or_b32_e32 v102, 19, v2
	v_cmp_gt_i32_e64 s[0:1], s91, v102
	v_mov_b32_e32 v3, v104
	v_mov_b32_e32 v107, v105
	v_mov_b32_e32 v108, v101
	v_mov_b32_e32 v110, v100
	s_and_saveexec_b64 s[10:11], s[0:1]
	s_cbranch_execz .LBB0_383
	v_lshlrev_b32_e32 v3, 4, v102
	s_movk_i32 s12, 0x1f0
	v_and_or_b32 v3, v3, s12, v168
	v_mov_b32_e32 v143, v1
	v_lshlrev_b32_e32 v110, 2, v3
	v_mov_b32_e32 v111, v1
	v_lshl_add_u64 v[106:107], s[6:7], 0, v[142:143]
	v_lshl_add_u64 v[110:111], s[6:7], 0, v[110:111]
	v_subrev_u32_e32 v211, s100, v106
	ds_read_b32 v108, v211
	v_subrev_u32_e32 v211, s100, v110
	ds_read_b32 v113, v211
	v_add_co_u32_e32 v106, vcc, 0x2000, v106
	s_waitcnt lgkmcnt(0)
	v_pk_mul_f32 v[114:115], v[104:105], v[108:109] op_sel_hi:[1,0]
	v_addc_co_u32_e32 v107, vcc, 0, v107, vcc
	v_subrev_u32_e32 v211, s100, v106
	ds_read_b32 v106, v211
	v_add_co_u32_e32 v110, vcc, 0x2000, v110
	s_nop 1
	v_addc_co_u32_e32 v111, vcc, 0, v111, vcc
	v_subrev_u32_e32 v211, s100, v110
	ds_read_b32 v112, v211
	v_mov_b32_e32 v110, v113
	s_waitcnt lgkmcnt(0)
	v_pk_mul_f32 v[116:117], v[104:105], v[106:107] op_sel:[1,0] op_sel_hi:[0,0]
	v_pk_fma_f32 v[106:107], v[104:105], v[108:109], v[116:117] op_sel_hi:[1,0,1]
	v_sub_f32_e32 v3, v114, v116
	v_mul_f32_e32 v106, v101, v113
	v_pk_fma_f32 v[108:109], v[100:101], v[112:113], v[106:107] op_sel_hi:[1,1,0] neg_lo:[1,0,0] neg_hi:[1,0,0]
	v_mov_b32_e32 v111, v112
	v_mul_f32_e32 v106, v101, v112
	v_pk_fma_f32 v[110:111], v[100:101], v[110:111], v[106:107] op_sel_hi:[1,1,0]

; __device__ __forceinline__ void inproj_tile(const Params& p, char* smem, int l, int mt, int nt) {
;     ...
;           float ss = 0.f;
; #pragma unroll
;           for (int n = 0; n < 4; ++n) ss += acc[m][n][j] * acc[m][n][j];
;           ss += __shfl_xor(ss, 1); ss += __shfl_xor(ss, 2); ss += __shfl_xor(ss, 4); ss += __shfl_xor(ss, 8);
;           float rstd = rsqrtf(ss * (1.f / 64.f) + EPSF);
;           int row = rowbase + m * 16 + fq * 4 + j;
;           float v[4];
; #pragma unroll
;           for (int n = 0; n < 4; ++n) v[n] = acc[m][n][j] * rstd * w4[n];
;           bool lat = row < MLAT;
;           float rv[4] = {v[0], v[1], v[2], v[3]};
;           if (lat) {
;             int t = row & 8191, pr = t >> 6, pc = t & 63;
;             float c0 = rope[pr * 16 + fr], s0 = rope[2048 + pr * 16 + fr];
;             float c1 = rope[pc * 16 + fr], s1 = rope[2048 + pc * 16 + fr];
;             rv[0] = v[0] * c0 - v[1] * s0; rv[1] = v[1] * c0 + v[0] * s0;
;             rv[2] = v[2] * c1 - v[3] * s1; rv[3] = v[3] * c1 + v[2] * s1;
.LBB0_391:
	s_or_b64 exec, exec, s[0:1]
	v_mov_b32_e32 v102, v88
	v_mov_b32_e32 v103, v92
	v_pk_mul_f32 v[102:103], v[102:103], v[102:103]
	v_mov_b32_e32 v106, v96
	v_mov_b32_e32 v107, v84
	v_pk_mul_f32 v[104:105], v[106:107], v[106:107]
	v_add_f32_e32 v3, v102, v103
	v_add_f32_e32 v3, v105, v3
	v_add_f32_e32 v3, v104, v3
	s_nop 1
	v_mov_b32_dpp v84, v3 quad_perm:[1,0,3,2] row_mask:0xf bank_mask:0xf
	v_mov_b32_e32 v102, v92
	v_mov_b32_e32 v103, v88
	v_or_b32_e32 v100, 32, v2
	v_cmp_gt_i32_e64 s[0:1], s91, v100
	s_waitcnt lgkmcnt(0)
	v_add_f32_e32 v3, v3, v84
	s_nop 1
	v_mov_b32_dpp v84, v3 quad_perm:[2,3,0,1] row_mask:0xf bank_mask:0xf
	s_waitcnt lgkmcnt(0)
	v_add_f32_e32 v3, v3, v84
	s_nop 1
	v_mov_b32_dpp v84, v3 row_half_mirror row_mask:0xf bank_mask:0xf
	s_waitcnt lgkmcnt(0)
	v_add_f32_e32 v3, v3, v84
	s_nop 1
	v_mov_b32_dpp v84, v3 row_mirror row_mask:0xf bank_mask:0xf
	s_waitcnt lgkmcnt(0)
	v_add_f32_e32 v3, v3, v84
	v_fmamk_f32 v3, v3, 0x3c800000, v197
	v_cmp_gt_f32_e32 vcc, s92, v3
	v_mul_f32_e32 v84, 0x4b800000, v3
	s_nop 0
	v_cndmask_b32_e32 v3, v3, v84, vcc
	v_rsq_f32_e32 v3, v3
	s_nop 0
	v_mul_f32_e32 v84, 0x45800000, v3
	v_cndmask_b32_e32 v84, v3, v84, vcc
	v_pk_mul_f32 v[102:103], v[84:85], v[102:103] op_sel_hi:[0,1]
	v_pk_mul_f32 v[104:105], v[138:139], v[102:103]
	v_pk_mul_f32 v[102:103], v[84:85], v[106:107] op_sel_hi:[0,1]
	v_pk_mul_f32 v[102:103], v[136:137], v[102:103]
	v_mov_b32_e32 v3, v104
	v_mov_b32_e32 v107, v105
	v_mov_b32_e32 v108, v103
	v_mov_b32_e32 v110, v102
	s_and_saveexec_b64 s[10:11], s[0:1]
	s_cbranch_execz .LBB0_393
	v_mov_b32_e32 v143, v1
	v_lshl_add_u64 v[106:107], s[6:7], 0, v[142:143]
	v_subrev_u32_e32 v211, s100, v106
	ds_read_b32 v84, v211
	v_add_co_u32_e32 v106, vcc, 0x2000, v106
	v_lshlrev_b32_e32 v3, 4, v100
	s_movk_i32 s12, 0x2c0
	v_addc_co_u32_e32 v107, vcc, 0, v107, vcc
	v_and_or_b32 v3, v3, s12, v168
	v_subrev_u32_e32 v211, s100, v106
	ds_read_b32 v88, v211
	v_lshlrev_b32_e32 v106, 2, v3
	v_mov_b32_e32 v107, v1
	v_lshl_add_u64 v[106:107], s[6:7], 0, v[106:107]
	v_subrev_u32_e32 v211, s100, v106
	ds_read_b32 v111, v211
	v_add_co_u32_e32 v106, vcc, 0x2000, v106
	s_waitcnt lgkmcnt(0)
	v_pk_mul_f32 v[112:113], v[104:105], v[84:85] op_sel_hi:[1,0]
	v_addc_co_u32_e32 v107, vcc, 0, v107, vcc
	v_subrev_u32_e32 v211, s100, v106
	ds_read_b32 v110, v211
	v_pk_mul_f32 v[114:115], v[104:105], v[88:89] op_sel:[1,0] op_sel_hi:[0,0]
	v_pk_fma_f32 v[106:107], v[104:105], v[84:85], v[114:115] op_sel_hi:[1,0,1]
	v_sub_f32_e32 v3, v112, v114
	v_mul_f32_e32 v84, v103, v111
	v_mov_b32_e32 v116, v111
	s_waitcnt lgkmcnt(0)
	v_pk_fma_f32 v[108:109], v[102:103], v[110:111], v[84:85] op_sel_hi:[1,1,0] neg_lo:[1,0,0] neg_hi:[1,0,0]
	v_mov_b32_e32 v117, v110
	v_mul_f32_e32 v84, v103, v110
	v_pk_fma_f32 v[110:111], v[102:103], v[116:117], v[84:85] op_sel_hi:[1,1,0]

; __device__ __forceinline__ void inproj_tile(const Params& p, char* smem, int l, int mt, int nt) {
;     ...
;           float ss = 0.f;
; #pragma unroll
;           for (int n = 0; n < 4; ++n) ss += acc[m][n][j] * acc[m][n][j];
;           ss += __shfl_xor(ss, 1); ss += __shfl_xor(ss, 2); ss += __shfl_xor(ss, 4); ss += __shfl_xor(ss, 8);
;           float rstd = rsqrtf(ss * (1.f / 64.f) + EPSF);
;           int row = rowbase + m * 16 + fq * 4 + j;
;           float v[4];
; #pragma unroll
;           for (int n = 0; n < 4; ++n) v[n] = acc[m][n][j] * rstd * w4[n];
;           bool lat = row < MLAT;
;           float rv[4] = {v[0], v[1], v[2], v[3]};
;           if (lat) {
;             int t = row & 8191, pr = t >> 6, pc = t & 63;
;             float c0 = rope[pr * 16 + fr], s0 = rope[2048 + pr * 16 + fr];
;             float c1 = rope[pc * 16 + fr], s1 = rope[2048 + pc * 16 + fr];
;             rv[0] = v[0] * c0 - v[1] * s0; rv[1] = v[1] * c0 + v[0] * s0;
;             rv[2] = v[2] * c1 - v[3] * s1; rv[3] = v[3] * c1 + v[2] * s1;
.LBB0_401:
	s_or_b64 exec, exec, s[0:1]
	v_mov_b32_e32 v92, v89
	v_pk_mul_f32 v[100:101], v[92:93], v[92:93]
	v_mov_b32_e32 v84, v97
	v_pk_mul_f32 v[96:97], v[84:85], v[84:85]
	v_add_f32_e32 v3, v100, v101
	v_add_f32_e32 v3, v97, v3
	v_add_f32_e32 v3, v96, v3
	s_nop 1
	v_mov_b32_dpp v88, v3 quad_perm:[1,0,3,2] row_mask:0xf bank_mask:0xf
	s_waitcnt lgkmcnt(0)
	v_add_f32_e32 v3, v3, v88
	s_nop 1
	v_mov_b32_dpp v88, v3 quad_perm:[2,3,0,1] row_mask:0xf bank_mask:0xf
	s_waitcnt lgkmcnt(0)
	v_add_f32_e32 v3, v3, v88
	s_nop 1
	v_mov_b32_dpp v88, v3 row_half_mirror row_mask:0xf bank_mask:0xf
	s_waitcnt lgkmcnt(0)
	v_add_f32_e32 v3, v3, v88
	s_nop 1
	v_mov_b32_dpp v88, v3 row_mirror row_mask:0xf bank_mask:0xf
	s_waitcnt lgkmcnt(0)
	v_add_f32_e32 v3, v3, v88
	v_fmamk_f32 v3, v3, 0x3c800000, v197
	v_cmp_gt_f32_e32 vcc, s92, v3
	v_mul_f32_e32 v88, 0x4b800000, v3
	s_nop 0
	v_cndmask_b32_e32 v3, v3, v88, vcc
	v_rsq_f32_e32 v3, v3
	s_nop 0
	v_mul_f32_e32 v88, 0x45800000, v3
	v_cndmask_b32_e32 v96, v3, v88, vcc
	v_mov_b32_e32 v88, v93
	v_pk_mul_f32 v[88:89], v[96:97], v[88:89] op_sel_hi:[0,1]
	v_pk_mul_f32 v[84:85], v[96:97], v[84:85] op_sel_hi:[0,1]
	v_pk_mul_f32 v[92:93], v[138:139], v[88:89]
	v_pk_mul_f32 v[84:85], v[136:137], v[84:85]
	v_or_b32_e32 v88, 33, v2
	v_cmp_gt_i32_e64 s[0:1], s91, v88
	v_mov_b32_e32 v3, v92
	v_mov_b32_e32 v97, v93
	v_mov_b32_e32 v100, v85
	v_mov_b32_e32 v102, v84
	s_and_saveexec_b64 s[10:11], s[0:1]
	s_cbranch_execz .LBB0_403
	v_lshlrev_b32_e32 v3, 4, v88
	s_movk_i32 s12, 0x2d0
	v_and_or_b32 v3, v3, s12, v168
	v_mov_b32_e32 v143, v1
	v_lshlrev_b32_e32 v102, 2, v3
	v_mov_b32_e32 v103, v1
	v_lshl_add_u64 v[96:97], s[6:7], 0, v[142:143]
	v_lshl_add_u64 v[102:103], s[6:7], 0, v[102:103]
	v_subrev_u32_e32 v211, s100, v96
	ds_read_b32 v100, v211
	v_subrev_u32_e32 v211, s100, v102
	ds_read_b32 v105, v211
	v_add_co_u32_e32 v96, vcc, 0x2000, v96
	s_waitcnt lgkmcnt(0)
	v_pk_mul_f32 v[106:107], v[92:93], v[100:101] op_sel_hi:[1,0]
	v_addc_co_u32_e32 v97, vcc, 0, v97, vcc
	v_subrev_u32_e32 v211, s100, v96
	ds_read_b32 v96, v211
	v_add_co_u32_e32 v102, vcc, 0x2000, v102
	s_nop 1
	v_addc_co_u32_e32 v103, vcc, 0, v103, vcc
	v_subrev_u32_e32 v211, s100, v102
	ds_read_b32 v104, v211
	v_mov_b32_e32 v102, v105
	s_waitcnt lgkmcnt(0)
	v_pk_mul_f32 v[108:109], v[92:93], v[96:97] op_sel:[1,0] op_sel_hi:[0,0]
	v_pk_fma_f32 v[96:97], v[92:93], v[100:101], v[108:109] op_sel_hi:[1,0,1]
	v_sub_f32_e32 v3, v106, v108
	v_mul_f32_e32 v96, v85, v105
	v_pk_fma_f32 v[100:101], v[84:85], v[104:105], v[96:97] op_sel_hi:[1,1,0] neg_lo:[1,0,0] neg_hi:[1,0,0]
	v_mov_b32_e32 v103, v104
	v_mul_f32_e32 v96, v85, v104
	v_pk_fma_f32 v[102:103], v[84:85], v[102:103], v[96:97] op_sel_hi:[1,1,0]

; __device__ __forceinline__ void inproj_tile(const Params& p, char* smem, int l, int mt, int nt) {
;     ...
;           float ss = 0.f;
; #pragma unroll
;           for (int n = 0; n < 4; ++n) ss += acc[m][n][j] * acc[m][n][j];
;           ss += __shfl_xor(ss, 1); ss += __shfl_xor(ss, 2); ss += __shfl_xor(ss, 4); ss += __shfl_xor(ss, 8);
;           float rstd = rsqrtf(ss * (1.f / 64.f) + EPSF);
;           int row = rowbase + m * 16 + fq * 4 + j;
;           float v[4];
; #pragma unroll
;           for (int n = 0; n < 4; ++n) v[n] = acc[m][n][j] * rstd * w4[n];
;           bool lat = row < MLAT;
;           float rv[4] = {v[0], v[1], v[2], v[3]};
;           if (lat) {
;             int t = row & 8191, pr = t >> 6, pc = t & 63;
;             float c0 = rope[pr * 16 + fr], s0 = rope[2048 + pr * 16 + fr];
;             float c1 = rope[pc * 16 + fr], s1 = rope[2048 + pc * 16 + fr];
;             rv[0] = v[0] * c0 - v[1] * s0; rv[1] = v[1] * c0 + v[0] * s0;
;             rv[2] = v[2] * c1 - v[3] * s1; rv[3] = v[3] * c1 + v[2] * s1;
.LBB0_411:
	s_or_b64 exec, exec, s[0:1]
	v_mov_b32_e32 v84, v90
	v_mov_b32_e32 v85, v94
	v_pk_mul_f32 v[84:85], v[84:85], v[84:85]
	v_mov_b32_e32 v88, v98
	v_mov_b32_e32 v89, v86
	v_pk_mul_f32 v[92:93], v[88:89], v[88:89]
	v_add_f32_e32 v3, v84, v85
	v_add_f32_e32 v3, v93, v3
	v_add_f32_e32 v3, v92, v3
	s_nop 1
	v_mov_b32_dpp v84, v3 quad_perm:[1,0,3,2] row_mask:0xf bank_mask:0xf
	v_mov_b32_e32 v92, v94
	v_mov_b32_e32 v93, v90
	s_waitcnt lgkmcnt(0)
	v_add_f32_e32 v3, v3, v84
	s_nop 1
	v_mov_b32_dpp v84, v3 quad_perm:[2,3,0,1] row_mask:0xf bank_mask:0xf
	s_waitcnt lgkmcnt(0)
	v_add_f32_e32 v3, v3, v84
	s_nop 1
	v_mov_b32_dpp v84, v3 row_half_mirror row_mask:0xf bank_mask:0xf
	s_waitcnt lgkmcnt(0)
	v_add_f32_e32 v3, v3, v84
	s_nop 1
	v_mov_b32_dpp v84, v3 row_mirror row_mask:0xf bank_mask:0xf
	s_waitcnt lgkmcnt(0)
	v_add_f32_e32 v3, v3, v84
	v_fmamk_f32 v3, v3, 0x3c800000, v197
	v_cmp_gt_f32_e32 vcc, s92, v3
	v_mul_f32_e32 v84, 0x4b800000, v3
	s_nop 0
	v_cndmask_b32_e32 v3, v3, v84, vcc
	v_rsq_f32_e32 v3, v3
	s_nop 0
	v_mul_f32_e32 v84, 0x45800000, v3
	v_cndmask_b32_e32 v84, v3, v84, vcc
	v_pk_mul_f32 v[92:93], v[84:85], v[92:93] op_sel_hi:[0,1]
	v_pk_mul_f32 v[84:85], v[84:85], v[88:89] op_sel_hi:[0,1]
	v_pk_mul_f32 v[92:93], v[138:139], v[92:93]
	v_pk_mul_f32 v[84:85], v[136:137], v[84:85]
	v_or_b32_e32 v88, 34, v2
	v_cmp_gt_i32_e64 s[0:1], s91, v88
	v_mov_b32_e32 v3, v92
	v_mov_b32_e32 v97, v93
	v_mov_b32_e32 v100, v85
	v_mov_b32_e32 v102, v84
	s_and_saveexec_b64 s[10:11], s[0:1]
	s_cbranch_execz .LBB0_413
	v_mov_b32_e32 v143, v1
	v_lshl_add_u64 v[96:97], s[6:7], 0, v[142:143]
	v_subrev_u32_e32 v211, s100, v96
	ds_read_b32 v86, v211
	v_add_co_u32_e32 v96, vcc, 0x2000, v96
	v_lshlrev_b32_e32 v3, 4, v88
	s_movk_i32 s12, 0x2e0
	v_addc_co_u32_e32 v97, vcc, 0, v97, vcc
	v_and_or_b32 v3, v3, s12, v168
	v_subrev_u32_e32 v211, s100, v96
	ds_read_b32 v90, v211
	v_lshlrev_b32_e32 v96, 2, v3
	v_mov_b32_e32 v97, v1
	v_lshl_add_u64 v[96:97], s[6:7], 0, v[96:97]
	v_subrev_u32_e32 v211, s100, v96
	ds_read_b32 v103, v211
	v_add_co_u32_e32 v96, vcc, 0x2000, v96
	s_waitcnt lgkmcnt(0)
	v_pk_mul_f32 v[104:105], v[92:93], v[86:87] op_sel_hi:[1,0]
	v_addc_co_u32_e32 v97, vcc, 0, v97, vcc
	v_subrev_u32_e32 v211, s100, v96
	ds_read_b32 v102, v211
	v_pk_mul_f32 v[106:107], v[92:93], v[90:91] op_sel:[1,0] op_sel_hi:[0,0]
	v_pk_fma_f32 v[96:97], v[92:93], v[86:87], v[106:107] op_sel_hi:[1,0,1]
	v_sub_f32_e32 v3, v104, v106
	v_mul_f32_e32 v86, v85, v103
	v_mov_b32_e32 v108, v103
	s_waitcnt lgkmcnt(0)
	v_pk_fma_f32 v[100:101], v[84:85], v[102:103], v[86:87] op_sel_hi:[1,1,0] neg_lo:[1,0,0] neg_hi:[1,0,0]
	v_mov_b32_e32 v109, v102
	v_mul_f32_e32 v86, v85, v102
	v_pk_fma_f32 v[102:103], v[84:85], v[108:109], v[86:87] op_sel_hi:[1,1,0]

; __device__ __forceinline__ void inproj_tile(const Params& p, char* smem, int l, int mt, int nt) {
;     ...
;           float ss = 0.f;
; #pragma unroll
;           for (int n = 0; n < 4; ++n) ss += acc[m][n][j] * acc[m][n][j];
;           ss += __shfl_xor(ss, 1); ss += __shfl_xor(ss, 2); ss += __shfl_xor(ss, 4); ss += __shfl_xor(ss, 8);
;           float rstd = rsqrtf(ss * (1.f / 64.f) + EPSF);
;           int row = rowbase + m * 16 + fq * 4 + j;
;           float v[4];
; #pragma unroll
;           for (int n = 0; n < 4; ++n) v[n] = acc[m][n][j] * rstd * w4[n];
;           bool lat = row < MLAT;
;           float rv[4] = {v[0], v[1], v[2], v[3]};
;           if (lat) {
;             int t = row & 8191, pr = t >> 6, pc = t & 63;
;             float c0 = rope[pr * 16 + fr], s0 = rope[2048 + pr * 16 + fr];
;             float c1 = rope[pc * 16 + fr], s1 = rope[2048 + pc * 16 + fr];
;             rv[0] = v[0] * c0 - v[1] * s0; rv[1] = v[1] * c0 + v[0] * s0;
;             rv[2] = v[2] * c1 - v[3] * s1; rv[3] = v[3] * c1 + v[2] * s1;
.LBB0_421:
	s_or_b64 exec, exec, s[0:1]
	v_mov_b32_e32 v94, v91
	v_pk_mul_f32 v[84:85], v[94:95], v[94:95]
	v_mov_b32_e32 v86, v99
	v_pk_mul_f32 v[88:89], v[86:87], v[86:87]
	v_add_f32_e32 v3, v84, v85
	v_add_f32_e32 v3, v89, v3
	v_add_f32_e32 v3, v88, v3
	s_nop 1
	v_mov_b32_dpp v84, v3 quad_perm:[1,0,3,2] row_mask:0xf bank_mask:0xf
	v_mov_b32_e32 v90, v95
	s_waitcnt lgkmcnt(0)
	v_add_f32_e32 v3, v3, v84
	s_nop 1
	v_mov_b32_dpp v84, v3 quad_perm:[2,3,0,1] row_mask:0xf bank_mask:0xf
	s_waitcnt lgkmcnt(0)
	v_add_f32_e32 v3, v3, v84
	s_nop 1
	v_mov_b32_dpp v84, v3 row_half_mirror row_mask:0xf bank_mask:0xf
	s_waitcnt lgkmcnt(0)
	v_add_f32_e32 v3, v3, v84
	s_nop 1
	v_mov_b32_dpp v84, v3 row_mirror row_mask:0xf bank_mask:0xf
	s_waitcnt lgkmcnt(0)
	v_add_f32_e32 v3, v3, v84
	v_fmamk_f32 v3, v3, 0x3c800000, v197
	v_cmp_gt_f32_e32 vcc, s92, v3
	v_mul_f32_e32 v84, 0x4b800000, v3
	s_nop 0
	v_cndmask_b32_e32 v3, v3, v84, vcc
	v_rsq_f32_e32 v3, v3
	s_nop 0
	v_mul_f32_e32 v84, 0x45800000, v3
	v_cndmask_b32_e32 v84, v3, v84, vcc
	v_pk_mul_f32 v[88:89], v[84:85], v[90:91] op_sel_hi:[0,1]
	v_pk_mul_f32 v[84:85], v[84:85], v[86:87] op_sel_hi:[0,1]
	v_pk_mul_f32 v[88:89], v[138:139], v[88:89]
	v_pk_mul_f32 v[84:85], v[136:137], v[84:85]
	v_or_b32_e32 v86, 35, v2
	v_cmp_gt_i32_e64 s[0:1], s91, v86
	v_mov_b32_e32 v3, v88
	v_mov_b32_e32 v91, v89
	v_mov_b32_e32 v92, v85
	v_mov_b32_e32 v94, v84
	s_and_saveexec_b64 s[10:11], s[0:1]
	s_cbranch_execz .LBB0_423
	v_lshlrev_b32_e32 v3, 4, v86
	s_movk_i32 s12, 0x2f0
	v_and_or_b32 v3, v3, s12, v168
	v_mov_b32_e32 v143, v1
	v_lshlrev_b32_e32 v94, 2, v3
	v_mov_b32_e32 v95, v1
	v_lshl_add_u64 v[90:91], s[6:7], 0, v[142:143]
	v_lshl_add_u64 v[94:95], s[6:7], 0, v[94:95]
	v_subrev_u32_e32 v211, s100, v90
	ds_read_b32 v92, v211
	v_subrev_u32_e32 v211, s100, v94
	ds_read_b32 v97, v211
	v_add_co_u32_e32 v90, vcc, 0x2000, v90
	s_waitcnt lgkmcnt(0)
	v_pk_mul_f32 v[98:99], v[88:89], v[92:93] op_sel_hi:[1,0]
	v_addc_co_u32_e32 v91, vcc, 0, v91, vcc
	v_subrev_u32_e32 v211, s100, v90
	ds_read_b32 v90, v211
	v_add_co_u32_e32 v94, vcc, 0x2000, v94
	s_nop 1
	v_addc_co_u32_e32 v95, vcc, 0, v95, vcc
	v_subrev_u32_e32 v211, s100, v94
	ds_read_b32 v96, v211
	v_mov_b32_e32 v94, v97
	s_waitcnt lgkmcnt(0)
	v_pk_mul_f32 v[100:101], v[88:89], v[90:91] op_sel:[1,0] op_sel_hi:[0,0]
	v_pk_fma_f32 v[90:91], v[88:89], v[92:93], v[100:101] op_sel_hi:[1,0,1]
	v_sub_f32_e32 v3, v98, v100
	v_mul_f32_e32 v90, v85, v97
	v_pk_fma_f32 v[92:93], v[84:85], v[96:97], v[90:91] op_sel_hi:[1,1,0] neg_lo:[1,0,0] neg_hi:[1,0,0]
	v_mov_b32_e32 v95, v96
	v_mul_f32_e32 v90, v85, v96
	v_pk_fma_f32 v[94:95], v[84:85], v[94:95], v[90:91] op_sel_hi:[1,1,0]

; __device__ __forceinline__ void inproj_tile(const Params& p, char* smem, int l, int mt, int nt) {
;     ...
;           float ss = 0.f;
; #pragma unroll
;           for (int n = 0; n < 4; ++n) ss += acc[m][n][j] * acc[m][n][j];
;           ss += __shfl_xor(ss, 1); ss += __shfl_xor(ss, 2); ss += __shfl_xor(ss, 4); ss += __shfl_xor(ss, 8);
;           float rstd = rsqrtf(ss * (1.f / 64.f) + EPSF);
;           int row = rowbase + m * 16 + fq * 4 + j;
;           float v[4];
; #pragma unroll
;           for (int n = 0; n < 4; ++n) v[n] = acc[m][n][j] * rstd * w4[n];
;           bool lat = row < MLAT;
;           float rv[4] = {v[0], v[1], v[2], v[3]};
;           if (lat) {
;             int t = row & 8191, pr = t >> 6, pc = t & 63;
;             float c0 = rope[pr * 16 + fr], s0 = rope[2048 + pr * 16 + fr];
;             float c1 = rope[pc * 16 + fr], s1 = rope[2048 + pc * 16 + fr];
;             rv[0] = v[0] * c0 - v[1] * s0; rv[1] = v[1] * c0 + v[0] * s0;
;             rv[2] = v[2] * c1 - v[3] * s1; rv[3] = v[3] * c1 + v[2] * s1;
.LBB0_431:
	s_or_b64 exec, exec, s[0:1]
	v_mov_b32_e32 v86, v72
	v_mov_b32_e32 v87, v76
	v_pk_mul_f32 v[86:87], v[86:87], v[86:87]
	v_mov_b32_e32 v90, v80
	v_mov_b32_e32 v91, v68
	v_pk_mul_f32 v[88:89], v[90:91], v[90:91]
	v_add_f32_e32 v3, v86, v87
	v_add_f32_e32 v3, v89, v3
	v_add_f32_e32 v3, v88, v3
	s_nop 1
	v_mov_b32_dpp v68, v3 quad_perm:[1,0,3,2] row_mask:0xf bank_mask:0xf
	v_mov_b32_e32 v86, v76
	v_mov_b32_e32 v87, v72
	v_or_b32_e32 v84, 48, v2
	v_cmp_gt_i32_e64 s[0:1], s91, v84
	s_waitcnt lgkmcnt(0)
	v_add_f32_e32 v3, v3, v68
	s_nop 1
	v_mov_b32_dpp v68, v3 quad_perm:[2,3,0,1] row_mask:0xf bank_mask:0xf
	s_waitcnt lgkmcnt(0)
	v_add_f32_e32 v3, v3, v68
	s_nop 1
	v_mov_b32_dpp v68, v3 row_half_mirror row_mask:0xf bank_mask:0xf
	s_waitcnt lgkmcnt(0)
	v_add_f32_e32 v3, v3, v68
	s_nop 1
	v_mov_b32_dpp v68, v3 row_mirror row_mask:0xf bank_mask:0xf
	s_waitcnt lgkmcnt(0)
	v_add_f32_e32 v3, v3, v68
	v_fmamk_f32 v3, v3, 0x3c800000, v197
	v_cmp_gt_f32_e32 vcc, s92, v3
	v_mul_f32_e32 v68, 0x4b800000, v3
	s_nop 0
	v_cndmask_b32_e32 v3, v3, v68, vcc
	v_rsq_f32_e32 v3, v3
	s_nop 0
	v_mul_f32_e32 v68, 0x45800000, v3
	v_cndmask_b32_e32 v68, v3, v68, vcc
	v_pk_mul_f32 v[86:87], v[68:69], v[86:87] op_sel_hi:[0,1]
	v_pk_mul_f32 v[88:89], v[138:139], v[86:87]
	v_pk_mul_f32 v[86:87], v[68:69], v[90:91] op_sel_hi:[0,1]
	v_pk_mul_f32 v[86:87], v[136:137], v[86:87]
	v_mov_b32_e32 v3, v88
	v_mov_b32_e32 v91, v89
	v_mov_b32_e32 v92, v87
	v_mov_b32_e32 v94, v86
	s_and_saveexec_b64 s[10:11], s[0:1]
	s_cbranch_execz .LBB0_433
	v_mov_b32_e32 v143, v1
	v_lshl_add_u64 v[90:91], s[6:7], 0, v[142:143]
	v_subrev_u32_e32 v211, s100, v90
	ds_read_b32 v68, v211
	v_add_co_u32_e32 v90, vcc, 0x2000, v90
	v_lshlrev_b32_e32 v3, 4, v84
	s_movk_i32 s12, 0x3c0
	v_addc_co_u32_e32 v91, vcc, 0, v91, vcc
	v_and_or_b32 v3, v3, s12, v168
	v_subrev_u32_e32 v211, s100, v90
	ds_read_b32 v72, v211
	v_lshlrev_b32_e32 v90, 2, v3
	v_mov_b32_e32 v91, v1
	v_lshl_add_u64 v[90:91], s[6:7], 0, v[90:91]
	v_subrev_u32_e32 v211, s100, v90
	ds_read_b32 v95, v211
	v_add_co_u32_e32 v90, vcc, 0x2000, v90
	s_waitcnt lgkmcnt(0)
	v_pk_mul_f32 v[96:97], v[88:89], v[68:69] op_sel_hi:[1,0]
	v_addc_co_u32_e32 v91, vcc, 0, v91, vcc
	v_subrev_u32_e32 v211, s100, v90
	ds_read_b32 v94, v211
	v_pk_mul_f32 v[98:99], v[88:89], v[72:73] op_sel:[1,0] op_sel_hi:[0,0]
	v_pk_fma_f32 v[90:91], v[88:89], v[68:69], v[98:99] op_sel_hi:[1,0,1]
	v_sub_f32_e32 v3, v96, v98
	v_mul_f32_e32 v68, v87, v95
	v_mov_b32_e32 v100, v95
	s_waitcnt lgkmcnt(0)
	v_pk_fma_f32 v[92:93], v[86:87], v[94:95], v[68:69] op_sel_hi:[1,1,0] neg_lo:[1,0,0] neg_hi:[1,0,0]
	v_mov_b32_e32 v101, v94
	v_mul_f32_e32 v68, v87, v94
	v_pk_fma_f32 v[94:95], v[86:87], v[100:101], v[68:69] op_sel_hi:[1,1,0]

; __device__ __forceinline__ void inproj_tile(const Params& p, char* smem, int l, int mt, int nt) {
;     ...
;           float ss = 0.f;
; #pragma unroll
;           for (int n = 0; n < 4; ++n) ss += acc[m][n][j] * acc[m][n][j];
;           ss += __shfl_xor(ss, 1); ss += __shfl_xor(ss, 2); ss += __shfl_xor(ss, 4); ss += __shfl_xor(ss, 8);
;           float rstd = rsqrtf(ss * (1.f / 64.f) + EPSF);
;           int row = rowbase + m * 16 + fq * 4 + j;
;           float v[4];
; #pragma unroll
;           for (int n = 0; n < 4; ++n) v[n] = acc[m][n][j] * rstd * w4[n];
;           bool lat = row < MLAT;
;           float rv[4] = {v[0], v[1], v[2], v[3]};
;           if (lat) {
;             int t = row & 8191, pr = t >> 6, pc = t & 63;
;             float c0 = rope[pr * 16 + fr], s0 = rope[2048 + pr * 16 + fr];
;             float c1 = rope[pc * 16 + fr], s1 = rope[2048 + pc * 16 + fr];
;             rv[0] = v[0] * c0 - v[1] * s0; rv[1] = v[1] * c0 + v[0] * s0;
;             rv[2] = v[2] * c1 - v[3] * s1; rv[3] = v[3] * c1 + v[2] * s1;
.LBB0_441:
	s_or_b64 exec, exec, s[0:1]
	v_mov_b32_e32 v76, v73
	v_pk_mul_f32 v[84:85], v[76:77], v[76:77]
	v_mov_b32_e32 v68, v81
	v_pk_mul_f32 v[80:81], v[68:69], v[68:69]
	v_add_f32_e32 v3, v84, v85
	v_add_f32_e32 v3, v81, v3
	v_add_f32_e32 v3, v80, v3
	s_nop 1
	v_mov_b32_dpp v72, v3 quad_perm:[1,0,3,2] row_mask:0xf bank_mask:0xf
	s_waitcnt lgkmcnt(0)
	v_add_f32_e32 v3, v3, v72
	s_nop 1
	v_mov_b32_dpp v72, v3 quad_perm:[2,3,0,1] row_mask:0xf bank_mask:0xf
	s_waitcnt lgkmcnt(0)
	v_add_f32_e32 v3, v3, v72
	s_nop 1
	v_mov_b32_dpp v72, v3 row_half_mirror row_mask:0xf bank_mask:0xf
	s_waitcnt lgkmcnt(0)
	v_add_f32_e32 v3, v3, v72
	s_nop 1
	v_mov_b32_dpp v72, v3 row_mirror row_mask:0xf bank_mask:0xf
	s_waitcnt lgkmcnt(0)
	v_add_f32_e32 v3, v3, v72
	v_fmamk_f32 v3, v3, 0x3c800000, v197
	v_cmp_gt_f32_e32 vcc, s92, v3
	v_mul_f32_e32 v72, 0x4b800000, v3
	s_nop 0
	v_cndmask_b32_e32 v3, v3, v72, vcc
	v_rsq_f32_e32 v3, v3
	s_nop 0
	v_mul_f32_e32 v72, 0x45800000, v3
	v_cndmask_b32_e32 v80, v3, v72, vcc
	v_mov_b32_e32 v72, v77
	v_pk_mul_f32 v[72:73], v[80:81], v[72:73] op_sel_hi:[0,1]
	v_pk_mul_f32 v[68:69], v[80:81], v[68:69] op_sel_hi:[0,1]
	v_pk_mul_f32 v[76:77], v[138:139], v[72:73]
	v_pk_mul_f32 v[68:69], v[136:137], v[68:69]
	v_or_b32_e32 v72, 49, v2
	v_cmp_gt_i32_e64 s[0:1], s91, v72
	v_mov_b32_e32 v3, v76
	v_mov_b32_e32 v81, v77
	v_mov_b32_e32 v84, v69
	v_mov_b32_e32 v86, v68
	s_and_saveexec_b64 s[10:11], s[0:1]
	s_cbranch_execz .LBB0_443
	v_lshlrev_b32_e32 v3, 4, v72
	s_movk_i32 s12, 0x3d0
	v_and_or_b32 v3, v3, s12, v168
	v_mov_b32_e32 v143, v1
	v_lshlrev_b32_e32 v86, 2, v3
	v_mov_b32_e32 v87, v1
	v_lshl_add_u64 v[80:81], s[6:7], 0, v[142:143]
	v_lshl_add_u64 v[86:87], s[6:7], 0, v[86:87]
	v_subrev_u32_e32 v211, s100, v80
	ds_read_b32 v84, v211
	v_subrev_u32_e32 v211, s100, v86
	ds_read_b32 v89, v211
	v_add_co_u32_e32 v80, vcc, 0x2000, v80
	s_waitcnt lgkmcnt(0)
	v_pk_mul_f32 v[90:91], v[76:77], v[84:85] op_sel_hi:[1,0]
	v_addc_co_u32_e32 v81, vcc, 0, v81, vcc
	v_subrev_u32_e32 v211, s100, v80
	ds_read_b32 v80, v211
	v_add_co_u32_e32 v86, vcc, 0x2000, v86
	s_nop 1
	v_addc_co_u32_e32 v87, vcc, 0, v87, vcc
	v_subrev_u32_e32 v211, s100, v86
	ds_read_b32 v88, v211
	v_mov_b32_e32 v86, v89
	s_waitcnt lgkmcnt(0)
	v_pk_mul_f32 v[92:93], v[76:77], v[80:81] op_sel:[1,0] op_sel_hi:[0,0]
	v_pk_fma_f32 v[80:81], v[76:77], v[84:85], v[92:93] op_sel_hi:[1,0,1]
	v_sub_f32_e32 v3, v90, v92
	v_mul_f32_e32 v80, v69, v89
	v_pk_fma_f32 v[84:85], v[68:69], v[88:89], v[80:81] op_sel_hi:[1,1,0] neg_lo:[1,0,0] neg_hi:[1,0,0]
	v_mov_b32_e32 v87, v88
	v_mul_f32_e32 v80, v69, v88
	v_pk_fma_f32 v[86:87], v[68:69], v[86:87], v[80:81] op_sel_hi:[1,1,0]

; __device__ __forceinline__ void inproj_tile(const Params& p, char* smem, int l, int mt, int nt) {
;     ...
;           float ss = 0.f;
; #pragma unroll
;           for (int n = 0; n < 4; ++n) ss += acc[m][n][j] * acc[m][n][j];
;           ss += __shfl_xor(ss, 1); ss += __shfl_xor(ss, 2); ss += __shfl_xor(ss, 4); ss += __shfl_xor(ss, 8);
;           float rstd = rsqrtf(ss * (1.f / 64.f) + EPSF);
;           int row = rowbase + m * 16 + fq * 4 + j;
;           float v[4];
; #pragma unroll
;           for (int n = 0; n < 4; ++n) v[n] = acc[m][n][j] * rstd * w4[n];
;           bool lat = row < MLAT;
;           float rv[4] = {v[0], v[1], v[2], v[3]};
;           if (lat) {
;             int t = row & 8191, pr = t >> 6, pc = t & 63;
;             float c0 = rope[pr * 16 + fr], s0 = rope[2048 + pr * 16 + fr];
;             float c1 = rope[pc * 16 + fr], s1 = rope[2048 + pc * 16 + fr];
;             rv[0] = v[0] * c0 - v[1] * s0; rv[1] = v[1] * c0 + v[0] * s0;
;             rv[2] = v[2] * c1 - v[3] * s1; rv[3] = v[3] * c1 + v[2] * s1;
.LBB0_451:
	s_or_b64 exec, exec, s[0:1]
	v_mov_b32_e32 v68, v74
	v_mov_b32_e32 v69, v78
	v_pk_mul_f32 v[68:69], v[68:69], v[68:69]
	v_mov_b32_e32 v72, v82
	v_mov_b32_e32 v73, v70
	v_pk_mul_f32 v[76:77], v[72:73], v[72:73]
	v_add_f32_e32 v3, v68, v69
	v_add_f32_e32 v3, v77, v3
	v_add_f32_e32 v3, v76, v3
	s_nop 1
	v_mov_b32_dpp v68, v3 quad_perm:[1,0,3,2] row_mask:0xf bank_mask:0xf
	v_mov_b32_e32 v76, v78
	v_mov_b32_e32 v77, v74
	s_waitcnt lgkmcnt(0)
	v_add_f32_e32 v3, v3, v68
	s_nop 1
	v_mov_b32_dpp v68, v3 quad_perm:[2,3,0,1] row_mask:0xf bank_mask:0xf
	s_waitcnt lgkmcnt(0)
	v_add_f32_e32 v3, v3, v68
	s_nop 1
	v_mov_b32_dpp v68, v3 row_half_mirror row_mask:0xf bank_mask:0xf
	s_waitcnt lgkmcnt(0)
	v_add_f32_e32 v3, v3, v68
	s_nop 1
	v_mov_b32_dpp v68, v3 row_mirror row_mask:0xf bank_mask:0xf
	s_waitcnt lgkmcnt(0)
	v_add_f32_e32 v3, v3, v68
	v_fmamk_f32 v3, v3, 0x3c800000, v197
	v_cmp_gt_f32_e32 vcc, s92, v3
	v_mul_f32_e32 v68, 0x4b800000, v3
	s_nop 0
	v_cndmask_b32_e32 v3, v3, v68, vcc
	v_rsq_f32_e32 v3, v3
	s_nop 0
	v_mul_f32_e32 v68, 0x45800000, v3
	v_cndmask_b32_e32 v68, v3, v68, vcc
	v_pk_mul_f32 v[76:77], v[68:69], v[76:77] op_sel_hi:[0,1]
	v_pk_mul_f32 v[68:69], v[68:69], v[72:73] op_sel_hi:[0,1]
	v_pk_mul_f32 v[76:77], v[138:139], v[76:77]
	v_pk_mul_f32 v[68:69], v[136:137], v[68:69]
	v_or_b32_e32 v72, 50, v2
	v_cmp_gt_i32_e64 s[0:1], s91, v72
	v_mov_b32_e32 v3, v76
	v_mov_b32_e32 v81, v77
	v_mov_b32_e32 v84, v69
	v_mov_b32_e32 v86, v68
	s_and_saveexec_b64 s[10:11], s[0:1]
	s_cbranch_execz .LBB0_453
	v_mov_b32_e32 v143, v1
	v_lshl_add_u64 v[80:81], s[6:7], 0, v[142:143]
	v_subrev_u32_e32 v211, s100, v80
	ds_read_b32 v70, v211
	v_add_co_u32_e32 v80, vcc, 0x2000, v80
	v_lshlrev_b32_e32 v3, 4, v72
	s_movk_i32 s12, 0x3e0
	v_addc_co_u32_e32 v81, vcc, 0, v81, vcc
	v_and_or_b32 v3, v3, s12, v168
	v_subrev_u32_e32 v211, s100, v80
	ds_read_b32 v74, v211
	v_lshlrev_b32_e32 v80, 2, v3
	v_mov_b32_e32 v81, v1
	v_lshl_add_u64 v[80:81], s[6:7], 0, v[80:81]
	v_subrev_u32_e32 v211, s100, v80
	ds_read_b32 v87, v211
	v_add_co_u32_e32 v80, vcc, 0x2000, v80
	s_waitcnt lgkmcnt(0)
	v_pk_mul_f32 v[88:89], v[76:77], v[70:71] op_sel_hi:[1,0]
	v_addc_co_u32_e32 v81, vcc, 0, v81, vcc
	v_subrev_u32_e32 v211, s100, v80
	ds_read_b32 v86, v211
	v_pk_mul_f32 v[90:91], v[76:77], v[74:75] op_sel:[1,0] op_sel_hi:[0,0]
	v_pk_fma_f32 v[80:81], v[76:77], v[70:71], v[90:91] op_sel_hi:[1,0,1]
	v_sub_f32_e32 v3, v88, v90
	v_mul_f32_e32 v70, v69, v87
	v_mov_b32_e32 v92, v87
	s_waitcnt lgkmcnt(0)
	v_pk_fma_f32 v[84:85], v[68:69], v[86:87], v[70:71] op_sel_hi:[1,1,0] neg_lo:[1,0,0] neg_hi:[1,0,0]
	v_mov_b32_e32 v93, v86
	v_mul_f32_e32 v70, v69, v86
	v_pk_fma_f32 v[86:87], v[68:69], v[92:93], v[70:71] op_sel_hi:[1,1,0]

; __device__ __forceinline__ void inproj_tile(const Params& p, char* smem, int l, int mt, int nt) {
;     ...
;           float ss = 0.f;
; #pragma unroll
;           for (int n = 0; n < 4; ++n) ss += acc[m][n][j] * acc[m][n][j];
;           ss += __shfl_xor(ss, 1); ss += __shfl_xor(ss, 2); ss += __shfl_xor(ss, 4); ss += __shfl_xor(ss, 8);
;           float rstd = rsqrtf(ss * (1.f / 64.f) + EPSF);
;           int row = rowbase + m * 16 + fq * 4 + j;
;           float v[4];
; #pragma unroll
;           for (int n = 0; n < 4; ++n) v[n] = acc[m][n][j] * rstd * w4[n];
;           bool lat = row < MLAT;
;           float rv[4] = {v[0], v[1], v[2], v[3]};
;           if (lat) {
;             int t = row & 8191, pr = t >> 6, pc = t & 63;
;             float c0 = rope[pr * 16 + fr], s0 = rope[2048 + pr * 16 + fr];
;             float c1 = rope[pc * 16 + fr], s1 = rope[2048 + pc * 16 + fr];
;             rv[0] = v[0] * c0 - v[1] * s0; rv[1] = v[1] * c0 + v[0] * s0;
;             rv[2] = v[2] * c1 - v[3] * s1; rv[3] = v[3] * c1 + v[2] * s1;
.LBB0_461:
	s_or_b64 exec, exec, s[0:1]
	v_mov_b32_e32 v78, v75
	v_pk_mul_f32 v[68:69], v[78:79], v[78:79]
	v_mov_b32_e32 v70, v83
	v_pk_mul_f32 v[72:73], v[70:71], v[70:71]
	v_add_f32_e32 v3, v68, v69
	v_add_f32_e32 v3, v73, v3
	v_add_f32_e32 v3, v72, v3
	s_nop 1
	v_mov_b32_dpp v68, v3 quad_perm:[1,0,3,2] row_mask:0xf bank_mask:0xf
	v_mov_b32_e32 v74, v79
	s_waitcnt lgkmcnt(0)
	v_add_f32_e32 v3, v3, v68
	s_nop 1
	v_mov_b32_dpp v68, v3 quad_perm:[2,3,0,1] row_mask:0xf bank_mask:0xf
	s_waitcnt lgkmcnt(0)
	v_add_f32_e32 v3, v3, v68
	s_nop 1
	v_mov_b32_dpp v68, v3 row_half_mirror row_mask:0xf bank_mask:0xf
	s_waitcnt lgkmcnt(0)
	v_add_f32_e32 v3, v3, v68
	s_nop 1
	v_mov_b32_dpp v68, v3 row_mirror row_mask:0xf bank_mask:0xf
	s_waitcnt lgkmcnt(0)
	v_add_f32_e32 v3, v3, v68
	v_fmamk_f32 v3, v3, 0x3c800000, v197
	v_cmp_gt_f32_e32 vcc, s92, v3
	v_mul_f32_e32 v68, 0x4b800000, v3
	s_nop 0
	v_cndmask_b32_e32 v3, v3, v68, vcc
	v_rsq_f32_e32 v3, v3
	s_nop 0
	v_mul_f32_e32 v68, 0x45800000, v3
	v_cndmask_b32_e32 v68, v3, v68, vcc
	v_pk_mul_f32 v[72:73], v[68:69], v[74:75] op_sel_hi:[0,1]
	v_pk_mul_f32 v[68:69], v[68:69], v[70:71] op_sel_hi:[0,1]
	v_pk_mul_f32 v[72:73], v[138:139], v[72:73]
	v_pk_mul_f32 v[68:69], v[136:137], v[68:69]
	v_or_b32_e32 v70, 51, v2
	v_cmp_gt_i32_e64 s[0:1], s91, v70
	v_mov_b32_e32 v3, v72
	v_mov_b32_e32 v75, v73
	v_mov_b32_e32 v76, v69
	v_mov_b32_e32 v78, v68
	s_and_saveexec_b64 s[10:11], s[0:1]
	s_cbranch_execz .LBB0_463
	v_lshlrev_b32_e32 v3, 4, v70
	s_movk_i32 s12, 0x3f0
	v_and_or_b32 v3, v3, s12, v168
	v_mov_b32_e32 v143, v1
	v_lshlrev_b32_e32 v78, 2, v3
	v_mov_b32_e32 v79, v1
	v_lshl_add_u64 v[74:75], s[6:7], 0, v[142:143]
	v_lshl_add_u64 v[78:79], s[6:7], 0, v[78:79]
	v_subrev_u32_e32 v211, s100, v74
	ds_read_b32 v76, v211
	v_subrev_u32_e32 v211, s100, v78
	ds_read_b32 v81, v211
	v_add_co_u32_e32 v74, vcc, 0x2000, v74
	s_waitcnt lgkmcnt(0)
	v_pk_mul_f32 v[82:83], v[72:73], v[76:77] op_sel_hi:[1,0]
	v_addc_co_u32_e32 v75, vcc, 0, v75, vcc
	v_subrev_u32_e32 v211, s100, v74
	ds_read_b32 v74, v211
	v_add_co_u32_e32 v78, vcc, 0x2000, v78
	s_nop 1
	v_addc_co_u32_e32 v79, vcc, 0, v79, vcc
	v_subrev_u32_e32 v211, s100, v78
	ds_read_b32 v80, v211
	v_mov_b32_e32 v78, v81
	s_waitcnt lgkmcnt(0)
	v_pk_mul_f32 v[84:85], v[72:73], v[74:75] op_sel:[1,0] op_sel_hi:[0,0]
	v_pk_fma_f32 v[74:75], v[72:73], v[76:77], v[84:85] op_sel_hi:[1,0,1]
	v_sub_f32_e32 v3, v82, v84
	v_mul_f32_e32 v74, v69, v81
	v_pk_fma_f32 v[76:77], v[68:69], v[80:81], v[74:75] op_sel_hi:[1,1,0] neg_lo:[1,0,0] neg_hi:[1,0,0]
	v_mov_b32_e32 v79, v80
	v_mul_f32_e32 v74, v69, v80
	v_pk_fma_f32 v[78:79], v[68:69], v[78:79], v[74:75] op_sel_hi:[1,1,0]

; __device__ __forceinline__ void inproj_tile(const Params& p, char* smem, int l, int mt, int nt) {
;     ...
;           float ss = 0.f;
; #pragma unroll
;           for (int n = 0; n < 4; ++n) ss += acc[m][n][j] * acc[m][n][j];
;           ss += __shfl_xor(ss, 1); ss += __shfl_xor(ss, 2); ss += __shfl_xor(ss, 4); ss += __shfl_xor(ss, 8);
;           float rstd = rsqrtf(ss * (1.f / 64.f) + EPSF);
;           int row = rowbase + m * 16 + fq * 4 + j;
;           float v[4];
; #pragma unroll
;           for (int n = 0; n < 4; ++n) v[n] = acc[m][n][j] * rstd * w4[n];
;           bool lat = row < MLAT;
;           float rv[4] = {v[0], v[1], v[2], v[3]};
;           if (lat) {
;             int t = row & 8191, pr = t >> 6, pc = t & 63;
;             float c0 = rope[pr * 16 + fr], s0 = rope[2048 + pr * 16 + fr];
;             float c1 = rope[pc * 16 + fr], s1 = rope[2048 + pc * 16 + fr];
;             rv[0] = v[0] * c0 - v[1] * s0; rv[1] = v[1] * c0 + v[0] * s0;
;             rv[2] = v[2] * c1 - v[3] * s1; rv[3] = v[3] * c1 + v[2] * s1;
.LBB0_471:
	s_or_b64 exec, exec, s[0:1]
	v_mov_b32_e32 v68, v56
	v_mov_b32_e32 v69, v60
	v_pk_mul_f32 v[68:69], v[68:69], v[68:69]
	v_mov_b32_e32 v72, v64
	v_mov_b32_e32 v73, v52
	v_pk_mul_f32 v[74:75], v[72:73], v[72:73]
	v_add_f32_e32 v52, v68, v69
	v_add_f32_e32 v52, v75, v52
	v_add_f32_e32 v52, v74, v52
	s_nop 1
	v_mov_b32_dpp v64, v52 quad_perm:[1,0,3,2] row_mask:0xf bank_mask:0xf
	v_mov_b32_e32 v68, v60
	v_mov_b32_e32 v69, v56
	v_or_b32_e32 v70, 64, v2
	v_lshrrev_b32_e32 v3, 2, v70
	s_waitcnt lgkmcnt(0)
	v_add_f32_e32 v52, v52, v64
	s_nop 1
	v_mov_b32_dpp v64, v52 quad_perm:[2,3,0,1] row_mask:0xf bank_mask:0xf
	s_movk_i32 s0, 0x7f0
	v_and_or_b32 v3, v3, s0, v168
	v_cmp_gt_i32_e64 s[0:1], s91, v70
	s_waitcnt lgkmcnt(0)
	v_add_f32_e32 v52, v52, v64
	s_nop 1
	v_mov_b32_dpp v64, v52 row_half_mirror row_mask:0xf bank_mask:0xf
	s_waitcnt lgkmcnt(0)
	v_add_f32_e32 v52, v52, v64
	s_nop 1
	v_mov_b32_dpp v64, v52 row_mirror row_mask:0xf bank_mask:0xf
	s_waitcnt lgkmcnt(0)
	v_add_f32_e32 v52, v52, v64
	v_fmamk_f32 v52, v52, 0x3c800000, v197
	v_cmp_gt_f32_e32 vcc, s92, v52
	v_mul_f32_e32 v64, 0x4b800000, v52
	s_nop 0
	v_cndmask_b32_e32 v52, v52, v64, vcc
	v_rsq_f32_e32 v52, v52
	s_nop 0
	v_mul_f32_e32 v64, 0x45800000, v52
	v_cndmask_b32_e32 v52, v52, v64, vcc
	v_pk_mul_f32 v[68:69], v[52:53], v[68:69] op_sel_hi:[0,1]
	v_pk_mul_f32 v[74:75], v[138:139], v[68:69]
	v_pk_mul_f32 v[68:69], v[52:53], v[72:73] op_sel_hi:[0,1]
	v_pk_mul_f32 v[72:73], v[136:137], v[68:69]
	v_lshlrev_b32_e32 v68, 2, v3
	v_mov_b32_e32 v3, v74
	v_mov_b32_e32 v77, v75
	v_mov_b32_e32 v78, v73
	v_mov_b32_e32 v80, v72
	s_and_saveexec_b64 s[10:11], s[0:1]
	s_cbranch_execz .LBB0_473
	v_mov_b32_e32 v69, v1
	v_lshl_add_u64 v[76:77], s[6:7], 0, v[68:69]
	v_subrev_u32_e32 v211, s100, v76
	ds_read_b32 v52, v211
	v_add_co_u32_e32 v76, vcc, 0x2000, v76
	v_mov_b32_e32 v141, v1
	s_nop 0
	v_addc_co_u32_e32 v77, vcc, 0, v77, vcc
	v_subrev_u32_e32 v211, s100, v76
	ds_read_b32 v56, v211
	v_lshl_add_u64 v[76:77], s[6:7], 0, v[140:141]
	v_subrev_u32_e32 v211, s100, v76
	ds_read_b32 v81, v211
	v_add_co_u32_e32 v76, vcc, 0x2000, v76
	s_waitcnt lgkmcnt(0)
	v_pk_mul_f32 v[82:83], v[74:75], v[52:53] op_sel_hi:[1,0]
	v_addc_co_u32_e32 v77, vcc, 0, v77, vcc
	v_subrev_u32_e32 v211, s100, v76
	ds_read_b32 v80, v211
	v_pk_mul_f32 v[84:85], v[74:75], v[56:57] op_sel:[1,0] op_sel_hi:[0,0]
	v_pk_fma_f32 v[76:77], v[74:75], v[52:53], v[84:85] op_sel_hi:[1,0,1]
	v_mul_f32_e32 v52, v73, v81
	v_mov_b32_e32 v86, v81
	v_sub_f32_e32 v3, v82, v84
	s_waitcnt lgkmcnt(0)
	v_pk_fma_f32 v[78:79], v[72:73], v[80:81], v[52:53] op_sel_hi:[1,1,0] neg_lo:[1,0,0] neg_hi:[1,0,0]
	v_mov_b32_e32 v87, v80
	v_mul_f32_e32 v52, v73, v80
	v_pk_fma_f32 v[80:81], v[72:73], v[86:87], v[52:53] op_sel_hi:[1,1,0]

; __device__ __forceinline__ void inproj_tile(const Params& p, char* smem, int l, int mt, int nt) {
;     ...
;           float ss = 0.f;
; #pragma unroll
;           for (int n = 0; n < 4; ++n) ss += acc[m][n][j] * acc[m][n][j];
;           ss += __shfl_xor(ss, 1); ss += __shfl_xor(ss, 2); ss += __shfl_xor(ss, 4); ss += __shfl_xor(ss, 8);
;           float rstd = rsqrtf(ss * (1.f / 64.f) + EPSF);
;           int row = rowbase + m * 16 + fq * 4 + j;
;           float v[4];
; #pragma unroll
;           for (int n = 0; n < 4; ++n) v[n] = acc[m][n][j] * rstd * w4[n];
;           bool lat = row < MLAT;
;           float rv[4] = {v[0], v[1], v[2], v[3]};
;           if (lat) {
;             int t = row & 8191, pr = t >> 6, pc = t & 63;
;             float c0 = rope[pr * 16 + fr], s0 = rope[2048 + pr * 16 + fr];
;             float c1 = rope[pc * 16 + fr], s1 = rope[2048 + pc * 16 + fr];
;             rv[0] = v[0] * c0 - v[1] * s0; rv[1] = v[1] * c0 + v[0] * s0;
;             rv[2] = v[2] * c1 - v[3] * s1; rv[3] = v[3] * c1 + v[2] * s1;
.LBB0_481:
	s_or_b64 exec, exec, s[0:1]
	v_mov_b32_e32 v60, v57
	v_pk_mul_f32 v[70:71], v[60:61], v[60:61]
	v_mov_b32_e32 v52, v65
	v_pk_mul_f32 v[64:65], v[52:53], v[52:53]
	v_add_f32_e32 v3, v70, v71
	v_add_f32_e32 v3, v65, v3
	v_add_f32_e32 v3, v64, v3
	s_nop 1
	v_mov_b32_dpp v56, v3 quad_perm:[1,0,3,2] row_mask:0xf bank_mask:0xf
	s_waitcnt lgkmcnt(0)
	v_add_f32_e32 v3, v3, v56
	s_nop 1
	v_mov_b32_dpp v56, v3 quad_perm:[2,3,0,1] row_mask:0xf bank_mask:0xf
	s_waitcnt lgkmcnt(0)
	v_add_f32_e32 v3, v3, v56
	s_nop 1
	v_mov_b32_dpp v56, v3 row_half_mirror row_mask:0xf bank_mask:0xf
	s_waitcnt lgkmcnt(0)
	v_add_f32_e32 v3, v3, v56
	s_nop 1
	v_mov_b32_dpp v56, v3 row_mirror row_mask:0xf bank_mask:0xf
	s_waitcnt lgkmcnt(0)
	v_add_f32_e32 v3, v3, v56
	v_fmamk_f32 v3, v3, 0x3c800000, v197
	v_cmp_gt_f32_e32 vcc, s92, v3
	v_mul_f32_e32 v56, 0x4b800000, v3
	s_nop 0
	v_cndmask_b32_e32 v3, v3, v56, vcc
	v_rsq_f32_e32 v3, v3
	s_nop 0
	v_mul_f32_e32 v56, 0x45800000, v3
	v_cndmask_b32_e32 v64, v3, v56, vcc
	v_mov_b32_e32 v56, v61
	v_pk_mul_f32 v[56:57], v[64:65], v[56:57] op_sel_hi:[0,1]
	v_pk_mul_f32 v[52:53], v[64:65], v[52:53] op_sel_hi:[0,1]
	v_pk_mul_f32 v[60:61], v[138:139], v[56:57]
	v_pk_mul_f32 v[52:53], v[136:137], v[52:53]
	v_or_b32_e32 v56, 0x41, v2
	v_cmp_gt_i32_e64 s[0:1], s91, v56
	v_mov_b32_e32 v3, v60
	v_mov_b32_e32 v65, v61
	v_mov_b32_e32 v70, v53
	v_mov_b32_e32 v72, v52
	s_and_saveexec_b64 s[10:11], s[0:1]
	s_cbranch_execz .LBB0_483
	v_lshlrev_b32_e32 v3, 4, v56
	s_movk_i32 s12, 0xd0
	v_and_or_b32 v3, v3, s12, v168
	v_mov_b32_e32 v69, v1
	v_lshlrev_b32_e32 v72, 2, v3
	v_mov_b32_e32 v73, v1
	v_lshl_add_u64 v[64:65], s[6:7], 0, v[68:69]
	v_lshl_add_u64 v[72:73], s[6:7], 0, v[72:73]
	v_subrev_u32_e32 v211, s100, v64
	ds_read_b32 v70, v211
	v_subrev_u32_e32 v211, s100, v72
	ds_read_b32 v75, v211
	v_add_co_u32_e32 v64, vcc, 0x2000, v64
	s_waitcnt lgkmcnt(0)
	v_pk_mul_f32 v[76:77], v[60:61], v[70:71] op_sel_hi:[1,0]
	v_addc_co_u32_e32 v65, vcc, 0, v65, vcc
	v_subrev_u32_e32 v211, s100, v64
	ds_read_b32 v64, v211
	v_add_co_u32_e32 v72, vcc, 0x2000, v72
	s_nop 1
	v_addc_co_u32_e32 v73, vcc, 0, v73, vcc
	v_subrev_u32_e32 v211, s100, v72
	ds_read_b32 v74, v211
	v_mov_b32_e32 v72, v75
	s_waitcnt lgkmcnt(0)
	v_pk_mul_f32 v[78:79], v[60:61], v[64:65] op_sel:[1,0] op_sel_hi:[0,0]
	v_pk_fma_f32 v[64:65], v[60:61], v[70:71], v[78:79] op_sel_hi:[1,0,1]
	v_sub_f32_e32 v3, v76, v78
	v_mul_f32_e32 v64, v53, v75
	v_pk_fma_f32 v[70:71], v[52:53], v[74:75], v[64:65] op_sel_hi:[1,1,0] neg_lo:[1,0,0] neg_hi:[1,0,0]
	v_mov_b32_e32 v73, v74
	v_mul_f32_e32 v64, v53, v74
	v_pk_fma_f32 v[72:73], v[52:53], v[72:73], v[64:65] op_sel_hi:[1,1,0]

; __device__ __forceinline__ void inproj_tile(const Params& p, char* smem, int l, int mt, int nt) {
;     ...
;           float ss = 0.f;
; #pragma unroll
;           for (int n = 0; n < 4; ++n) ss += acc[m][n][j] * acc[m][n][j];
;           ss += __shfl_xor(ss, 1); ss += __shfl_xor(ss, 2); ss += __shfl_xor(ss, 4); ss += __shfl_xor(ss, 8);
;           float rstd = rsqrtf(ss * (1.f / 64.f) + EPSF);
;           int row = rowbase + m * 16 + fq * 4 + j;
;           float v[4];
; #pragma unroll
;           for (int n = 0; n < 4; ++n) v[n] = acc[m][n][j] * rstd * w4[n];
;           bool lat = row < MLAT;
;           float rv[4] = {v[0], v[1], v[2], v[3]};
;           if (lat) {
;             int t = row & 8191, pr = t >> 6, pc = t & 63;
;             float c0 = rope[pr * 16 + fr], s0 = rope[2048 + pr * 16 + fr];
;             float c1 = rope[pc * 16 + fr], s1 = rope[2048 + pc * 16 + fr];
;             rv[0] = v[0] * c0 - v[1] * s0; rv[1] = v[1] * c0 + v[0] * s0;
;             rv[2] = v[2] * c1 - v[3] * s1; rv[3] = v[3] * c1 + v[2] * s1;
.LBB0_491:
	s_or_b64 exec, exec, s[0:1]
	v_mov_b32_e32 v52, v58
	v_mov_b32_e32 v53, v62
	v_pk_mul_f32 v[52:53], v[52:53], v[52:53]
	v_mov_b32_e32 v56, v66
	v_mov_b32_e32 v57, v54
	v_pk_mul_f32 v[60:61], v[56:57], v[56:57]
	v_add_f32_e32 v3, v52, v53
	v_add_f32_e32 v3, v61, v3
	v_add_f32_e32 v3, v60, v3
	s_nop 1
	v_mov_b32_dpp v52, v3 quad_perm:[1,0,3,2] row_mask:0xf bank_mask:0xf
	v_mov_b32_e32 v60, v62
	v_mov_b32_e32 v61, v58
	s_waitcnt lgkmcnt(0)
	v_add_f32_e32 v3, v3, v52
	s_nop 1
	v_mov_b32_dpp v52, v3 quad_perm:[2,3,0,1] row_mask:0xf bank_mask:0xf
	s_waitcnt lgkmcnt(0)
	v_add_f32_e32 v3, v3, v52
	s_nop 1
	v_mov_b32_dpp v52, v3 row_half_mirror row_mask:0xf bank_mask:0xf
	s_waitcnt lgkmcnt(0)
	v_add_f32_e32 v3, v3, v52
	s_nop 1
	v_mov_b32_dpp v52, v3 row_mirror row_mask:0xf bank_mask:0xf
	s_waitcnt lgkmcnt(0)
	v_add_f32_e32 v3, v3, v52
	v_fmamk_f32 v3, v3, 0x3c800000, v197
	v_cmp_gt_f32_e32 vcc, s92, v3
	v_mul_f32_e32 v52, 0x4b800000, v3
	s_nop 0
	v_cndmask_b32_e32 v3, v3, v52, vcc
	v_rsq_f32_e32 v3, v3
	s_nop 0
	v_mul_f32_e32 v52, 0x45800000, v3
	v_cndmask_b32_e32 v52, v3, v52, vcc
	v_pk_mul_f32 v[60:61], v[52:53], v[60:61] op_sel_hi:[0,1]
	v_pk_mul_f32 v[52:53], v[52:53], v[56:57] op_sel_hi:[0,1]
	v_pk_mul_f32 v[60:61], v[138:139], v[60:61]
	v_pk_mul_f32 v[52:53], v[136:137], v[52:53]
	v_or_b32_e32 v56, 0x42, v2
	v_cmp_gt_i32_e64 s[0:1], s91, v56
	v_mov_b32_e32 v3, v60
	v_mov_b32_e32 v65, v61
	v_mov_b32_e32 v70, v53
	v_mov_b32_e32 v72, v52
	s_and_saveexec_b64 s[10:11], s[0:1]
	s_cbranch_execz .LBB0_493
	v_mov_b32_e32 v69, v1
	v_lshl_add_u64 v[64:65], s[6:7], 0, v[68:69]
	v_subrev_u32_e32 v211, s100, v64
	ds_read_b32 v54, v211
	v_add_co_u32_e32 v64, vcc, 0x2000, v64
	v_lshlrev_b32_e32 v3, 4, v56
	s_movk_i32 s12, 0xe0
	v_addc_co_u32_e32 v65, vcc, 0, v65, vcc
	v_and_or_b32 v3, v3, s12, v168
	v_subrev_u32_e32 v211, s100, v64
	ds_read_b32 v58, v211
	v_lshlrev_b32_e32 v64, 2, v3
	v_mov_b32_e32 v65, v1
	v_lshl_add_u64 v[64:65], s[6:7], 0, v[64:65]
	v_subrev_u32_e32 v211, s100, v64
	ds_read_b32 v73, v211
	v_add_co_u32_e32 v64, vcc, 0x2000, v64
	s_waitcnt lgkmcnt(0)
	v_pk_mul_f32 v[74:75], v[60:61], v[54:55] op_sel_hi:[1,0]
	v_addc_co_u32_e32 v65, vcc, 0, v65, vcc
	v_subrev_u32_e32 v211, s100, v64
	ds_read_b32 v72, v211
	v_pk_mul_f32 v[76:77], v[60:61], v[58:59] op_sel:[1,0] op_sel_hi:[0,0]
	v_pk_fma_f32 v[64:65], v[60:61], v[54:55], v[76:77] op_sel_hi:[1,0,1]
	v_sub_f32_e32 v3, v74, v76
	v_mul_f32_e32 v54, v53, v73
	v_mov_b32_e32 v78, v73
	s_waitcnt lgkmcnt(0)
	v_pk_fma_f32 v[70:71], v[52:53], v[72:73], v[54:55] op_sel_hi:[1,1,0] neg_lo:[1,0,0] neg_hi:[1,0,0]
	v_mov_b32_e32 v79, v72
	v_mul_f32_e32 v54, v53, v72
	v_pk_fma_f32 v[72:73], v[52:53], v[78:79], v[54:55] op_sel_hi:[1,1,0]

; __device__ __forceinline__ void inproj_tile(const Params& p, char* smem, int l, int mt, int nt) {
;     ...
;           float ss = 0.f;
; #pragma unroll
;           for (int n = 0; n < 4; ++n) ss += acc[m][n][j] * acc[m][n][j];
;           ss += __shfl_xor(ss, 1); ss += __shfl_xor(ss, 2); ss += __shfl_xor(ss, 4); ss += __shfl_xor(ss, 8);
;           float rstd = rsqrtf(ss * (1.f / 64.f) + EPSF);
;           int row = rowbase + m * 16 + fq * 4 + j;
;           float v[4];
; #pragma unroll
;           for (int n = 0; n < 4; ++n) v[n] = acc[m][n][j] * rstd * w4[n];
;           bool lat = row < MLAT;
;           float rv[4] = {v[0], v[1], v[2], v[3]};
;           if (lat) {
;             int t = row & 8191, pr = t >> 6, pc = t & 63;
;             float c0 = rope[pr * 16 + fr], s0 = rope[2048 + pr * 16 + fr];
;             float c1 = rope[pc * 16 + fr], s1 = rope[2048 + pc * 16 + fr];
;             rv[0] = v[0] * c0 - v[1] * s0; rv[1] = v[1] * c0 + v[0] * s0;
;             rv[2] = v[2] * c1 - v[3] * s1; rv[3] = v[3] * c1 + v[2] * s1;
.LBB0_501:
	s_or_b64 exec, exec, s[0:1]
	v_mov_b32_e32 v62, v59
	v_pk_mul_f32 v[52:53], v[62:63], v[62:63]
	v_mov_b32_e32 v54, v67
	v_pk_mul_f32 v[56:57], v[54:55], v[54:55]
	v_add_f32_e32 v3, v52, v53
	v_add_f32_e32 v3, v57, v3
	v_add_f32_e32 v3, v56, v3
	s_nop 1
	v_mov_b32_dpp v52, v3 quad_perm:[1,0,3,2] row_mask:0xf bank_mask:0xf
	v_mov_b32_e32 v58, v63
	s_waitcnt lgkmcnt(0)
	v_add_f32_e32 v3, v3, v52
	s_nop 1
	v_mov_b32_dpp v52, v3 quad_perm:[2,3,0,1] row_mask:0xf bank_mask:0xf
	s_waitcnt lgkmcnt(0)
	v_add_f32_e32 v3, v3, v52
	s_nop 1
	v_mov_b32_dpp v52, v3 row_half_mirror row_mask:0xf bank_mask:0xf
	s_waitcnt lgkmcnt(0)
	v_add_f32_e32 v3, v3, v52
	s_nop 1
	v_mov_b32_dpp v52, v3 row_mirror row_mask:0xf bank_mask:0xf
	s_waitcnt lgkmcnt(0)
	v_add_f32_e32 v3, v3, v52
	v_fmamk_f32 v3, v3, 0x3c800000, v197
	v_cmp_gt_f32_e32 vcc, s92, v3
	v_mul_f32_e32 v52, 0x4b800000, v3
	s_nop 0
	v_cndmask_b32_e32 v3, v3, v52, vcc
	v_rsq_f32_e32 v3, v3
	s_nop 0
	v_mul_f32_e32 v52, 0x45800000, v3
	v_cndmask_b32_e32 v52, v3, v52, vcc
	v_pk_mul_f32 v[56:57], v[52:53], v[58:59] op_sel_hi:[0,1]
	v_pk_mul_f32 v[52:53], v[52:53], v[54:55] op_sel_hi:[0,1]
	v_pk_mul_f32 v[56:57], v[138:139], v[56:57]
	v_pk_mul_f32 v[52:53], v[136:137], v[52:53]
	v_or_b32_e32 v54, 0x43, v2
	v_cmp_gt_i32_e64 s[0:1], s91, v54
	v_mov_b32_e32 v3, v56
	v_mov_b32_e32 v59, v57
	v_mov_b32_e32 v60, v53
	v_mov_b32_e32 v62, v52
	s_and_saveexec_b64 s[10:11], s[0:1]
	s_cbranch_execz .LBB0_503
	v_lshlrev_b32_e32 v3, 4, v54
	s_movk_i32 s12, 0xf0
	v_and_or_b32 v3, v3, s12, v168
	v_mov_b32_e32 v69, v1
	v_lshlrev_b32_e32 v62, 2, v3
	v_mov_b32_e32 v63, v1
	v_lshl_add_u64 v[58:59], s[6:7], 0, v[68:69]
	v_lshl_add_u64 v[62:63], s[6:7], 0, v[62:63]
	v_subrev_u32_e32 v211, s100, v58
	ds_read_b32 v60, v211
	v_subrev_u32_e32 v211, s100, v62
	ds_read_b32 v65, v211
	v_add_co_u32_e32 v58, vcc, 0x2000, v58
	s_waitcnt lgkmcnt(0)
	v_pk_mul_f32 v[66:67], v[56:57], v[60:61] op_sel_hi:[1,0]
	v_addc_co_u32_e32 v59, vcc, 0, v59, vcc
	v_subrev_u32_e32 v211, s100, v58
	ds_read_b32 v58, v211
	v_add_co_u32_e32 v62, vcc, 0x2000, v62
	s_nop 1
	v_addc_co_u32_e32 v63, vcc, 0, v63, vcc
	v_subrev_u32_e32 v211, s100, v62
	ds_read_b32 v64, v211
	v_mov_b32_e32 v62, v65
	s_waitcnt lgkmcnt(0)
	v_pk_mul_f32 v[68:69], v[56:57], v[58:59] op_sel:[1,0] op_sel_hi:[0,0]
	v_pk_fma_f32 v[58:59], v[56:57], v[60:61], v[68:69] op_sel_hi:[1,0,1]
	v_sub_f32_e32 v3, v66, v68
	v_mul_f32_e32 v58, v53, v65
	v_pk_fma_f32 v[60:61], v[52:53], v[64:65], v[58:59] op_sel_hi:[1,1,0] neg_lo:[1,0,0] neg_hi:[1,0,0]
	v_mov_b32_e32 v63, v64
	v_mul_f32_e32 v58, v53, v64
	v_pk_fma_f32 v[62:63], v[52:53], v[62:63], v[58:59] op_sel_hi:[1,1,0]

; __device__ __forceinline__ void inproj_tile(const Params& p, char* smem, int l, int mt, int nt) {
;     ...
;           float ss = 0.f;
; #pragma unroll
;           for (int n = 0; n < 4; ++n) ss += acc[m][n][j] * acc[m][n][j];
;           ss += __shfl_xor(ss, 1); ss += __shfl_xor(ss, 2); ss += __shfl_xor(ss, 4); ss += __shfl_xor(ss, 8);
;           float rstd = rsqrtf(ss * (1.f / 64.f) + EPSF);
;           int row = rowbase + m * 16 + fq * 4 + j;
;           float v[4];
; #pragma unroll
;           for (int n = 0; n < 4; ++n) v[n] = acc[m][n][j] * rstd * w4[n];
;           bool lat = row < MLAT;
;           float rv[4] = {v[0], v[1], v[2], v[3]};
;           if (lat) {
;             int t = row & 8191, pr = t >> 6, pc = t & 63;
;             float c0 = rope[pr * 16 + fr], s0 = rope[2048 + pr * 16 + fr];
;             float c1 = rope[pc * 16 + fr], s1 = rope[2048 + pc * 16 + fr];
;             rv[0] = v[0] * c0 - v[1] * s0; rv[1] = v[1] * c0 + v[0] * s0;
;             rv[2] = v[2] * c1 - v[3] * s1; rv[3] = v[3] * c1 + v[2] * s1;
.LBB0_511:
	s_or_b64 exec, exec, s[0:1]
	v_mov_b32_e32 v52, v40
	v_mov_b32_e32 v53, v44
	v_pk_mul_f32 v[52:53], v[52:53], v[52:53]
	v_mov_b32_e32 v56, v48
	v_mov_b32_e32 v57, v36
	v_pk_mul_f32 v[58:59], v[56:57], v[56:57]
	v_add_f32_e32 v36, v52, v53
	v_add_f32_e32 v36, v59, v36
	v_add_f32_e32 v36, v58, v36
	s_nop 1
	v_mov_b32_dpp v48, v36 quad_perm:[1,0,3,2] row_mask:0xf bank_mask:0xf
	v_mov_b32_e32 v52, v44
	v_mov_b32_e32 v53, v40
	v_or_b32_e32 v54, 0x50, v2
	v_lshrrev_b32_e32 v3, 2, v54
	s_waitcnt lgkmcnt(0)
	v_add_f32_e32 v36, v36, v48
	s_nop 1
	v_mov_b32_dpp v48, v36 quad_perm:[2,3,0,1] row_mask:0xf bank_mask:0xf
	s_movk_i32 s0, 0x7f0
	v_and_or_b32 v3, v3, s0, v168
	v_cmp_gt_i32_e64 s[0:1], s91, v54
	s_waitcnt lgkmcnt(0)
	v_add_f32_e32 v36, v36, v48
	s_nop 1
	v_mov_b32_dpp v48, v36 row_half_mirror row_mask:0xf bank_mask:0xf
	s_waitcnt lgkmcnt(0)
	v_add_f32_e32 v36, v36, v48
	s_nop 1
	v_mov_b32_dpp v48, v36 row_mirror row_mask:0xf bank_mask:0xf
	s_waitcnt lgkmcnt(0)
	v_add_f32_e32 v36, v36, v48
	v_fmamk_f32 v36, v36, 0x3c800000, v197
	v_cmp_gt_f32_e32 vcc, s92, v36
	v_mul_f32_e32 v48, 0x4b800000, v36
	s_nop 0
	v_cndmask_b32_e32 v36, v36, v48, vcc
	v_rsq_f32_e32 v36, v36
	s_nop 0
	v_mul_f32_e32 v48, 0x45800000, v36
	v_cndmask_b32_e32 v36, v36, v48, vcc
	v_pk_mul_f32 v[52:53], v[36:37], v[52:53] op_sel_hi:[0,1]
	v_pk_mul_f32 v[58:59], v[138:139], v[52:53]
	v_pk_mul_f32 v[52:53], v[36:37], v[56:57] op_sel_hi:[0,1]
	v_pk_mul_f32 v[56:57], v[136:137], v[52:53]
	v_lshlrev_b32_e32 v52, 2, v3
	v_mov_b32_e32 v3, v58
	v_mov_b32_e32 v61, v59
	v_mov_b32_e32 v62, v57
	v_mov_b32_e32 v64, v56
	s_and_saveexec_b64 s[10:11], s[0:1]
	s_cbranch_execz .LBB0_513
	v_mov_b32_e32 v53, v1
	v_lshl_add_u64 v[60:61], s[6:7], 0, v[52:53]
	v_subrev_u32_e32 v211, s100, v60
	ds_read_b32 v36, v211
	v_add_co_u32_e32 v60, vcc, 0x2000, v60
	v_lshlrev_b32_e32 v3, 4, v54
	s_movk_i32 s12, 0x1c0
	v_addc_co_u32_e32 v61, vcc, 0, v61, vcc
	v_and_or_b32 v3, v3, s12, v168
	v_subrev_u32_e32 v211, s100, v60
	ds_read_b32 v40, v211
	v_lshlrev_b32_e32 v60, 2, v3
	v_mov_b32_e32 v61, v1
	v_lshl_add_u64 v[60:61], s[6:7], 0, v[60:61]
	v_subrev_u32_e32 v211, s100, v60
	ds_read_b32 v65, v211
	v_add_co_u32_e32 v60, vcc, 0x2000, v60
	s_waitcnt lgkmcnt(0)
	v_pk_mul_f32 v[66:67], v[58:59], v[36:37] op_sel_hi:[1,0]
	v_addc_co_u32_e32 v61, vcc, 0, v61, vcc
	v_subrev_u32_e32 v211, s100, v60
	ds_read_b32 v64, v211
	v_pk_mul_f32 v[68:69], v[58:59], v[40:41] op_sel:[1,0] op_sel_hi:[0,0]
	v_pk_fma_f32 v[60:61], v[58:59], v[36:37], v[68:69] op_sel_hi:[1,0,1]
	v_sub_f32_e32 v3, v66, v68
	v_mul_f32_e32 v36, v57, v65
	v_mov_b32_e32 v70, v65
	s_waitcnt lgkmcnt(0)
	v_pk_fma_f32 v[62:63], v[56:57], v[64:65], v[36:37] op_sel_hi:[1,1,0] neg_lo:[1,0,0] neg_hi:[1,0,0]
	v_mov_b32_e32 v71, v64
	v_mul_f32_e32 v36, v57, v64
	v_pk_fma_f32 v[64:65], v[56:57], v[70:71], v[36:37] op_sel_hi:[1,1,0]

; __device__ __forceinline__ void inproj_tile(const Params& p, char* smem, int l, int mt, int nt) {
;     ...
;           float ss = 0.f;
; #pragma unroll
;           for (int n = 0; n < 4; ++n) ss += acc[m][n][j] * acc[m][n][j];
;           ss += __shfl_xor(ss, 1); ss += __shfl_xor(ss, 2); ss += __shfl_xor(ss, 4); ss += __shfl_xor(ss, 8);
;           float rstd = rsqrtf(ss * (1.f / 64.f) + EPSF);
;           int row = rowbase + m * 16 + fq * 4 + j;
;           float v[4];
; #pragma unroll
;           for (int n = 0; n < 4; ++n) v[n] = acc[m][n][j] * rstd * w4[n];
;           bool lat = row < MLAT;
;           float rv[4] = {v[0], v[1], v[2], v[3]};
;           if (lat) {
;             int t = row & 8191, pr = t >> 6, pc = t & 63;
;             float c0 = rope[pr * 16 + fr], s0 = rope[2048 + pr * 16 + fr];
;             float c1 = rope[pc * 16 + fr], s1 = rope[2048 + pc * 16 + fr];
;             rv[0] = v[0] * c0 - v[1] * s0; rv[1] = v[1] * c0 + v[0] * s0;
;             rv[2] = v[2] * c1 - v[3] * s1; rv[3] = v[3] * c1 + v[2] * s1;
.LBB0_521:
	s_or_b64 exec, exec, s[0:1]
	v_mov_b32_e32 v44, v41
	v_pk_mul_f32 v[54:55], v[44:45], v[44:45]
	v_mov_b32_e32 v36, v49
	v_pk_mul_f32 v[48:49], v[36:37], v[36:37]
	v_add_f32_e32 v3, v54, v55
	v_add_f32_e32 v3, v49, v3
	v_add_f32_e32 v3, v48, v3
	s_nop 1
	v_mov_b32_dpp v40, v3 quad_perm:[1,0,3,2] row_mask:0xf bank_mask:0xf
	s_waitcnt lgkmcnt(0)
	v_add_f32_e32 v3, v3, v40
	s_nop 1
	v_mov_b32_dpp v40, v3 quad_perm:[2,3,0,1] row_mask:0xf bank_mask:0xf
	s_waitcnt lgkmcnt(0)
	v_add_f32_e32 v3, v3, v40
	s_nop 1
	v_mov_b32_dpp v40, v3 row_half_mirror row_mask:0xf bank_mask:0xf
	s_waitcnt lgkmcnt(0)
	v_add_f32_e32 v3, v3, v40
	s_nop 1
	v_mov_b32_dpp v40, v3 row_mirror row_mask:0xf bank_mask:0xf
	s_waitcnt lgkmcnt(0)
	v_add_f32_e32 v3, v3, v40
	v_fmamk_f32 v3, v3, 0x3c800000, v197
	v_cmp_gt_f32_e32 vcc, s92, v3
	v_mul_f32_e32 v40, 0x4b800000, v3
	s_nop 0
	v_cndmask_b32_e32 v3, v3, v40, vcc
	v_rsq_f32_e32 v3, v3
	s_nop 0
	v_mul_f32_e32 v40, 0x45800000, v3
	v_cndmask_b32_e32 v48, v3, v40, vcc
	v_mov_b32_e32 v40, v45
	v_pk_mul_f32 v[40:41], v[48:49], v[40:41] op_sel_hi:[0,1]
	v_pk_mul_f32 v[36:37], v[48:49], v[36:37] op_sel_hi:[0,1]
	v_pk_mul_f32 v[44:45], v[138:139], v[40:41]
	v_pk_mul_f32 v[36:37], v[136:137], v[36:37]
	v_or_b32_e32 v40, 0x51, v2
	v_cmp_gt_i32_e64 s[0:1], s91, v40
	v_mov_b32_e32 v3, v44
	v_mov_b32_e32 v49, v45
	v_mov_b32_e32 v54, v37
	v_mov_b32_e32 v56, v36
	s_and_saveexec_b64 s[10:11], s[0:1]
	s_cbranch_execz .LBB0_523
	v_lshlrev_b32_e32 v3, 4, v40
	s_movk_i32 s12, 0x1d0
	v_and_or_b32 v3, v3, s12, v168
	v_mov_b32_e32 v53, v1
	v_lshlrev_b32_e32 v56, 2, v3
	v_mov_b32_e32 v57, v1
	v_lshl_add_u64 v[48:49], s[6:7], 0, v[52:53]
	v_lshl_add_u64 v[56:57], s[6:7], 0, v[56:57]
	v_subrev_u32_e32 v211, s100, v48
	ds_read_b32 v54, v211
	v_subrev_u32_e32 v211, s100, v56
	ds_read_b32 v59, v211
	v_add_co_u32_e32 v48, vcc, 0x2000, v48
	s_waitcnt lgkmcnt(0)
	v_pk_mul_f32 v[60:61], v[44:45], v[54:55] op_sel_hi:[1,0]
	v_addc_co_u32_e32 v49, vcc, 0, v49, vcc
	v_subrev_u32_e32 v211, s100, v48
	ds_read_b32 v48, v211
	v_add_co_u32_e32 v56, vcc, 0x2000, v56
	s_nop 1
	v_addc_co_u32_e32 v57, vcc, 0, v57, vcc
	v_subrev_u32_e32 v211, s100, v56
	ds_read_b32 v58, v211
	v_mov_b32_e32 v56, v59
	s_waitcnt lgkmcnt(0)
	v_pk_mul_f32 v[62:63], v[44:45], v[48:49] op_sel:[1,0] op_sel_hi:[0,0]
	v_pk_fma_f32 v[48:49], v[44:45], v[54:55], v[62:63] op_sel_hi:[1,0,1]
	v_sub_f32_e32 v3, v60, v62
	v_mul_f32_e32 v48, v37, v59
	v_pk_fma_f32 v[54:55], v[36:37], v[58:59], v[48:49] op_sel_hi:[1,1,0] neg_lo:[1,0,0] neg_hi:[1,0,0]
	v_mov_b32_e32 v57, v58
	v_mul_f32_e32 v48, v37, v58
	v_pk_fma_f32 v[56:57], v[36:37], v[56:57], v[48:49] op_sel_hi:[1,1,0]

; __device__ __forceinline__ void inproj_tile(const Params& p, char* smem, int l, int mt, int nt) {
;     ...
;           float ss = 0.f;
; #pragma unroll
;           for (int n = 0; n < 4; ++n) ss += acc[m][n][j] * acc[m][n][j];
;           ss += __shfl_xor(ss, 1); ss += __shfl_xor(ss, 2); ss += __shfl_xor(ss, 4); ss += __shfl_xor(ss, 8);
;           float rstd = rsqrtf(ss * (1.f / 64.f) + EPSF);
;           int row = rowbase + m * 16 + fq * 4 + j;
;           float v[4];
; #pragma unroll
;           for (int n = 0; n < 4; ++n) v[n] = acc[m][n][j] * rstd * w4[n];
;           bool lat = row < MLAT;
;           float rv[4] = {v[0], v[1], v[2], v[3]};
;           if (lat) {
;             int t = row & 8191, pr = t >> 6, pc = t & 63;
;             float c0 = rope[pr * 16 + fr], s0 = rope[2048 + pr * 16 + fr];
;             float c1 = rope[pc * 16 + fr], s1 = rope[2048 + pc * 16 + fr];
;             rv[0] = v[0] * c0 - v[1] * s0; rv[1] = v[1] * c0 + v[0] * s0;
;             rv[2] = v[2] * c1 - v[3] * s1; rv[3] = v[3] * c1 + v[2] * s1;
.LBB0_531:
	s_or_b64 exec, exec, s[0:1]
	v_mov_b32_e32 v36, v42
	v_mov_b32_e32 v37, v46
	v_pk_mul_f32 v[36:37], v[36:37], v[36:37]
	v_mov_b32_e32 v40, v50
	v_mov_b32_e32 v41, v38
	v_pk_mul_f32 v[44:45], v[40:41], v[40:41]
	v_add_f32_e32 v3, v36, v37
	v_add_f32_e32 v3, v45, v3
	v_add_f32_e32 v3, v44, v3
	s_nop 1
	v_mov_b32_dpp v36, v3 quad_perm:[1,0,3,2] row_mask:0xf bank_mask:0xf
	v_mov_b32_e32 v44, v46
	v_mov_b32_e32 v45, v42
	s_waitcnt lgkmcnt(0)
	v_add_f32_e32 v3, v3, v36
	s_nop 1
	v_mov_b32_dpp v36, v3 quad_perm:[2,3,0,1] row_mask:0xf bank_mask:0xf
	s_waitcnt lgkmcnt(0)
	v_add_f32_e32 v3, v3, v36
	s_nop 1
	v_mov_b32_dpp v36, v3 row_half_mirror row_mask:0xf bank_mask:0xf
	s_waitcnt lgkmcnt(0)
	v_add_f32_e32 v3, v3, v36
	s_nop 1
	v_mov_b32_dpp v36, v3 row_mirror row_mask:0xf bank_mask:0xf
	s_waitcnt lgkmcnt(0)
	v_add_f32_e32 v3, v3, v36
	v_fmamk_f32 v3, v3, 0x3c800000, v197
	v_cmp_gt_f32_e32 vcc, s92, v3
	v_mul_f32_e32 v36, 0x4b800000, v3
	s_nop 0
	v_cndmask_b32_e32 v3, v3, v36, vcc
	v_rsq_f32_e32 v3, v3
	s_nop 0
	v_mul_f32_e32 v36, 0x45800000, v3
	v_cndmask_b32_e32 v36, v3, v36, vcc
	v_pk_mul_f32 v[44:45], v[36:37], v[44:45] op_sel_hi:[0,1]
	v_pk_mul_f32 v[36:37], v[36:37], v[40:41] op_sel_hi:[0,1]
	v_pk_mul_f32 v[44:45], v[138:139], v[44:45]
	v_pk_mul_f32 v[36:37], v[136:137], v[36:37]
	v_or_b32_e32 v40, 0x52, v2
	v_cmp_gt_i32_e64 s[0:1], s91, v40
	v_mov_b32_e32 v3, v44
	v_mov_b32_e32 v49, v45
	v_mov_b32_e32 v54, v37
	v_mov_b32_e32 v56, v36
	s_and_saveexec_b64 s[10:11], s[0:1]
	s_cbranch_execz .LBB0_533
	v_mov_b32_e32 v53, v1
	v_lshl_add_u64 v[48:49], s[6:7], 0, v[52:53]
	v_subrev_u32_e32 v211, s100, v48
	ds_read_b32 v38, v211
	v_add_co_u32_e32 v48, vcc, 0x2000, v48
	v_lshlrev_b32_e32 v3, 4, v40
	s_nop 0
	v_addc_co_u32_e32 v49, vcc, 0, v49, vcc
	v_and_or_b32 v3, v3, s40, v168
	v_subrev_u32_e32 v211, s100, v48
	ds_read_b32 v42, v211
	v_lshlrev_b32_e32 v48, 2, v3
	v_mov_b32_e32 v49, v1
	v_lshl_add_u64 v[48:49], s[6:7], 0, v[48:49]
	v_subrev_u32_e32 v211, s100, v48
	ds_read_b32 v57, v211
	v_add_co_u32_e32 v48, vcc, 0x2000, v48
	s_waitcnt lgkmcnt(0)
	v_pk_mul_f32 v[58:59], v[44:45], v[38:39] op_sel_hi:[1,0]
	v_addc_co_u32_e32 v49, vcc, 0, v49, vcc
	v_subrev_u32_e32 v211, s100, v48
	ds_read_b32 v56, v211
	v_pk_mul_f32 v[60:61], v[44:45], v[42:43] op_sel:[1,0] op_sel_hi:[0,0]
	v_pk_fma_f32 v[48:49], v[44:45], v[38:39], v[60:61] op_sel_hi:[1,0,1]
	v_sub_f32_e32 v3, v58, v60
	v_mul_f32_e32 v38, v37, v57
	v_mov_b32_e32 v62, v57
	s_waitcnt lgkmcnt(0)
	v_pk_fma_f32 v[54:55], v[36:37], v[56:57], v[38:39] op_sel_hi:[1,1,0] neg_lo:[1,0,0] neg_hi:[1,0,0]
	v_mov_b32_e32 v63, v56
	v_mul_f32_e32 v38, v37, v56
	v_pk_fma_f32 v[56:57], v[36:37], v[62:63], v[38:39] op_sel_hi:[1,1,0]

; __device__ __forceinline__ void inproj_tile(const Params& p, char* smem, int l, int mt, int nt) {
;     ...
;           float ss = 0.f;
; #pragma unroll
;           for (int n = 0; n < 4; ++n) ss += acc[m][n][j] * acc[m][n][j];
;           ss += __shfl_xor(ss, 1); ss += __shfl_xor(ss, 2); ss += __shfl_xor(ss, 4); ss += __shfl_xor(ss, 8);
;           float rstd = rsqrtf(ss * (1.f / 64.f) + EPSF);
;           int row = rowbase + m * 16 + fq * 4 + j;
;           float v[4];
; #pragma unroll
;           for (int n = 0; n < 4; ++n) v[n] = acc[m][n][j] * rstd * w4[n];
;           bool lat = row < MLAT;
;           float rv[4] = {v[0], v[1], v[2], v[3]};
;           if (lat) {
;             int t = row & 8191, pr = t >> 6, pc = t & 63;
;             float c0 = rope[pr * 16 + fr], s0 = rope[2048 + pr * 16 + fr];
;             float c1 = rope[pc * 16 + fr], s1 = rope[2048 + pc * 16 + fr];
;             rv[0] = v[0] * c0 - v[1] * s0; rv[1] = v[1] * c0 + v[0] * s0;
;             rv[2] = v[2] * c1 - v[3] * s1; rv[3] = v[3] * c1 + v[2] * s1;
.LBB0_541:
	s_or_b64 exec, exec, s[0:1]
	v_mov_b32_e32 v46, v43
	v_pk_mul_f32 v[36:37], v[46:47], v[46:47]
	v_mov_b32_e32 v38, v51
	v_pk_mul_f32 v[40:41], v[38:39], v[38:39]
	v_add_f32_e32 v3, v36, v37
	v_add_f32_e32 v3, v41, v3
	v_add_f32_e32 v3, v40, v3
	s_nop 1
	v_mov_b32_dpp v36, v3 quad_perm:[1,0,3,2] row_mask:0xf bank_mask:0xf
	v_mov_b32_e32 v42, v47
	s_waitcnt lgkmcnt(0)
	v_add_f32_e32 v3, v3, v36
	s_nop 1
	v_mov_b32_dpp v36, v3 quad_perm:[2,3,0,1] row_mask:0xf bank_mask:0xf
	s_waitcnt lgkmcnt(0)
	v_add_f32_e32 v3, v3, v36
	s_nop 1
	v_mov_b32_dpp v36, v3 row_half_mirror row_mask:0xf bank_mask:0xf
	s_waitcnt lgkmcnt(0)
	v_add_f32_e32 v3, v3, v36
	s_nop 1
	v_mov_b32_dpp v36, v3 row_mirror row_mask:0xf bank_mask:0xf
	s_waitcnt lgkmcnt(0)
	v_add_f32_e32 v3, v3, v36
	v_fmamk_f32 v3, v3, 0x3c800000, v197
	v_cmp_gt_f32_e32 vcc, s92, v3
	v_mul_f32_e32 v36, 0x4b800000, v3
	s_nop 0
	v_cndmask_b32_e32 v3, v3, v36, vcc
	v_rsq_f32_e32 v3, v3
	s_nop 0
	v_mul_f32_e32 v36, 0x45800000, v3
	v_cndmask_b32_e32 v36, v3, v36, vcc
	v_pk_mul_f32 v[40:41], v[36:37], v[42:43] op_sel_hi:[0,1]
	v_pk_mul_f32 v[36:37], v[36:37], v[38:39] op_sel_hi:[0,1]
	v_pk_mul_f32 v[40:41], v[138:139], v[40:41]
	v_pk_mul_f32 v[36:37], v[136:137], v[36:37]
	v_or_b32_e32 v38, 0x53, v2
	v_cmp_gt_i32_e64 s[0:1], s91, v38
	v_mov_b32_e32 v3, v40
	v_mov_b32_e32 v43, v41
	v_mov_b32_e32 v44, v37
	v_mov_b32_e32 v46, v36
	s_and_saveexec_b64 s[10:11], s[0:1]
	s_cbranch_execz .LBB0_543
	v_lshlrev_b32_e32 v3, 4, v38
	s_movk_i32 s12, 0x1f0
	v_and_or_b32 v3, v3, s12, v168
	v_mov_b32_e32 v53, v1
	v_lshlrev_b32_e32 v46, 2, v3
	v_mov_b32_e32 v47, v1
	v_lshl_add_u64 v[42:43], s[6:7], 0, v[52:53]
	v_lshl_add_u64 v[46:47], s[6:7], 0, v[46:47]
	v_subrev_u32_e32 v211, s100, v42
	ds_read_b32 v44, v211
	v_subrev_u32_e32 v211, s100, v46
	ds_read_b32 v49, v211
	v_add_co_u32_e32 v42, vcc, 0x2000, v42
	s_waitcnt lgkmcnt(0)
	v_pk_mul_f32 v[50:51], v[40:41], v[44:45] op_sel_hi:[1,0]
	v_addc_co_u32_e32 v43, vcc, 0, v43, vcc
	v_subrev_u32_e32 v211, s100, v42
	ds_read_b32 v42, v211
	v_add_co_u32_e32 v46, vcc, 0x2000, v46
	s_nop 1
	v_addc_co_u32_e32 v47, vcc, 0, v47, vcc
	v_subrev_u32_e32 v211, s100, v46
	ds_read_b32 v48, v211
	v_mov_b32_e32 v46, v49
	s_waitcnt lgkmcnt(0)
	v_pk_mul_f32 v[52:53], v[40:41], v[42:43] op_sel:[1,0] op_sel_hi:[0,0]
	v_pk_fma_f32 v[42:43], v[40:41], v[44:45], v[52:53] op_sel_hi:[1,0,1]
	v_sub_f32_e32 v3, v50, v52
	v_mul_f32_e32 v42, v37, v49
	v_pk_fma_f32 v[44:45], v[36:37], v[48:49], v[42:43] op_sel_hi:[1,1,0] neg_lo:[1,0,0] neg_hi:[1,0,0]
	v_mov_b32_e32 v47, v48
	v_mul_f32_e32 v42, v37, v48
	v_pk_fma_f32 v[46:47], v[36:37], v[46:47], v[42:43] op_sel_hi:[1,1,0]

; __device__ __forceinline__ void inproj_tile(const Params& p, char* smem, int l, int mt, int nt) {
;     ...
;           float ss = 0.f;
; #pragma unroll
;           for (int n = 0; n < 4; ++n) ss += acc[m][n][j] * acc[m][n][j];
;           ss += __shfl_xor(ss, 1); ss += __shfl_xor(ss, 2); ss += __shfl_xor(ss, 4); ss += __shfl_xor(ss, 8);
;           float rstd = rsqrtf(ss * (1.f / 64.f) + EPSF);
;           int row = rowbase + m * 16 + fq * 4 + j;
;           float v[4];
; #pragma unroll
;           for (int n = 0; n < 4; ++n) v[n] = acc[m][n][j] * rstd * w4[n];
;           bool lat = row < MLAT;
;           float rv[4] = {v[0], v[1], v[2], v[3]};
;           if (lat) {
;             int t = row & 8191, pr = t >> 6, pc = t & 63;
;             float c0 = rope[pr * 16 + fr], s0 = rope[2048 + pr * 16 + fr];
;             float c1 = rope[pc * 16 + fr], s1 = rope[2048 + pc * 16 + fr];
;             rv[0] = v[0] * c0 - v[1] * s0; rv[1] = v[1] * c0 + v[0] * s0;
;             rv[2] = v[2] * c1 - v[3] * s1; rv[3] = v[3] * c1 + v[2] * s1;
.LBB0_551:
	s_or_b64 exec, exec, s[0:1]
	v_mov_b32_e32 v36, v24
	v_mov_b32_e32 v37, v28
	v_pk_mul_f32 v[36:37], v[36:37], v[36:37]
	v_mov_b32_e32 v40, v32
	v_mov_b32_e32 v41, v20
	v_pk_mul_f32 v[42:43], v[40:41], v[40:41]
	v_add_f32_e32 v20, v36, v37
	v_add_f32_e32 v20, v43, v20
	v_add_f32_e32 v20, v42, v20
	s_nop 1
	v_mov_b32_dpp v32, v20 quad_perm:[1,0,3,2] row_mask:0xf bank_mask:0xf
	v_mov_b32_e32 v36, v28
	v_mov_b32_e32 v37, v24
	v_or_b32_e32 v38, 0x60, v2
	v_lshrrev_b32_e32 v3, 2, v38
	s_waitcnt lgkmcnt(0)
	v_add_f32_e32 v20, v20, v32
	s_nop 1
	v_mov_b32_dpp v32, v20 quad_perm:[2,3,0,1] row_mask:0xf bank_mask:0xf
	s_movk_i32 s0, 0x7f0
	v_and_or_b32 v3, v3, s0, v168
	v_cmp_gt_i32_e64 s[0:1], s91, v38
	s_waitcnt lgkmcnt(0)
	v_add_f32_e32 v20, v20, v32
	s_nop 1
	v_mov_b32_dpp v32, v20 row_half_mirror row_mask:0xf bank_mask:0xf
	s_waitcnt lgkmcnt(0)
	v_add_f32_e32 v20, v20, v32
	s_nop 1
	v_mov_b32_dpp v32, v20 row_mirror row_mask:0xf bank_mask:0xf
	s_waitcnt lgkmcnt(0)
	v_add_f32_e32 v20, v20, v32
	v_fmamk_f32 v20, v20, 0x3c800000, v197
	v_cmp_gt_f32_e32 vcc, s92, v20
	v_mul_f32_e32 v32, 0x4b800000, v20
	s_nop 0
	v_cndmask_b32_e32 v20, v20, v32, vcc
	v_rsq_f32_e32 v20, v20
	s_nop 0
	v_mul_f32_e32 v32, 0x45800000, v20
	v_cndmask_b32_e32 v20, v20, v32, vcc
	v_pk_mul_f32 v[36:37], v[20:21], v[36:37] op_sel_hi:[0,1]
	v_pk_mul_f32 v[42:43], v[138:139], v[36:37]
	v_pk_mul_f32 v[36:37], v[20:21], v[40:41] op_sel_hi:[0,1]
	v_pk_mul_f32 v[40:41], v[136:137], v[36:37]
	v_lshlrev_b32_e32 v36, 2, v3
	v_mov_b32_e32 v3, v42
	v_mov_b32_e32 v45, v43
	v_mov_b32_e32 v46, v41
	v_mov_b32_e32 v48, v40
	s_and_saveexec_b64 s[10:11], s[0:1]
	s_cbranch_execz .LBB0_553
	v_mov_b32_e32 v37, v1
	v_lshl_add_u64 v[44:45], s[6:7], 0, v[36:37]
	v_subrev_u32_e32 v211, s100, v44
	ds_read_b32 v20, v211
	v_add_co_u32_e32 v44, vcc, 0x2000, v44
	v_lshlrev_b32_e32 v3, 4, v38
	s_movk_i32 s12, 0x2c0
	v_addc_co_u32_e32 v45, vcc, 0, v45, vcc
	v_and_or_b32 v3, v3, s12, v168
	v_subrev_u32_e32 v211, s100, v44
	ds_read_b32 v24, v211
	v_lshlrev_b32_e32 v44, 2, v3
	v_mov_b32_e32 v45, v1
	v_lshl_add_u64 v[44:45], s[6:7], 0, v[44:45]
	v_subrev_u32_e32 v211, s100, v44
	ds_read_b32 v49, v211
	v_add_co_u32_e32 v44, vcc, 0x2000, v44
	s_waitcnt lgkmcnt(0)
	v_pk_mul_f32 v[50:51], v[42:43], v[20:21] op_sel_hi:[1,0]
	v_addc_co_u32_e32 v45, vcc, 0, v45, vcc
	v_subrev_u32_e32 v211, s100, v44
	ds_read_b32 v48, v211
	v_pk_mul_f32 v[52:53], v[42:43], v[24:25] op_sel:[1,0] op_sel_hi:[0,0]
	v_pk_fma_f32 v[44:45], v[42:43], v[20:21], v[52:53] op_sel_hi:[1,0,1]
	v_sub_f32_e32 v3, v50, v52
	v_mul_f32_e32 v20, v41, v49
	v_mov_b32_e32 v54, v49
	s_waitcnt lgkmcnt(0)
	v_pk_fma_f32 v[46:47], v[40:41], v[48:49], v[20:21] op_sel_hi:[1,1,0] neg_lo:[1,0,0] neg_hi:[1,0,0]
	v_mov_b32_e32 v55, v48
	v_mul_f32_e32 v20, v41, v48
	v_pk_fma_f32 v[48:49], v[40:41], v[54:55], v[20:21] op_sel_hi:[1,1,0]

; __device__ __forceinline__ void inproj_tile(const Params& p, char* smem, int l, int mt, int nt) {
;     ...
;           float ss = 0.f;
; #pragma unroll
;           for (int n = 0; n < 4; ++n) ss += acc[m][n][j] * acc[m][n][j];
;           ss += __shfl_xor(ss, 1); ss += __shfl_xor(ss, 2); ss += __shfl_xor(ss, 4); ss += __shfl_xor(ss, 8);
;           float rstd = rsqrtf(ss * (1.f / 64.f) + EPSF);
;           int row = rowbase + m * 16 + fq * 4 + j;
;           float v[4];
; #pragma unroll
;           for (int n = 0; n < 4; ++n) v[n] = acc[m][n][j] * rstd * w4[n];
;           bool lat = row < MLAT;
;           float rv[4] = {v[0], v[1], v[2], v[3]};
;           if (lat) {
;             int t = row & 8191, pr = t >> 6, pc = t & 63;
;             float c0 = rope[pr * 16 + fr], s0 = rope[2048 + pr * 16 + fr];
;             float c1 = rope[pc * 16 + fr], s1 = rope[2048 + pc * 16 + fr];
;             rv[0] = v[0] * c0 - v[1] * s0; rv[1] = v[1] * c0 + v[0] * s0;
;             rv[2] = v[2] * c1 - v[3] * s1; rv[3] = v[3] * c1 + v[2] * s1;
.LBB0_561:
	s_or_b64 exec, exec, s[0:1]
	v_mov_b32_e32 v28, v25
	v_pk_mul_f32 v[38:39], v[28:29], v[28:29]
	v_mov_b32_e32 v20, v33
	v_pk_mul_f32 v[32:33], v[20:21], v[20:21]
	v_add_f32_e32 v3, v38, v39
	v_add_f32_e32 v3, v33, v3
	v_add_f32_e32 v3, v32, v3
	s_nop 1
	v_mov_b32_dpp v24, v3 quad_perm:[1,0,3,2] row_mask:0xf bank_mask:0xf
	s_waitcnt lgkmcnt(0)
	v_add_f32_e32 v3, v3, v24
	s_nop 1
	v_mov_b32_dpp v24, v3 quad_perm:[2,3,0,1] row_mask:0xf bank_mask:0xf
	s_waitcnt lgkmcnt(0)
	v_add_f32_e32 v3, v3, v24
	s_nop 1
	v_mov_b32_dpp v24, v3 row_half_mirror row_mask:0xf bank_mask:0xf
	s_waitcnt lgkmcnt(0)
	v_add_f32_e32 v3, v3, v24
	s_nop 1
	v_mov_b32_dpp v24, v3 row_mirror row_mask:0xf bank_mask:0xf
	s_waitcnt lgkmcnt(0)
	v_add_f32_e32 v3, v3, v24
	v_fmamk_f32 v3, v3, 0x3c800000, v197
	v_cmp_gt_f32_e32 vcc, s92, v3
	v_mul_f32_e32 v24, 0x4b800000, v3
	s_nop 0
	v_cndmask_b32_e32 v3, v3, v24, vcc
	v_rsq_f32_e32 v3, v3
	s_nop 0
	v_mul_f32_e32 v24, 0x45800000, v3
	v_cndmask_b32_e32 v32, v3, v24, vcc
	v_mov_b32_e32 v24, v29
	v_pk_mul_f32 v[24:25], v[32:33], v[24:25] op_sel_hi:[0,1]
	v_pk_mul_f32 v[20:21], v[32:33], v[20:21] op_sel_hi:[0,1]
	v_pk_mul_f32 v[28:29], v[138:139], v[24:25]
	v_pk_mul_f32 v[20:21], v[136:137], v[20:21]
	v_or_b32_e32 v24, 0x61, v2
	v_cmp_gt_i32_e64 s[0:1], s91, v24
	v_mov_b32_e32 v3, v28
	v_mov_b32_e32 v33, v29
	v_mov_b32_e32 v38, v21
	v_mov_b32_e32 v40, v20
	s_and_saveexec_b64 s[10:11], s[0:1]
	s_cbranch_execz .LBB0_563
	v_lshlrev_b32_e32 v3, 4, v24
	s_movk_i32 s12, 0x2d0
	v_and_or_b32 v3, v3, s12, v168
	v_mov_b32_e32 v37, v1
	v_lshlrev_b32_e32 v40, 2, v3
	v_mov_b32_e32 v41, v1
	v_lshl_add_u64 v[32:33], s[6:7], 0, v[36:37]
	v_lshl_add_u64 v[40:41], s[6:7], 0, v[40:41]
	v_subrev_u32_e32 v211, s100, v32
	ds_read_b32 v38, v211
	v_subrev_u32_e32 v211, s100, v40
	ds_read_b32 v43, v211
	v_add_co_u32_e32 v32, vcc, 0x2000, v32
	s_waitcnt lgkmcnt(0)
	v_pk_mul_f32 v[44:45], v[28:29], v[38:39] op_sel_hi:[1,0]
	v_addc_co_u32_e32 v33, vcc, 0, v33, vcc
	v_subrev_u32_e32 v211, s100, v32
	ds_read_b32 v32, v211
	v_add_co_u32_e32 v40, vcc, 0x2000, v40
	s_nop 1
	v_addc_co_u32_e32 v41, vcc, 0, v41, vcc
	v_subrev_u32_e32 v211, s100, v40
	ds_read_b32 v42, v211
	v_mov_b32_e32 v40, v43
	s_waitcnt lgkmcnt(0)
	v_pk_mul_f32 v[46:47], v[28:29], v[32:33] op_sel:[1,0] op_sel_hi:[0,0]
	v_pk_fma_f32 v[32:33], v[28:29], v[38:39], v[46:47] op_sel_hi:[1,0,1]
	v_sub_f32_e32 v3, v44, v46
	v_mul_f32_e32 v32, v21, v43
	v_pk_fma_f32 v[38:39], v[20:21], v[42:43], v[32:33] op_sel_hi:[1,1,0] neg_lo:[1,0,0] neg_hi:[1,0,0]
	v_mov_b32_e32 v41, v42
	v_mul_f32_e32 v32, v21, v42
	v_pk_fma_f32 v[40:41], v[20:21], v[40:41], v[32:33] op_sel_hi:[1,1,0]

; __device__ __forceinline__ void inproj_tile(const Params& p, char* smem, int l, int mt, int nt) {
;     ...
;           float ss = 0.f;
; #pragma unroll
;           for (int n = 0; n < 4; ++n) ss += acc[m][n][j] * acc[m][n][j];
;           ss += __shfl_xor(ss, 1); ss += __shfl_xor(ss, 2); ss += __shfl_xor(ss, 4); ss += __shfl_xor(ss, 8);
;           float rstd = rsqrtf(ss * (1.f / 64.f) + EPSF);
;           int row = rowbase + m * 16 + fq * 4 + j;
;           float v[4];
; #pragma unroll
;           for (int n = 0; n < 4; ++n) v[n] = acc[m][n][j] * rstd * w4[n];
;           bool lat = row < MLAT;
;           float rv[4] = {v[0], v[1], v[2], v[3]};
;           if (lat) {
;             int t = row & 8191, pr = t >> 6, pc = t & 63;
;             float c0 = rope[pr * 16 + fr], s0 = rope[2048 + pr * 16 + fr];
;             float c1 = rope[pc * 16 + fr], s1 = rope[2048 + pc * 16 + fr];
;             rv[0] = v[0] * c0 - v[1] * s0; rv[1] = v[1] * c0 + v[0] * s0;
;             rv[2] = v[2] * c1 - v[3] * s1; rv[3] = v[3] * c1 + v[2] * s1;
.LBB0_571:
	s_or_b64 exec, exec, s[0:1]
	v_mov_b32_e32 v20, v26
	v_mov_b32_e32 v21, v30
	v_pk_mul_f32 v[20:21], v[20:21], v[20:21]
	v_mov_b32_e32 v24, v34
	v_mov_b32_e32 v25, v22
	v_pk_mul_f32 v[28:29], v[24:25], v[24:25]
	v_add_f32_e32 v3, v20, v21
	v_add_f32_e32 v3, v29, v3
	v_add_f32_e32 v3, v28, v3
	s_nop 1
	v_mov_b32_dpp v20, v3 quad_perm:[1,0,3,2] row_mask:0xf bank_mask:0xf
	v_mov_b32_e32 v28, v30
	v_mov_b32_e32 v29, v26
	s_waitcnt lgkmcnt(0)
	v_add_f32_e32 v3, v3, v20
	s_nop 1
	v_mov_b32_dpp v20, v3 quad_perm:[2,3,0,1] row_mask:0xf bank_mask:0xf
	s_waitcnt lgkmcnt(0)
	v_add_f32_e32 v3, v3, v20
	s_nop 1
	v_mov_b32_dpp v20, v3 row_half_mirror row_mask:0xf bank_mask:0xf
	s_waitcnt lgkmcnt(0)
	v_add_f32_e32 v3, v3, v20
	s_nop 1
	v_mov_b32_dpp v20, v3 row_mirror row_mask:0xf bank_mask:0xf
	s_waitcnt lgkmcnt(0)
	v_add_f32_e32 v3, v3, v20
	v_fmamk_f32 v3, v3, 0x3c800000, v197
	v_cmp_gt_f32_e32 vcc, s92, v3
	v_mul_f32_e32 v20, 0x4b800000, v3
	s_nop 0
	v_cndmask_b32_e32 v3, v3, v20, vcc
	v_rsq_f32_e32 v3, v3
	s_nop 0
	v_mul_f32_e32 v20, 0x45800000, v3
	v_cndmask_b32_e32 v20, v3, v20, vcc
	v_pk_mul_f32 v[28:29], v[20:21], v[28:29] op_sel_hi:[0,1]
	v_pk_mul_f32 v[20:21], v[20:21], v[24:25] op_sel_hi:[0,1]
	v_pk_mul_f32 v[28:29], v[138:139], v[28:29]
	v_pk_mul_f32 v[20:21], v[136:137], v[20:21]
	v_or_b32_e32 v24, 0x62, v2
	v_cmp_gt_i32_e64 s[0:1], s91, v24
	v_mov_b32_e32 v3, v28
	v_mov_b32_e32 v33, v29
	v_mov_b32_e32 v38, v21
	v_mov_b32_e32 v40, v20
	s_and_saveexec_b64 s[10:11], s[0:1]
	s_cbranch_execz .LBB0_573
	v_mov_b32_e32 v37, v1
	v_lshl_add_u64 v[32:33], s[6:7], 0, v[36:37]
	v_subrev_u32_e32 v211, s100, v32
	ds_read_b32 v22, v211
	v_add_co_u32_e32 v32, vcc, 0x2000, v32
	v_lshlrev_b32_e32 v3, 4, v24
	s_movk_i32 s12, 0x2e0
	v_addc_co_u32_e32 v33, vcc, 0, v33, vcc
	v_and_or_b32 v3, v3, s12, v168
	v_subrev_u32_e32 v211, s100, v32
	ds_read_b32 v26, v211
	v_lshlrev_b32_e32 v32, 2, v3
	v_mov_b32_e32 v33, v1
	v_lshl_add_u64 v[32:33], s[6:7], 0, v[32:33]
	v_subrev_u32_e32 v211, s100, v32
	ds_read_b32 v41, v211
	v_add_co_u32_e32 v32, vcc, 0x2000, v32
	s_waitcnt lgkmcnt(0)
	v_pk_mul_f32 v[42:43], v[28:29], v[22:23] op_sel_hi:[1,0]
	v_addc_co_u32_e32 v33, vcc, 0, v33, vcc
	v_subrev_u32_e32 v211, s100, v32
	ds_read_b32 v40, v211
	v_pk_mul_f32 v[44:45], v[28:29], v[26:27] op_sel:[1,0] op_sel_hi:[0,0]
	v_pk_fma_f32 v[32:33], v[28:29], v[22:23], v[44:45] op_sel_hi:[1,0,1]
	v_sub_f32_e32 v3, v42, v44
	v_mul_f32_e32 v22, v21, v41
	v_mov_b32_e32 v46, v41
	s_waitcnt lgkmcnt(0)
	v_pk_fma_f32 v[38:39], v[20:21], v[40:41], v[22:23] op_sel_hi:[1,1,0] neg_lo:[1,0,0] neg_hi:[1,0,0]
	v_mov_b32_e32 v47, v40
	v_mul_f32_e32 v22, v21, v40
	v_pk_fma_f32 v[40:41], v[20:21], v[46:47], v[22:23] op_sel_hi:[1,1,0]

; __device__ __forceinline__ void inproj_tile(const Params& p, char* smem, int l, int mt, int nt) {
;     ...
;           float ss = 0.f;
; #pragma unroll
;           for (int n = 0; n < 4; ++n) ss += acc[m][n][j] * acc[m][n][j];
;           ss += __shfl_xor(ss, 1); ss += __shfl_xor(ss, 2); ss += __shfl_xor(ss, 4); ss += __shfl_xor(ss, 8);
;           float rstd = rsqrtf(ss * (1.f / 64.f) + EPSF);
;           int row = rowbase + m * 16 + fq * 4 + j;
;           float v[4];
; #pragma unroll
;           for (int n = 0; n < 4; ++n) v[n] = acc[m][n][j] * rstd * w4[n];
;           bool lat = row < MLAT;
;           float rv[4] = {v[0], v[1], v[2], v[3]};
;           if (lat) {
;             int t = row & 8191, pr = t >> 6, pc = t & 63;
;             float c0 = rope[pr * 16 + fr], s0 = rope[2048 + pr * 16 + fr];
;             float c1 = rope[pc * 16 + fr], s1 = rope[2048 + pc * 16 + fr];
;             rv[0] = v[0] * c0 - v[1] * s0; rv[1] = v[1] * c0 + v[0] * s0;
;             rv[2] = v[2] * c1 - v[3] * s1; rv[3] = v[3] * c1 + v[2] * s1;
.LBB0_581:
	s_or_b64 exec, exec, s[0:1]
	v_mov_b32_e32 v30, v27
	v_pk_mul_f32 v[20:21], v[30:31], v[30:31]
	v_mov_b32_e32 v22, v35
	v_pk_mul_f32 v[24:25], v[22:23], v[22:23]
	v_add_f32_e32 v3, v20, v21
	v_add_f32_e32 v3, v25, v3
	v_add_f32_e32 v3, v24, v3
	s_nop 1
	v_mov_b32_dpp v20, v3 quad_perm:[1,0,3,2] row_mask:0xf bank_mask:0xf
	v_mov_b32_e32 v26, v31
	s_waitcnt lgkmcnt(0)
	v_add_f32_e32 v3, v3, v20
	s_nop 1
	v_mov_b32_dpp v20, v3 quad_perm:[2,3,0,1] row_mask:0xf bank_mask:0xf
	s_waitcnt lgkmcnt(0)
	v_add_f32_e32 v3, v3, v20
	s_nop 1
	v_mov_b32_dpp v20, v3 row_half_mirror row_mask:0xf bank_mask:0xf
	s_waitcnt lgkmcnt(0)
	v_add_f32_e32 v3, v3, v20
	s_nop 1
	v_mov_b32_dpp v20, v3 row_mirror row_mask:0xf bank_mask:0xf
	s_waitcnt lgkmcnt(0)
	v_add_f32_e32 v3, v3, v20
	v_fmamk_f32 v3, v3, 0x3c800000, v197
	v_cmp_gt_f32_e32 vcc, s92, v3
	v_mul_f32_e32 v20, 0x4b800000, v3
	s_nop 0
	v_cndmask_b32_e32 v3, v3, v20, vcc
	v_rsq_f32_e32 v3, v3
	s_nop 0
	v_mul_f32_e32 v20, 0x45800000, v3
	v_cndmask_b32_e32 v20, v3, v20, vcc
	v_pk_mul_f32 v[24:25], v[20:21], v[26:27] op_sel_hi:[0,1]
	v_pk_mul_f32 v[20:21], v[20:21], v[22:23] op_sel_hi:[0,1]
	v_pk_mul_f32 v[24:25], v[138:139], v[24:25]
	v_pk_mul_f32 v[20:21], v[136:137], v[20:21]
	v_or_b32_e32 v22, 0x63, v2
	v_cmp_gt_i32_e64 s[0:1], s91, v22
	v_mov_b32_e32 v3, v24
	v_mov_b32_e32 v27, v25
	v_mov_b32_e32 v28, v21
	v_mov_b32_e32 v30, v20
	s_and_saveexec_b64 s[10:11], s[0:1]
	s_cbranch_execz .LBB0_583
	v_lshlrev_b32_e32 v3, 4, v22
	s_movk_i32 s12, 0x2f0
	v_and_or_b32 v3, v3, s12, v168
	v_mov_b32_e32 v37, v1
	v_lshlrev_b32_e32 v30, 2, v3
	v_mov_b32_e32 v31, v1
	v_lshl_add_u64 v[26:27], s[6:7], 0, v[36:37]
	v_lshl_add_u64 v[30:31], s[6:7], 0, v[30:31]
	v_subrev_u32_e32 v211, s100, v26
	ds_read_b32 v28, v211
	v_subrev_u32_e32 v211, s100, v30
	ds_read_b32 v33, v211
	v_add_co_u32_e32 v26, vcc, 0x2000, v26
	s_waitcnt lgkmcnt(0)
	v_pk_mul_f32 v[34:35], v[24:25], v[28:29] op_sel_hi:[1,0]
	v_addc_co_u32_e32 v27, vcc, 0, v27, vcc
	v_subrev_u32_e32 v211, s100, v26
	ds_read_b32 v26, v211
	v_add_co_u32_e32 v30, vcc, 0x2000, v30
	s_nop 1
	v_addc_co_u32_e32 v31, vcc, 0, v31, vcc
	v_subrev_u32_e32 v211, s100, v30
	ds_read_b32 v32, v211
	v_mov_b32_e32 v30, v33
	s_waitcnt lgkmcnt(0)
	v_pk_mul_f32 v[36:37], v[24:25], v[26:27] op_sel:[1,0] op_sel_hi:[0,0]
	v_pk_fma_f32 v[26:27], v[24:25], v[28:29], v[36:37] op_sel_hi:[1,0,1]
	v_sub_f32_e32 v3, v34, v36
	v_mul_f32_e32 v26, v21, v33
	v_pk_fma_f32 v[28:29], v[20:21], v[32:33], v[26:27] op_sel_hi:[1,1,0] neg_lo:[1,0,0] neg_hi:[1,0,0]
	v_mov_b32_e32 v31, v32
	v_mul_f32_e32 v26, v21, v32
	v_pk_fma_f32 v[30:31], v[20:21], v[30:31], v[26:27] op_sel_hi:[1,1,0]

; __device__ __forceinline__ void inproj_tile(const Params& p, char* smem, int l, int mt, int nt) {
;     ...
;           float ss = 0.f;
; #pragma unroll
;           for (int n = 0; n < 4; ++n) ss += acc[m][n][j] * acc[m][n][j];
;           ss += __shfl_xor(ss, 1); ss += __shfl_xor(ss, 2); ss += __shfl_xor(ss, 4); ss += __shfl_xor(ss, 8);
;           float rstd = rsqrtf(ss * (1.f / 64.f) + EPSF);
;           int row = rowbase + m * 16 + fq * 4 + j;
;           float v[4];
; #pragma unroll
;           for (int n = 0; n < 4; ++n) v[n] = acc[m][n][j] * rstd * w4[n];
;           bool lat = row < MLAT;
;           float rv[4] = {v[0], v[1], v[2], v[3]};
;           if (lat) {
;             int t = row & 8191, pr = t >> 6, pc = t & 63;
;             float c0 = rope[pr * 16 + fr], s0 = rope[2048 + pr * 16 + fr];
;             float c1 = rope[pc * 16 + fr], s1 = rope[2048 + pc * 16 + fr];
;             rv[0] = v[0] * c0 - v[1] * s0; rv[1] = v[1] * c0 + v[0] * s0;
;             rv[2] = v[2] * c1 - v[3] * s1; rv[3] = v[3] * c1 + v[2] * s1;
;           }
;           if (isq) {
; #pragma unroll
;             for (int n = 0; n < 4; ++n) UL[(size_t)row * 2560 + colbase + n * 16 + fr] = f2bf(v[n]);
;             if (lat) {
; #pragma unroll
;               for (int n = 0; n < 4; ++n) QROT[(size_t)row * 512 + colbase + n * 16 + fr] = f2bf(rv[n]);
.LBB0_591:
	s_or_b64 exec, exec, s[0:1]
	v_mov_b32_e32 v20, v8
	v_mov_b32_e32 v21, v12
	v_pk_mul_f32 v[20:21], v[20:21], v[20:21]
	v_mov_b32_e32 v24, v16
	v_mov_b32_e32 v25, v4
	v_pk_mul_f32 v[26:27], v[24:25], v[24:25]
	v_add_f32_e32 v4, v20, v21
	v_add_f32_e32 v4, v27, v4
	v_add_f32_e32 v4, v26, v4
	s_nop 1
	v_mov_b32_dpp v16, v4 quad_perm:[1,0,3,2] row_mask:0xf bank_mask:0xf
	v_mov_b32_e32 v20, v12
	v_mov_b32_e32 v21, v8
	v_or_b32_e32 v22, 0x70, v2
	v_lshrrev_b32_e32 v3, 2, v22
	s_waitcnt lgkmcnt(0)
	v_add_f32_e32 v4, v4, v16
	s_nop 1
	v_mov_b32_dpp v16, v4 quad_perm:[2,3,0,1] row_mask:0xf bank_mask:0xf
	s_movk_i32 s0, 0x7f0
	v_and_or_b32 v3, v3, s0, v168
	v_cmp_gt_i32_e64 s[0:1], s91, v22
	s_waitcnt lgkmcnt(0)
	v_add_f32_e32 v4, v4, v16
	s_nop 1
	v_mov_b32_dpp v16, v4 row_half_mirror row_mask:0xf bank_mask:0xf
	s_waitcnt lgkmcnt(0)
	v_add_f32_e32 v4, v4, v16
	s_nop 1
	v_mov_b32_dpp v16, v4 row_mirror row_mask:0xf bank_mask:0xf
	s_waitcnt lgkmcnt(0)
	v_add_f32_e32 v4, v4, v16
	v_fmamk_f32 v4, v4, 0x3c800000, v197
	v_cmp_gt_f32_e32 vcc, s92, v4
	v_mul_f32_e32 v16, 0x4b800000, v4
	s_nop 0
	v_cndmask_b32_e32 v4, v4, v16, vcc
	v_rsq_f32_e32 v4, v4
	s_nop 0
	v_mul_f32_e32 v16, 0x45800000, v4
	v_cndmask_b32_e32 v4, v4, v16, vcc
	v_pk_mul_f32 v[20:21], v[4:5], v[20:21] op_sel_hi:[0,1]
	v_pk_mul_f32 v[26:27], v[138:139], v[20:21]
	v_pk_mul_f32 v[20:21], v[4:5], v[24:25] op_sel_hi:[0,1]
	v_pk_mul_f32 v[24:25], v[136:137], v[20:21]
	v_lshlrev_b32_e32 v20, 2, v3
	v_mov_b32_e32 v3, v26
	v_mov_b32_e32 v29, v27
	v_mov_b32_e32 v30, v25
	v_mov_b32_e32 v32, v24
	s_and_saveexec_b64 s[10:11], s[0:1]
	s_cbranch_execz .LBB0_593
	v_mov_b32_e32 v21, v1
	v_lshl_add_u64 v[28:29], s[6:7], 0, v[20:21]
	v_subrev_u32_e32 v211, s100, v28
	ds_read_b32 v4, v211
	v_add_co_u32_e32 v28, vcc, 0x2000, v28
	v_lshlrev_b32_e32 v3, 4, v22
	s_movk_i32 s12, 0x3c0
	v_addc_co_u32_e32 v29, vcc, 0, v29, vcc
	v_and_or_b32 v3, v3, s12, v168
	v_subrev_u32_e32 v211, s100, v28
	ds_read_b32 v8, v211
	v_lshlrev_b32_e32 v28, 2, v3
	v_mov_b32_e32 v29, v1
	v_lshl_add_u64 v[28:29], s[6:7], 0, v[28:29]
	v_subrev_u32_e32 v211, s100, v28
	ds_read_b32 v33, v211
	v_add_co_u32_e32 v28, vcc, 0x2000, v28
	s_waitcnt lgkmcnt(0)
	v_pk_mul_f32 v[34:35], v[26:27], v[4:5] op_sel_hi:[1,0]
	v_addc_co_u32_e32 v29, vcc, 0, v29, vcc
	v_subrev_u32_e32 v211, s100, v28
	ds_read_b32 v32, v211
	v_pk_mul_f32 v[36:37], v[26:27], v[8:9] op_sel:[1,0] op_sel_hi:[0,0]
	v_pk_fma_f32 v[28:29], v[26:27], v[4:5], v[36:37] op_sel_hi:[1,0,1]
	v_sub_f32_e32 v3, v34, v36
	v_mul_f32_e32 v4, v25, v33
	v_mov_b32_e32 v38, v33
	s_waitcnt lgkmcnt(0)
	v_pk_fma_f32 v[30:31], v[24:25], v[32:33], v[4:5] op_sel_hi:[1,1,0] neg_lo:[1,0,0] neg_hi:[1,0,0]
	v_mov_b32_e32 v39, v32
	v_mul_f32_e32 v4, v25, v32
	v_pk_fma_f32 v[32:33], v[24:25], v[38:39], v[4:5] op_sel_hi:[1,1,0]

; __device__ __forceinline__ void inproj_tile(const Params& p, char* smem, int l, int mt, int nt) {
;     ...
;           float ss = 0.f;
; #pragma unroll
;           for (int n = 0; n < 4; ++n) ss += acc[m][n][j] * acc[m][n][j];
;           ss += __shfl_xor(ss, 1); ss += __shfl_xor(ss, 2); ss += __shfl_xor(ss, 4); ss += __shfl_xor(ss, 8);
;           float rstd = rsqrtf(ss * (1.f / 64.f) + EPSF);
;           int row = rowbase + m * 16 + fq * 4 + j;
;           float v[4];
; #pragma unroll
;           for (int n = 0; n < 4; ++n) v[n] = acc[m][n][j] * rstd * w4[n];
;           bool lat = row < MLAT;
;           float rv[4] = {v[0], v[1], v[2], v[3]};
;           if (lat) {
;             int t = row & 8191, pr = t >> 6, pc = t & 63;
;             float c0 = rope[pr * 16 + fr], s0 = rope[2048 + pr * 16 + fr];
;             float c1 = rope[pc * 16 + fr], s1 = rope[2048 + pc * 16 + fr];
;             rv[0] = v[0] * c0 - v[1] * s0; rv[1] = v[1] * c0 + v[0] * s0;
;             rv[2] = v[2] * c1 - v[3] * s1; rv[3] = v[3] * c1 + v[2] * s1;
;           }
;           if (isq) {
; #pragma unroll
;             for (int n = 0; n < 4; ++n) UL[(size_t)row * 2560 + colbase + n * 16 + fr] = f2bf(v[n]);
;             if (lat) {
; #pragma unroll
;               for (int n = 0; n < 4; ++n) QROT[(size_t)row * 512 + colbase + n * 16 + fr] = f2bf(rv[n]);
.LBB0_601:
	s_or_b64 exec, exec, s[0:1]
	v_mov_b32_e32 v12, v9
	v_pk_mul_f32 v[22:23], v[12:13], v[12:13]
	v_mov_b32_e32 v4, v17
	v_pk_mul_f32 v[16:17], v[4:5], v[4:5]
	v_add_f32_e32 v3, v22, v23
	v_add_f32_e32 v3, v17, v3
	v_add_f32_e32 v3, v16, v3
	s_nop 1
	v_mov_b32_dpp v8, v3 quad_perm:[1,0,3,2] row_mask:0xf bank_mask:0xf
	s_waitcnt lgkmcnt(0)
	v_add_f32_e32 v3, v3, v8
	s_nop 1
	v_mov_b32_dpp v8, v3 quad_perm:[2,3,0,1] row_mask:0xf bank_mask:0xf
	s_waitcnt lgkmcnt(0)
	v_add_f32_e32 v3, v3, v8
	s_nop 1
	v_mov_b32_dpp v8, v3 row_half_mirror row_mask:0xf bank_mask:0xf
	s_waitcnt lgkmcnt(0)
	v_add_f32_e32 v3, v3, v8
	s_nop 1
	v_mov_b32_dpp v8, v3 row_mirror row_mask:0xf bank_mask:0xf
	s_waitcnt lgkmcnt(0)
	v_add_f32_e32 v3, v3, v8
	v_fmamk_f32 v3, v3, 0x3c800000, v197
	v_cmp_gt_f32_e32 vcc, s92, v3
	v_mul_f32_e32 v8, 0x4b800000, v3
	s_nop 0
	v_cndmask_b32_e32 v3, v3, v8, vcc
	v_rsq_f32_e32 v3, v3
	s_nop 0
	v_mul_f32_e32 v8, 0x45800000, v3
	v_cndmask_b32_e32 v16, v3, v8, vcc
	v_mov_b32_e32 v8, v13
	v_pk_mul_f32 v[8:9], v[16:17], v[8:9] op_sel_hi:[0,1]
	v_pk_mul_f32 v[4:5], v[16:17], v[4:5] op_sel_hi:[0,1]
	v_pk_mul_f32 v[12:13], v[138:139], v[8:9]
	v_pk_mul_f32 v[4:5], v[136:137], v[4:5]
	v_or_b32_e32 v8, 0x71, v2
	v_cmp_gt_i32_e64 s[0:1], s91, v8
	v_mov_b32_e32 v3, v12
	v_mov_b32_e32 v17, v13
	v_mov_b32_e32 v22, v5
	v_mov_b32_e32 v24, v4
	s_and_saveexec_b64 s[10:11], s[0:1]
	s_cbranch_execz .LBB0_603
	v_lshlrev_b32_e32 v3, 4, v8
	s_movk_i32 s12, 0x3d0
	v_and_or_b32 v3, v3, s12, v168
	v_mov_b32_e32 v21, v1
	v_lshlrev_b32_e32 v24, 2, v3
	v_mov_b32_e32 v25, v1
	v_lshl_add_u64 v[16:17], s[6:7], 0, v[20:21]
	v_lshl_add_u64 v[24:25], s[6:7], 0, v[24:25]
	v_subrev_u32_e32 v211, s100, v16
	ds_read_b32 v22, v211
	v_subrev_u32_e32 v211, s100, v24
	ds_read_b32 v27, v211
	v_add_co_u32_e32 v16, vcc, 0x2000, v16
	s_waitcnt lgkmcnt(0)
	v_pk_mul_f32 v[28:29], v[12:13], v[22:23] op_sel_hi:[1,0]
	v_addc_co_u32_e32 v17, vcc, 0, v17, vcc
	v_subrev_u32_e32 v211, s100, v16
	ds_read_b32 v16, v211
	v_add_co_u32_e32 v24, vcc, 0x2000, v24
	s_nop 1
	v_addc_co_u32_e32 v25, vcc, 0, v25, vcc
	v_subrev_u32_e32 v211, s100, v24
	ds_read_b32 v26, v211
	v_mov_b32_e32 v24, v27
	s_waitcnt lgkmcnt(0)
	v_pk_mul_f32 v[30:31], v[12:13], v[16:17] op_sel:[1,0] op_sel_hi:[0,0]
	v_pk_fma_f32 v[16:17], v[12:13], v[22:23], v[30:31] op_sel_hi:[1,0,1]
	v_sub_f32_e32 v3, v28, v30
	v_mul_f32_e32 v16, v5, v27
	v_pk_fma_f32 v[22:23], v[4:5], v[26:27], v[16:17] op_sel_hi:[1,1,0] neg_lo:[1,0,0] neg_hi:[1,0,0]
	v_mov_b32_e32 v25, v26
	v_mul_f32_e32 v16, v5, v26
	v_pk_fma_f32 v[24:25], v[4:5], v[24:25], v[16:17] op_sel_hi:[1,1,0]

; __device__ __forceinline__ void inproj_tile(const Params& p, char* smem, int l, int mt, int nt) {
;     ...
;           float ss = 0.f;
; #pragma unroll
;           for (int n = 0; n < 4; ++n) ss += acc[m][n][j] * acc[m][n][j];
;           ss += __shfl_xor(ss, 1); ss += __shfl_xor(ss, 2); ss += __shfl_xor(ss, 4); ss += __shfl_xor(ss, 8);
;           float rstd = rsqrtf(ss * (1.f / 64.f) + EPSF);
;           int row = rowbase + m * 16 + fq * 4 + j;
;           float v[4];
; #pragma unroll
;           for (int n = 0; n < 4; ++n) v[n] = acc[m][n][j] * rstd * w4[n];
;           bool lat = row < MLAT;
;           float rv[4] = {v[0], v[1], v[2], v[3]};
;           if (lat) {
;             int t = row & 8191, pr = t >> 6, pc = t & 63;
;             float c0 = rope[pr * 16 + fr], s0 = rope[2048 + pr * 16 + fr];
;             float c1 = rope[pc * 16 + fr], s1 = rope[2048 + pc * 16 + fr];
;             rv[0] = v[0] * c0 - v[1] * s0; rv[1] = v[1] * c0 + v[0] * s0;
;             rv[2] = v[2] * c1 - v[3] * s1; rv[3] = v[3] * c1 + v[2] * s1;
;           }
;           if (isq) {
; #pragma unroll
;             for (int n = 0; n < 4; ++n) UL[(size_t)row * 2560 + colbase + n * 16 + fr] = f2bf(v[n]);
;             if (lat) {
; #pragma unroll
;               for (int n = 0; n < 4; ++n) QROT[(size_t)row * 512 + colbase + n * 16 + fr] = f2bf(rv[n]);
.LBB0_611:
	s_or_b64 exec, exec, s[0:1]
	v_mov_b32_e32 v4, v10
	v_mov_b32_e32 v5, v14
	v_pk_mul_f32 v[4:5], v[4:5], v[4:5]
	v_mov_b32_e32 v8, v18
	v_mov_b32_e32 v9, v6
	v_pk_mul_f32 v[12:13], v[8:9], v[8:9]
	v_add_f32_e32 v3, v4, v5
	v_add_f32_e32 v3, v13, v3
	v_add_f32_e32 v3, v12, v3
	s_nop 1
	v_mov_b32_dpp v4, v3 quad_perm:[1,0,3,2] row_mask:0xf bank_mask:0xf
	v_mov_b32_e32 v12, v14
	v_mov_b32_e32 v13, v10
	s_waitcnt lgkmcnt(0)
	v_add_f32_e32 v3, v3, v4
	s_nop 1
	v_mov_b32_dpp v4, v3 quad_perm:[2,3,0,1] row_mask:0xf bank_mask:0xf
	s_waitcnt lgkmcnt(0)
	v_add_f32_e32 v3, v3, v4
	s_nop 1
	v_mov_b32_dpp v4, v3 row_half_mirror row_mask:0xf bank_mask:0xf
	s_waitcnt lgkmcnt(0)
	v_add_f32_e32 v3, v3, v4
	s_nop 1
	v_mov_b32_dpp v4, v3 row_mirror row_mask:0xf bank_mask:0xf
	s_waitcnt lgkmcnt(0)
	v_add_f32_e32 v3, v3, v4
	v_fmamk_f32 v3, v3, 0x3c800000, v197
	v_cmp_gt_f32_e32 vcc, s92, v3
	v_mul_f32_e32 v4, 0x4b800000, v3
	s_nop 0
	v_cndmask_b32_e32 v3, v3, v4, vcc
	v_rsq_f32_e32 v3, v3
	s_nop 0
	v_mul_f32_e32 v4, 0x45800000, v3
	v_cndmask_b32_e32 v4, v3, v4, vcc
	v_pk_mul_f32 v[12:13], v[4:5], v[12:13] op_sel_hi:[0,1]
	v_pk_mul_f32 v[4:5], v[4:5], v[8:9] op_sel_hi:[0,1]
	v_pk_mul_f32 v[12:13], v[138:139], v[12:13]
	v_pk_mul_f32 v[4:5], v[136:137], v[4:5]
	v_or_b32_e32 v8, 0x72, v2
	v_cmp_gt_i32_e64 s[0:1], s91, v8
	v_mov_b32_e32 v3, v12
	v_mov_b32_e32 v17, v13
	v_mov_b32_e32 v22, v5
	v_mov_b32_e32 v24, v4
	s_and_saveexec_b64 s[10:11], s[0:1]
	s_cbranch_execz .LBB0_613
	v_mov_b32_e32 v21, v1
	v_lshl_add_u64 v[16:17], s[6:7], 0, v[20:21]
	v_subrev_u32_e32 v211, s100, v16
	ds_read_b32 v6, v211
	v_add_co_u32_e32 v16, vcc, 0x2000, v16
	v_lshlrev_b32_e32 v3, 4, v8
	s_movk_i32 s12, 0x3e0
	v_addc_co_u32_e32 v17, vcc, 0, v17, vcc
	v_and_or_b32 v3, v3, s12, v168
	v_subrev_u32_e32 v211, s100, v16
	ds_read_b32 v10, v211
	v_lshlrev_b32_e32 v16, 2, v3
	v_mov_b32_e32 v17, v1
	v_lshl_add_u64 v[16:17], s[6:7], 0, v[16:17]
	v_subrev_u32_e32 v211, s100, v16
	ds_read_b32 v25, v211
	v_add_co_u32_e32 v16, vcc, 0x2000, v16
	s_waitcnt lgkmcnt(0)
	v_pk_mul_f32 v[26:27], v[12:13], v[6:7] op_sel_hi:[1,0]
	v_addc_co_u32_e32 v17, vcc, 0, v17, vcc
	v_subrev_u32_e32 v211, s100, v16
	ds_read_b32 v24, v211
	v_pk_mul_f32 v[28:29], v[12:13], v[10:11] op_sel:[1,0] op_sel_hi:[0,0]
	v_pk_fma_f32 v[16:17], v[12:13], v[6:7], v[28:29] op_sel_hi:[1,0,1]
	v_sub_f32_e32 v3, v26, v28
	v_mul_f32_e32 v6, v5, v25
	v_mov_b32_e32 v30, v25
	s_waitcnt lgkmcnt(0)
	v_pk_fma_f32 v[22:23], v[4:5], v[24:25], v[6:7] op_sel_hi:[1,1,0] neg_lo:[1,0,0] neg_hi:[1,0,0]
	v_mov_b32_e32 v31, v24
	v_mul_f32_e32 v6, v5, v24
	v_pk_fma_f32 v[24:25], v[4:5], v[30:31], v[6:7] op_sel_hi:[1,1,0]

; __device__ __forceinline__ void inproj_tile(const Params& p, char* smem, int l, int mt, int nt) {
;     ...
;           float ss = 0.f;
; #pragma unroll
;           for (int n = 0; n < 4; ++n) ss += acc[m][n][j] * acc[m][n][j];
;           ss += __shfl_xor(ss, 1); ss += __shfl_xor(ss, 2); ss += __shfl_xor(ss, 4); ss += __shfl_xor(ss, 8);
;           float rstd = rsqrtf(ss * (1.f / 64.f) + EPSF);
;           int row = rowbase + m * 16 + fq * 4 + j;
;           float v[4];
; #pragma unroll
;           for (int n = 0; n < 4; ++n) v[n] = acc[m][n][j] * rstd * w4[n];
;           bool lat = row < MLAT;
;           float rv[4] = {v[0], v[1], v[2], v[3]};
;           if (lat) {
;             int t = row & 8191, pr = t >> 6, pc = t & 63;
;             float c0 = rope[pr * 16 + fr], s0 = rope[2048 + pr * 16 + fr];
;             float c1 = rope[pc * 16 + fr], s1 = rope[2048 + pc * 16 + fr];
;             rv[0] = v[0] * c0 - v[1] * s0; rv[1] = v[1] * c0 + v[0] * s0;
;             rv[2] = v[2] * c1 - v[3] * s1; rv[3] = v[3] * c1 + v[2] * s1;
;           }
;           if (isq) {
; #pragma unroll
;             for (int n = 0; n < 4; ++n) UL[(size_t)row * 2560 + colbase + n * 16 + fr] = f2bf(v[n]);
;             if (lat) {
; #pragma unroll
;               for (int n = 0; n < 4; ++n) QROT[(size_t)row * 512 + colbase + n * 16 + fr] = f2bf(rv[n]);
.LBB0_621:
	s_or_b64 exec, exec, s[0:1]
	v_mov_b32_e32 v14, v11
	v_pk_mul_f32 v[4:5], v[14:15], v[14:15]
	v_mov_b32_e32 v6, v19
	v_pk_mul_f32 v[8:9], v[6:7], v[6:7]
	v_add_f32_e32 v3, v4, v5
	v_add_f32_e32 v3, v9, v3
	v_add_f32_e32 v3, v8, v3
	s_nop 1
	v_mov_b32_dpp v4, v3 quad_perm:[1,0,3,2] row_mask:0xf bank_mask:0xf
	v_mov_b32_e32 v10, v15
	v_or_b32_e32 v2, 0x73, v2
	v_cmp_gt_i32_e64 s[0:1], s91, v2
	s_waitcnt lgkmcnt(0)
	v_add_f32_e32 v3, v3, v4
	s_nop 1
	v_mov_b32_dpp v4, v3 quad_perm:[2,3,0,1] row_mask:0xf bank_mask:0xf
	s_waitcnt lgkmcnt(0)
	v_add_f32_e32 v3, v3, v4
	s_nop 1
	v_mov_b32_dpp v4, v3 row_half_mirror row_mask:0xf bank_mask:0xf
	s_waitcnt lgkmcnt(0)
	v_add_f32_e32 v3, v3, v4
	s_nop 1
	v_mov_b32_dpp v4, v3 row_mirror row_mask:0xf bank_mask:0xf
	s_waitcnt lgkmcnt(0)
	v_add_f32_e32 v3, v3, v4
	v_fmamk_f32 v3, v3, 0x3c800000, v197
	v_cmp_gt_f32_e32 vcc, s92, v3
	v_mul_f32_e32 v4, 0x4b800000, v3
	s_nop 0
	v_cndmask_b32_e32 v3, v3, v4, vcc
	v_rsq_f32_e32 v3, v3
	s_nop 0
	v_mul_f32_e32 v4, 0x45800000, v3
	v_cndmask_b32_e32 v4, v3, v4, vcc
	v_pk_mul_f32 v[8:9], v[4:5], v[10:11] op_sel_hi:[0,1]
	v_pk_mul_f32 v[4:5], v[4:5], v[6:7] op_sel_hi:[0,1]
	v_pk_mul_f32 v[8:9], v[138:139], v[8:9]
	v_pk_mul_f32 v[4:5], v[136:137], v[4:5]
	v_mov_b32_e32 v6, v8
	v_mov_b32_e32 v7, v9
	v_mov_b32_e32 v10, v5
	v_mov_b32_e32 v12, v4
	s_and_saveexec_b64 s[10:11], s[0:1]
	s_cbranch_execz .LBB0_623
	v_lshlrev_b32_e32 v3, 4, v2
	s_movk_i32 s12, 0x3f0
	v_and_or_b32 v3, v3, s12, v168
	v_mov_b32_e32 v21, v1
	v_lshlrev_b32_e32 v12, 2, v3
	v_mov_b32_e32 v13, v1
	v_lshl_add_u64 v[6:7], s[6:7], 0, v[20:21]
	v_lshl_add_u64 v[12:13], s[6:7], 0, v[12:13]
	v_subrev_u32_e32 v211, s100, v6
	ds_read_b32 v10, v211
	v_subrev_u32_e32 v211, s100, v12
	ds_read_b32 v15, v211
	v_add_co_u32_e32 v6, vcc, 0x2000, v6
	s_waitcnt lgkmcnt(0)
	v_pk_mul_f32 v[16:17], v[8:9], v[10:11] op_sel_hi:[1,0]
	v_addc_co_u32_e32 v7, vcc, 0, v7, vcc
	v_subrev_u32_e32 v211, s100, v6
	ds_read_b32 v6, v211
	v_add_co_u32_e32 v12, vcc, 0x2000, v12
	s_nop 1
	v_addc_co_u32_e32 v13, vcc, 0, v13, vcc
	v_subrev_u32_e32 v211, s100, v12
	ds_read_b32 v14, v211
	v_mov_b32_e32 v12, v15
	s_waitcnt lgkmcnt(0)
	v_pk_mul_f32 v[18:19], v[8:9], v[6:7] op_sel:[1,0] op_sel_hi:[0,0]
	v_pk_fma_f32 v[6:7], v[8:9], v[10:11], v[18:19] op_sel_hi:[1,0,1]
	v_mov_b32_e32 v13, v14
	v_mul_f32_e32 v6, v5, v15
	v_pk_fma_f32 v[10:11], v[4:5], v[14:15], v[6:7] op_sel_hi:[1,1,0] neg_lo:[1,0,0] neg_hi:[1,0,0]
	v_mul_f32_e32 v6, v5, v14
	v_pk_fma_f32 v[12:13], v[4:5], v[12:13], v[6:7] op_sel_hi:[1,1,0]
	v_sub_f32_e32 v6, v16, v18
